# UP epilogue: (rs,rs) mov pairs folded into pk_fma op_sel; sigmoid mul/add packed per register pair (removed slots kept as s_nop)
# baseline (speedup 1.0000x reference)
.LBB0_560:
	s_mov_b32 s98, 1.0
	s_mov_b32 s99, 1.0
	s_mov_b32 s100, 0xbfb8aa3b
	s_mov_b32 s101, 0xbfb8aa3b
	s_bitcmp1_b32 s29, 0
	s_cselect_b32 s3, 0x1800, 0
	s_add_i32 s3, s3, 0
	s_add_i32 s3, s3, 0x22100
	s_add_i32 s7, s3, s79
	v_lshl_add_u32 v1, v173, 2, s7
	v_add_u32_e32 v1, 0x1000, v1
	ds_read2_b32 v[146:147], v1 offset0:32 offset1:48
	v_lshl_add_u32 v223, v184, 2, s3
	ds_read_b128 v[118:121], v223 offset:5120
	ds_read_b128 v[30:33], v223 offset:5136
	s_waitcnt lgkmcnt(0)
	v_fmamk_f32 v54, v147, 0x3a800000, v222
	v_rsq_f32_e32 v150, v54
	ds_read_b128 v[122:125], v223 offset:5632
	ds_read_b128 v[54:57], v223 offset:5648
	ds_read2_b32 v[148:149], v1 offset1:16
	ds_read2_b32 v[202:203], v1 offset0:160 offset1:176
	ds_read2_b32 v[204:205], v1 offset0:128 offset1:144
	s_waitcnt lgkmcnt(0)
	v_pk_fma_f32 v[166:167], v[138:139], v[150:151], v[122:123] op_sel_hi:[1,0,1]
	v_cndmask_b32_e64 v1, 0, 1, s[20:21]
	v_pk_fma_f32 v[144:145], v[144:145], v[150:151], v[120:121] op_sel_hi:[1,0,1]
	v_fmamk_f32 v138, v203, 0x3a800000, v222
	v_rsq_f32_e32 v138, v138
	v_pk_fma_f32 v[142:143], v[142:143], v[150:151], v[118:119] op_sel_hi:[1,0,1]
	v_pk_fma_f32 v[84:85], v[84:85], v[150:151], v[32:33] op_sel_hi:[1,0,1]
	v_pk_fma_f32 v[82:83], v[82:83], v[150:151], v[30:31] op_sel_hi:[1,0,1]
	v_pk_fma_f32 v[168:169], v[140:141], v[150:151], v[124:125] op_sel_hi:[1,0,1]
	v_pk_fma_f32 v[100:101], v[100:101], v[150:151], v[56:57] op_sel_hi:[1,0,1]
	v_pk_fma_f32 v[98:99], v[98:99], v[150:151], v[54:55] op_sel_hi:[1,0,1]
	v_pk_fma_f32 v[116:117], v[116:117], v[138:139], v[120:121] op_sel_hi:[1,0,1]
	v_pk_fma_f32 v[114:115], v[114:115], v[138:139], v[118:119] op_sel_hi:[1,0,1]
	v_pk_fma_f32 v[28:29], v[28:29], v[138:139], v[32:33] op_sel_hi:[1,0,1]
	v_pk_fma_f32 v[26:27], v[26:27], v[138:139], v[30:31] op_sel_hi:[1,0,1]
	v_pk_fma_f32 v[128:129], v[128:129], v[138:139], v[124:125] op_sel_hi:[1,0,1]
	v_pk_fma_f32 v[126:127], v[126:127], v[138:139], v[122:123] op_sel_hi:[1,0,1]
	v_pk_fma_f32 v[60:61], v[60:61], v[138:139], v[56:57] op_sel_hi:[1,0,1]
	v_pk_fma_f32 v[58:59], v[58:59], v[138:139], v[54:55] op_sel_hi:[1,0,1]
	v_cmp_ne_u32_e64 s[8:9], 1, v1
	s_and_saveexec_b64 s[48:49], s[0:1]
	s_cbranch_execz .LBB0_563
	v_add_u32_e32 v1, s91, v212
	ds_write_b128 v1, v[142:145]
	v_add_u32_e32 v1, s97, v212
	ds_write_b128 v1, v[82:85]
	v_add_u32_e32 v1, s96, v212
	ds_write_b128 v1, v[166:169]
	v_add_u32_e32 v1, s87, v212
	ds_write_b128 v1, v[98:101]
	v_add_u32_e32 v1, s91, v213
	ds_write_b128 v1, v[114:117]
	v_add_u32_e32 v1, s97, v213
	ds_write_b128 v1, v[26:29]
	v_add_u32_e32 v1, s96, v213
	ds_write_b128 v1, v[126:129]
	v_add_u32_e32 v1, s87, v213
	s_and_b64 vcc, exec, s[8:9]
	ds_write_b128 v1, v[58:61]
	s_cbranch_vccnz .LBB0_563
	v_lshl_add_u32 v1, s28, 1, v214
	s_lshl_b32 s50, s46, 7
	v_mov_b64_e32 v[138:139], s[22:23]
	s_ashr_i32 s51, s50, 31
	v_mad_i64_i32 v[138:139], s[84:85], v1, s76, v[138:139]
	v_lshl_add_u64 v[138:139], s[50:51], 2, v[138:139]
	v_lshlrev_b32_e32 v140, 2, v184
	v_mov_b32_e32 v141, v183
	v_lshl_add_u64 v[138:139], v[138:139], 0, v[140:141]
	global_store_dwordx4 v[138:139], v[114:117], off
	global_store_dwordx4 v[138:139], v[26:29], off offset:16
	v_add_co_u32_e32 v138, vcc, 0x2000, v138
	s_nop 1
	v_addc_co_u32_e32 v139, vcc, 0, v139, vcc
	global_store_dwordx4 v[138:139], v[126:129], off offset:3072
	global_store_dwordx4 v[138:139], v[58:61], off offset:3088

.LBB0_567:
	s_or_b64 exec, exec, s[48:49]
	s_nop 0
	ds_read_b128 v[150:153], v223
	ds_read_b128 v[154:157], v223 offset:1024
	ds_read_b128 v[162:165], v223 offset:2048
	ds_read_b128 v[134:137], v223 offset:3072
	v_mov_b32_e32 v158, 0
	v_mov_b32_e32 v159, 0
	v_mov_b32_e32 v160, 0
	v_mov_b32_e32 v161, 0
	s_and_saveexec_b64 s[48:49], s[30:31]
	v_add_u32_e32 v1, 0, v215
	v_add_u32_e32 v1, 0x20000, v1
	ds_read_b128 v[158:161], v1
	s_or_b64 exec, exec, s[48:49]
	v_mov_b32_e32 v195, v194
	v_mov_b32_e32 v199, v198
	v_pk_fma_f32 v[208:209], v[62:63], v[194:195], v[118:119] op_sel_hi:[1,0,1]
	s_nop 0
	s_nop 0
	v_pk_fma_f32 v[62:63], v[52:53], v[196:197], v[120:121] op_sel_hi:[1,0,1]
	v_pk_fma_f32 v[52:53], v[46:47], v[198:199], v[118:119] op_sel_hi:[1,0,1]
	s_waitcnt lgkmcnt(0)
	v_pk_fma_f32 v[46:47], v[142:143], v[162:163], v[134:135]
	s_nop 4
	v_fmac_f32_dpp v46, v142, v154 row_shr:1 row_mask:0xf bank_mask:0xf
	s_nop 0
	v_fmac_f32_dpp v46, v142, v150 row_shr:2 row_mask:0xf bank_mask:0xf
	v_mov_b32_e32 v197, v196
	v_fmac_f32_dpp v46, v52, v154 row_shl:15 row_mask:0xf bank_mask:0xf
	s_nop 0
	s_nop 0
	v_fmac_f32_dpp v46, v52, v150 row_shl:14 row_mask:0xf bank_mask:0xf
	v_fmac_f32_dpp v47, v143, v155 row_shr:1 row_mask:0xf bank_mask:0xf
	v_pk_fma_f32 v[206:207], v[64:65], v[194:195], v[120:121] op_sel_hi:[1,0,1]
	v_pk_fma_f32 v[64:65], v[50:51], v[196:197], v[118:119] op_sel_hi:[1,0,1]
	s_nop 0
	s_nop 0
	v_fmac_f32_dpp v47, v143, v151 row_shr:2 row_mask:0xf bank_mask:0xf
	v_pk_fma_f32 v[50:51], v[48:49], v[198:199], v[120:121] op_sel_hi:[1,0,1]
	v_fmac_f32_dpp v47, v53, v155 row_shl:15 row_mask:0xf bank_mask:0xf
	v_pk_fma_f32 v[48:49], v[144:145], v[164:165], v[136:137]
	v_fmac_f32_dpp v47, v53, v151 row_shl:14 row_mask:0xf bank_mask:0xf
	v_fmac_f32_dpp v48, v144, v156 row_shr:1 row_mask:0xf bank_mask:0xf
	s_nop 0
	v_fmac_f32_dpp v48, v144, v152 row_shr:2 row_mask:0xf bank_mask:0xf
	s_nop 0
	v_fmac_f32_dpp v48, v50, v156 row_shl:15 row_mask:0xf bank_mask:0xf
	s_nop 0
	v_fmac_f32_dpp v48, v50, v152 row_shl:14 row_mask:0xf bank_mask:0xf
	v_fmac_f32_dpp v49, v145, v157 row_shr:1 row_mask:0xf bank_mask:0xf
	s_nop 0
	v_fmac_f32_dpp v49, v145, v153 row_shr:2 row_mask:0xf bank_mask:0xf
	s_nop 0
	v_fmac_f32_dpp v49, v51, v157 row_shl:15 row_mask:0xf bank_mask:0xf
	s_nop 0
	v_fmac_f32_dpp v49, v51, v153 row_shl:14 row_mask:0xf bank_mask:0xf
	s_nop 0
	s_nop 0
	s_nop 0
	s_nop 0
	s_nop 0
	s_nop 0
	s_nop 0
	s_nop 0
	s_nop 0
	v_pk_mul_f32 v[244:245], v[48:49], s[100:101]
	v_exp_f32_e32 v244, v244
	v_exp_f32_e32 v245, v245
	s_nop 0
	v_pk_add_f32 v[244:245], v[244:245], s[98:99]
	v_rcp_f32_e32 v144, v244
	v_rcp_f32_e32 v145, v245
	v_pk_mul_f32 v[244:245], v[46:47], s[100:101]
	v_exp_f32_e32 v244, v244
	v_exp_f32_e32 v245, v245
	s_nop 0
	v_pk_add_f32 v[244:245], v[244:245], s[98:99]
	v_rcp_f32_e32 v142, v244
	v_rcp_f32_e32 v143, v245
	v_pk_mul_f32 v[48:49], v[148:149], v[48:49]
	v_pk_mul_f32 v[46:47], v[146:147], v[46:47]
	v_pk_mul_f32 v[48:49], v[48:49], v[144:145]
	v_pk_mul_f32 v[46:47], v[46:47], v[142:143]
	v_pk_fma_f32 v[142:143], v[52:53], v[162:163], v[134:135]
	v_fmac_f32_dpp v142, v52, v154 row_shr:1 row_mask:0xf bank_mask:0xf
	s_nop 0
	v_fmac_f32_dpp v142, v52, v150 row_shr:2 row_mask:0xf bank_mask:0xf
	v_fma_f32 v52, v50, v164, v136
	v_fmac_f32_dpp v142, v64, v154 row_shl:15 row_mask:0xf bank_mask:0xf
	s_nop 0
	v_fmac_f32_dpp v142, v64, v150 row_shl:14 row_mask:0xf bank_mask:0xf
	v_fmac_f32_dpp v143, v53, v155 row_shr:1 row_mask:0xf bank_mask:0xf
	s_nop 0
	v_fmac_f32_dpp v143, v53, v151 row_shr:2 row_mask:0xf bank_mask:0xf
	s_nop 0
	v_fmac_f32_dpp v143, v65, v155 row_shl:15 row_mask:0xf bank_mask:0xf
	s_nop 0
	v_fmac_f32_dpp v143, v65, v151 row_shl:14 row_mask:0xf bank_mask:0xf
	v_fmac_f32_dpp v52, v50, v156 row_shr:1 row_mask:0xf bank_mask:0xf
	v_fma_f32 v53, v51, v165, v137
	v_fmac_f32_dpp v52, v50, v152 row_shr:2 row_mask:0xf bank_mask:0xf
	s_nop 0
	v_fmac_f32_dpp v52, v62, v156 row_shl:15 row_mask:0xf bank_mask:0xf
	s_nop 0
	v_fmac_f32_dpp v52, v62, v152 row_shl:14 row_mask:0xf bank_mask:0xf
	v_fmac_f32_dpp v53, v51, v157 row_shr:1 row_mask:0xf bank_mask:0xf
	s_nop 0
	v_fmac_f32_dpp v53, v51, v153 row_shr:2 row_mask:0xf bank_mask:0xf
	s_nop 0
	v_fmac_f32_dpp v53, v63, v157 row_shl:15 row_mask:0xf bank_mask:0xf
	s_nop 0
	v_fmac_f32_dpp v53, v63, v153 row_shl:14 row_mask:0xf bank_mask:0xf
	s_nop 0
	s_nop 0
	s_nop 0
	s_nop 0
	s_nop 0
	s_nop 0
	s_nop 0
	v_pk_mul_f32 v[244:245], v[52:53], s[100:101]
	v_exp_f32_e32 v244, v244
	v_exp_f32_e32 v245, v245
	s_nop 0
	v_pk_add_f32 v[244:245], v[244:245], s[98:99]
	v_rcp_f32_e32 v144, v244
	v_rcp_f32_e32 v145, v245
	v_pk_mul_f32 v[244:245], v[142:143], s[100:101]
	v_exp_f32_e32 v244, v244
	v_exp_f32_e32 v245, v245
	s_nop 0
	v_pk_add_f32 v[244:245], v[244:245], s[98:99]
	v_rcp_f32_e32 v50, v244
	v_rcp_f32_e32 v51, v245
	v_pk_mul_f32 v[52:53], v[132:133], v[52:53]
	v_pk_mul_f32 v[130:131], v[130:131], v[142:143]
	v_pk_mul_f32 v[52:53], v[52:53], v[144:145]
	v_pk_mul_f32 v[50:51], v[130:131], v[50:51]
	v_pk_fma_f32 v[130:131], v[64:65], v[162:163], v[134:135]
	v_fmac_f32_dpp v130, v64, v154 row_shr:1 row_mask:0xf bank_mask:0xf
	s_nop 0
	v_fmac_f32_dpp v130, v64, v150 row_shr:2 row_mask:0xf bank_mask:0xf
	v_fma_f32 v64, v62, v164, v136
	v_fmac_f32_dpp v130, v208, v154 row_shl:15 row_mask:0xf bank_mask:0xf
	v_pk_fma_f32 v[134:135], v[208:209], v[162:163], v[134:135]
	v_fmac_f32_dpp v130, v208, v150 row_shl:14 row_mask:0xf bank_mask:0xf
	v_fmac_f32_dpp v131, v65, v155 row_shr:1 row_mask:0xf bank_mask:0xf
	s_nop 0
	v_fmac_f32_dpp v131, v65, v151 row_shr:2 row_mask:0xf bank_mask:0xf
	v_mul_f32_e32 v1, 0xbfb8aa3b, v130
	v_fmac_f32_dpp v131, v209, v155 row_shl:15 row_mask:0xf bank_mask:0xf
	v_exp_f32_e32 v1, v1
	v_fmac_f32_dpp v131, v209, v151 row_shl:14 row_mask:0xf bank_mask:0xf
	v_fmac_f32_dpp v64, v62, v156 row_shr:1 row_mask:0xf bank_mask:0xf
	v_fma_f32 v65, v63, v165, v137
	v_fmac_f32_dpp v64, v62, v152 row_shr:2 row_mask:0xf bank_mask:0xf
	v_add_f32_e32 v1, 1.0, v1
	v_fmac_f32_dpp v64, v206, v156 row_shl:15 row_mask:0xf bank_mask:0xf
	v_rcp_f32_e32 v62, v1
	v_fmac_f32_dpp v64, v206, v152 row_shl:14 row_mask:0xf bank_mask:0xf
	v_fmac_f32_dpp v65, v63, v157 row_shr:1 row_mask:0xf bank_mask:0xf
	v_mul_f32_e32 v1, 0xbfb8aa3b, v131
	v_fmac_f32_dpp v65, v63, v153 row_shr:2 row_mask:0xf bank_mask:0xf
	s_nop 0
	v_fmac_f32_dpp v65, v207, v157 row_shl:15 row_mask:0xf bank_mask:0xf
	s_nop 0
	v_fmac_f32_dpp v65, v207, v153 row_shl:14 row_mask:0xf bank_mask:0xf
	v_exp_f32_e32 v1, v1
	s_nop 0
	s_nop 0
	s_nop 0
	v_add_f32_e32 v1, 1.0, v1
	s_nop 0
	s_nop 0
	v_pk_mul_f32 v[244:245], v[64:65], s[100:101]
	v_exp_f32_e32 v244, v244
	v_exp_f32_e32 v245, v245
	s_nop 0
	v_pk_add_f32 v[244:245], v[244:245], s[98:99]
	v_rcp_f32_e32 v132, v244
	v_rcp_f32_e32 v133, v245
	v_rcp_f32_e32 v63, v1
	v_pk_mul_f32 v[64:65], v[80:81], v[64:65]
	v_pk_mul_f32 v[78:79], v[78:79], v[130:131]
	v_pk_mul_f32 v[64:65], v[64:65], v[132:133]
	v_pk_mul_f32 v[62:63], v[78:79], v[62:63]
	v_pk_fma_f32 v[136:137], v[206:207], v[164:165], v[136:137]
	v_fmac_f32_dpp v134, v208, v154 row_shr:1 row_mask:0xf bank_mask:0xf
	s_nop 0
	v_fmac_f32_dpp v134, v208, v150 row_shr:2 row_mask:0xf bank_mask:0xf
	s_nop 0
	v_fmac_f32_dpp v134, v158, v154 row_shl:15 row_mask:0xf bank_mask:0xf
	s_nop 0
	v_fmac_f32_dpp v134, v158, v150 row_shl:14 row_mask:0xf bank_mask:0xf
	v_fmac_f32_dpp v135, v209, v155 row_shr:1 row_mask:0xf bank_mask:0xf
	s_nop 0
	v_fmac_f32_dpp v135, v209, v151 row_shr:2 row_mask:0xf bank_mask:0xf
	s_nop 0
	v_fmac_f32_dpp v135, v159, v155 row_shl:15 row_mask:0xf bank_mask:0xf
	s_nop 0
	v_fmac_f32_dpp v135, v159, v151 row_shl:14 row_mask:0xf bank_mask:0xf
	v_fmac_f32_dpp v136, v206, v156 row_shr:1 row_mask:0xf bank_mask:0xf
	s_nop 0
	v_fmac_f32_dpp v136, v206, v152 row_shr:2 row_mask:0xf bank_mask:0xf
	s_nop 0
	v_fmac_f32_dpp v136, v160, v156 row_shl:15 row_mask:0xf bank_mask:0xf
	s_nop 0
	v_fmac_f32_dpp v136, v160, v152 row_shl:14 row_mask:0xf bank_mask:0xf
	v_fmac_f32_dpp v137, v207, v157 row_shr:1 row_mask:0xf bank_mask:0xf
	s_nop 0
	v_fmac_f32_dpp v137, v207, v153 row_shr:2 row_mask:0xf bank_mask:0xf
	s_nop 0
	v_fmac_f32_dpp v137, v161, v157 row_shl:15 row_mask:0xf bank_mask:0xf
	s_nop 0
	v_fmac_f32_dpp v137, v161, v153 row_shl:14 row_mask:0xf bank_mask:0xf
	s_and_saveexec_b64 s[48:49], s[34:35]
	s_cbranch_execz .LBB0_571
	global_store_dwordx4 v[166:167], v[134:137], off
.LBB0_571:
	s_or_b64 exec, exec, s[48:49]
	s_nop 0
	s_nop 0
	s_nop 0
	v_mul_f32_e32 v79, 0xbfb8aa3b, v136
	s_nop 0
	s_nop 0
	s_nop 0
	v_exp_f32_e32 v1, v79
	v_mul_f32_e32 v79, 0xbfb8aa3b, v137
	v_exp_f32_e32 v79, v79
	s_nop 0
	v_add_f32_e32 v1, 1.0, v1
	v_rcp_f32_e32 v80, v1
	v_add_f32_e32 v1, 1.0, v79
	v_rcp_f32_e32 v81, v1
	v_pk_mul_f32 v[244:245], v[134:135], s[100:101]
	v_exp_f32_e32 v244, v244
	v_exp_f32_e32 v245, v245
	s_nop 0
	v_pk_add_f32 v[244:245], v[244:245], s[98:99]
	v_rcp_f32_e32 v78, v244
	v_rcp_f32_e32 v79, v245
	v_pk_mul_f32 v[130:131], v[140:141], v[136:137]
	v_pk_mul_f32 v[132:133], v[138:139], v[134:135]
	v_pk_mul_f32 v[80:81], v[130:131], v[80:81]
	v_pk_mul_f32 v[78:79], v[132:133], v[78:79]
	v_mov_b32_e32 v134, 0
	ds_read_b128 v[142:145], v223 offset:512
	ds_read_b128 v[146:149], v223 offset:1536
	ds_read_b128 v[154:157], v223 offset:2560
	ds_read_b128 v[130:133], v223 offset:3584
	v_mov_b32_e32 v150, 0
	v_mov_b32_e32 v151, 0
	v_mov_b32_e32 v152, 0
	v_mov_b32_e32 v153, 0
	s_and_saveexec_b64 s[48:49], s[0:1]
	v_add_u32_e32 v1, s91, v216
	ds_read_b128 v[150:153], v1 offset:512
	s_or_b64 exec, exec, s[48:49]
	v_fmamk_f32 v135, v202, 0x3a800000, v222
	v_rsq_f32_e32 v160, v135
	s_waitcnt lgkmcnt(0)
	v_pk_fma_f32 v[138:139], v[126:127], v[154:155], v[130:131]
	s_nop 4
	v_fmac_f32_dpp v138, v126, v146 row_shr:1 row_mask:0xf bank_mask:0xf
	v_pk_fma_f32 v[102:103], v[102:103], v[160:161], v[122:123] op_sel_hi:[1,0,1]
	v_fmac_f32_dpp v138, v126, v142 row_shr:2 row_mask:0xf bank_mask:0xf
	s_nop 0
	v_fmac_f32_dpp v138, v102, v146 row_shl:15 row_mask:0xf bank_mask:0xf
	v_pk_fma_f32 v[140:141], v[128:129], v[156:157], v[132:133]
	v_fmac_f32_dpp v138, v102, v142 row_shl:14 row_mask:0xf bank_mask:0xf
	v_fmac_f32_dpp v139, v127, v147 row_shr:1 row_mask:0xf bank_mask:0xf
	v_fmamk_f32 v1, v204, 0x3a800000, v222
	v_fmac_f32_dpp v139, v127, v143 row_shr:2 row_mask:0xf bank_mask:0xf
	v_rsq_f32_e32 v158, v1
	v_fmac_f32_dpp v139, v103, v147 row_shl:15 row_mask:0xf bank_mask:0xf
	v_fmamk_f32 v1, v205, 0x3a800000, v222
	v_fmac_f32_dpp v139, v103, v143 row_shl:14 row_mask:0xf bank_mask:0xf
	v_fmac_f32_dpp v140, v128, v148 row_shr:1 row_mask:0xf bank_mask:0xf
	v_rsq_f32_e32 v162, v1
	v_fmac_f32_dpp v140, v128, v144 row_shr:2 row_mask:0xf bank_mask:0xf
	v_pk_fma_f32 v[104:105], v[104:105], v[160:161], v[124:125] op_sel_hi:[1,0,1]
	s_nop 0
	v_fmac_f32_dpp v140, v104, v148 row_shl:15 row_mask:0xf bank_mask:0xf
	v_pk_fma_f32 v[164:165], v[106:107], v[162:163], v[122:123] op_sel_hi:[1,0,1]
	v_fmac_f32_dpp v140, v104, v144 row_shl:14 row_mask:0xf bank_mask:0xf
	v_fmac_f32_dpp v141, v129, v149 row_shr:1 row_mask:0xf bank_mask:0xf
	v_pk_fma_f32 v[106:107], v[102:103], v[154:155], v[130:131]
	v_fmac_f32_dpp v141, v129, v145 row_shr:2 row_mask:0xf bank_mask:0xf
	s_nop 0
	v_fmac_f32_dpp v141, v105, v149 row_shl:15 row_mask:0xf bank_mask:0xf
	v_pk_fma_f32 v[136:137], v[108:109], v[162:163], v[124:125] op_sel_hi:[1,0,1]
	v_fmac_f32_dpp v141, v105, v145 row_shl:14 row_mask:0xf bank_mask:0xf
	v_pk_fma_f32 v[108:109], v[104:105], v[156:157], v[132:133]
	v_fmac_f32_dpp v106, v102, v146 row_shr:1 row_mask:0xf bank_mask:0xf
	s_nop 0
	v_fmac_f32_dpp v106, v102, v142 row_shr:2 row_mask:0xf bank_mask:0xf
	s_nop 0
	v_fmac_f32_dpp v106, v164, v146 row_shl:15 row_mask:0xf bank_mask:0xf
	v_pk_fma_f32 v[110:111], v[110:111], v[158:159], v[122:123] op_sel_hi:[1,0,1]
	v_fmac_f32_dpp v106, v164, v142 row_shl:14 row_mask:0xf bank_mask:0xf
	v_fmac_f32_dpp v107, v103, v147 row_shr:1 row_mask:0xf bank_mask:0xf
	v_pk_fma_f32 v[112:113], v[112:113], v[158:159], v[124:125] op_sel_hi:[1,0,1]
	v_fmac_f32_dpp v107, v103, v143 row_shr:2 row_mask:0xf bank_mask:0xf
	v_pk_fma_f32 v[102:103], v[164:165], v[154:155], v[130:131]
	v_fmac_f32_dpp v107, v165, v147 row_shl:15 row_mask:0xf bank_mask:0xf
	v_pk_fma_f32 v[130:131], v[110:111], v[154:155], v[130:131]
	v_fmac_f32_dpp v107, v165, v143 row_shl:14 row_mask:0xf bank_mask:0xf
	v_fmac_f32_dpp v108, v104, v148 row_shr:1 row_mask:0xf bank_mask:0xf
	s_nop 0
	v_fmac_f32_dpp v108, v104, v144 row_shr:2 row_mask:0xf bank_mask:0xf
	v_fma_f32 v104, v136, v156, v132
	v_fmac_f32_dpp v108, v136, v148 row_shl:15 row_mask:0xf bank_mask:0xf
	s_nop 0
	v_fmac_f32_dpp v108, v136, v144 row_shl:14 row_mask:0xf bank_mask:0xf
	v_fmac_f32_dpp v109, v105, v149 row_shr:1 row_mask:0xf bank_mask:0xf
	v_mov_b32_e32 v135, 0
	v_fmac_f32_dpp v109, v105, v145 row_shr:2 row_mask:0xf bank_mask:0xf
	v_fma_f32 v105, v137, v157, v133
	v_fmac_f32_dpp v109, v137, v149 row_shl:15 row_mask:0xf bank_mask:0xf
	v_pk_fma_f32 v[132:133], v[112:113], v[156:157], v[132:133]
	v_fmac_f32_dpp v109, v137, v145 row_shl:14 row_mask:0xf bank_mask:0xf
	s_nop 0
	v_fmac_f32_dpp v102, v164, v146 row_shr:1 row_mask:0xf bank_mask:0xf
	s_nop 0
	v_fmac_f32_dpp v102, v164, v142 row_shr:2 row_mask:0xf bank_mask:0xf
	s_nop 0
	v_fmac_f32_dpp v102, v110, v146 row_shl:15 row_mask:0xf bank_mask:0xf
	s_nop 0
	v_fmac_f32_dpp v102, v110, v142 row_shl:14 row_mask:0xf bank_mask:0xf
	v_fmac_f32_dpp v103, v165, v147 row_shr:1 row_mask:0xf bank_mask:0xf
	s_nop 0
	v_fmac_f32_dpp v103, v165, v143 row_shr:2 row_mask:0xf bank_mask:0xf
	s_nop 0
	v_fmac_f32_dpp v103, v111, v147 row_shl:15 row_mask:0xf bank_mask:0xf
	s_nop 0
	v_fmac_f32_dpp v103, v111, v143 row_shl:14 row_mask:0xf bank_mask:0xf
	v_fmac_f32_dpp v104, v136, v148 row_shr:1 row_mask:0xf bank_mask:0xf
	s_nop 0
	v_fmac_f32_dpp v104, v136, v144 row_shr:2 row_mask:0xf bank_mask:0xf
	v_mov_b32_e32 v136, 0
	v_fmac_f32_dpp v104, v112, v148 row_shl:15 row_mask:0xf bank_mask:0xf
	s_nop 0
	v_fmac_f32_dpp v104, v112, v144 row_shl:14 row_mask:0xf bank_mask:0xf
	v_fmac_f32_dpp v105, v137, v149 row_shr:1 row_mask:0xf bank_mask:0xf
	s_nop 0
	v_fmac_f32_dpp v105, v137, v145 row_shr:2 row_mask:0xf bank_mask:0xf
	v_mov_b32_e32 v137, 0
	v_fmac_f32_dpp v105, v113, v149 row_shl:15 row_mask:0xf bank_mask:0xf
	s_nop 0
	v_fmac_f32_dpp v105, v113, v145 row_shl:14 row_mask:0xf bank_mask:0xf
	s_nop 0
	v_fmac_f32_dpp v130, v110, v146 row_shr:1 row_mask:0xf bank_mask:0xf
	s_nop 0
	v_fmac_f32_dpp v130, v110, v142 row_shr:2 row_mask:0xf bank_mask:0xf
	s_nop 0
	v_fmac_f32_dpp v130, v150, v146 row_shl:15 row_mask:0xf bank_mask:0xf
	s_nop 0
	v_fmac_f32_dpp v130, v150, v142 row_shl:14 row_mask:0xf bank_mask:0xf
	v_fmac_f32_dpp v131, v111, v147 row_shr:1 row_mask:0xf bank_mask:0xf
	s_nop 0
	v_fmac_f32_dpp v131, v111, v143 row_shr:2 row_mask:0xf bank_mask:0xf
	s_nop 0
	v_fmac_f32_dpp v131, v151, v147 row_shl:15 row_mask:0xf bank_mask:0xf
	s_nop 0
	v_fmac_f32_dpp v131, v151, v143 row_shl:14 row_mask:0xf bank_mask:0xf
	v_fmac_f32_dpp v132, v112, v148 row_shr:1 row_mask:0xf bank_mask:0xf
	s_nop 0
	v_fmac_f32_dpp v132, v112, v144 row_shr:2 row_mask:0xf bank_mask:0xf
	s_nop 0
	v_fmac_f32_dpp v132, v152, v148 row_shl:15 row_mask:0xf bank_mask:0xf
	s_nop 0
	v_fmac_f32_dpp v132, v152, v144 row_shl:14 row_mask:0xf bank_mask:0xf
	v_fmac_f32_dpp v133, v113, v149 row_shr:1 row_mask:0xf bank_mask:0xf
	s_nop 0
	v_fmac_f32_dpp v133, v113, v145 row_shr:2 row_mask:0xf bank_mask:0xf
	s_nop 0
	v_fmac_f32_dpp v133, v153, v149 row_shl:15 row_mask:0xf bank_mask:0xf
	s_nop 0
	v_fmac_f32_dpp v133, v153, v145 row_shl:14 row_mask:0xf bank_mask:0xf
	s_nop 0
	ds_read_b128 v[122:125], v223
	ds_read_b128 v[126:129], v223 offset:1024
	ds_read_b128 v[142:145], v223 offset:2048
	ds_read_b128 v[110:113], v223 offset:3072
	s_and_saveexec_b64 s[48:49], s[0:1]
	v_add_u32_e32 v1, 0, v216
	v_add_u32_e32 v1, 0x20000, v1
	ds_read_b128 v[134:137], v1
	s_or_b64 exec, exec, s[48:49]
	v_mov_b32_e32 v159, v158
	v_mov_b32_e32 v161, v160
	v_pk_fma_f32 v[148:149], v[94:95], v[158:159], v[118:119] op_sel_hi:[1,0,1]
	s_nop 0
	s_nop 0
	v_pk_fma_f32 v[94:95], v[92:93], v[162:163], v[120:121] op_sel_hi:[1,0,1]
	v_pk_fma_f32 v[92:93], v[86:87], v[160:161], v[118:119] op_sel_hi:[1,0,1]
	s_waitcnt lgkmcnt(0)
	v_pk_fma_f32 v[86:87], v[114:115], v[142:143], v[110:111]
	s_nop 4
	v_fmac_f32_dpp v86, v114, v126 row_shr:1 row_mask:0xf bank_mask:0xf
	s_nop 0
	v_fmac_f32_dpp v86, v114, v122 row_shr:2 row_mask:0xf bank_mask:0xf
	v_mov_b32_e32 v163, v162
	v_fmac_f32_dpp v86, v92, v126 row_shl:15 row_mask:0xf bank_mask:0xf
	s_nop 0
	s_nop 0
	v_fmac_f32_dpp v86, v92, v122 row_shl:14 row_mask:0xf bank_mask:0xf
	v_fmac_f32_dpp v87, v115, v127 row_shr:1 row_mask:0xf bank_mask:0xf
	v_pk_fma_f32 v[146:147], v[96:97], v[158:159], v[120:121] op_sel_hi:[1,0,1]
	v_pk_fma_f32 v[96:97], v[90:91], v[162:163], v[118:119] op_sel_hi:[1,0,1]
	s_nop 0
	s_nop 0
	v_fmac_f32_dpp v87, v115, v123 row_shr:2 row_mask:0xf bank_mask:0xf
	v_pk_fma_f32 v[90:91], v[88:89], v[160:161], v[120:121] op_sel_hi:[1,0,1]
	v_fmac_f32_dpp v87, v93, v127 row_shl:15 row_mask:0xf bank_mask:0xf
	v_pk_fma_f32 v[88:89], v[116:117], v[144:145], v[112:113]
	v_fmac_f32_dpp v87, v93, v123 row_shl:14 row_mask:0xf bank_mask:0xf
	v_fmac_f32_dpp v88, v116, v128 row_shr:1 row_mask:0xf bank_mask:0xf
	s_nop 0
	v_fmac_f32_dpp v88, v116, v124 row_shr:2 row_mask:0xf bank_mask:0xf
	s_nop 0
	v_fmac_f32_dpp v88, v90, v128 row_shl:15 row_mask:0xf bank_mask:0xf
	s_nop 0
	v_fmac_f32_dpp v88, v90, v124 row_shl:14 row_mask:0xf bank_mask:0xf
	v_fmac_f32_dpp v89, v117, v129 row_shr:1 row_mask:0xf bank_mask:0xf
	s_nop 0
	v_fmac_f32_dpp v89, v117, v125 row_shr:2 row_mask:0xf bank_mask:0xf
	s_nop 0
	v_fmac_f32_dpp v89, v91, v129 row_shl:15 row_mask:0xf bank_mask:0xf
	s_nop 0
	v_fmac_f32_dpp v89, v91, v125 row_shl:14 row_mask:0xf bank_mask:0xf
	s_nop 0
	s_nop 0
	s_nop 0
	s_nop 0
	s_nop 0
	s_nop 0
	s_nop 0
	s_nop 0
	s_nop 0
	v_pk_mul_f32 v[244:245], v[88:89], s[100:101]
	v_exp_f32_e32 v244, v244
	v_exp_f32_e32 v245, v245
	s_nop 0
	v_pk_add_f32 v[244:245], v[244:245], s[98:99]
	v_rcp_f32_e32 v116, v244
	v_rcp_f32_e32 v117, v245
	v_pk_mul_f32 v[244:245], v[86:87], s[100:101]
	v_exp_f32_e32 v244, v244
	v_exp_f32_e32 v245, v245
	s_nop 0
	v_pk_add_f32 v[244:245], v[244:245], s[98:99]
	v_rcp_f32_e32 v114, v244
	v_rcp_f32_e32 v115, v245
	v_pk_mul_f32 v[88:89], v[140:141], v[88:89]
	v_pk_mul_f32 v[86:87], v[138:139], v[86:87]
	v_pk_mul_f32 v[88:89], v[88:89], v[116:117]
	v_pk_mul_f32 v[86:87], v[86:87], v[114:115]
	v_pk_fma_f32 v[114:115], v[92:93], v[142:143], v[110:111]
	v_fmac_f32_dpp v114, v92, v126 row_shr:1 row_mask:0xf bank_mask:0xf
	s_nop 0
	v_fmac_f32_dpp v114, v92, v122 row_shr:2 row_mask:0xf bank_mask:0xf
	v_fma_f32 v92, v90, v144, v112
	v_fmac_f32_dpp v114, v96, v126 row_shl:15 row_mask:0xf bank_mask:0xf
	s_nop 0
	v_fmac_f32_dpp v114, v96, v122 row_shl:14 row_mask:0xf bank_mask:0xf
	v_fmac_f32_dpp v115, v93, v127 row_shr:1 row_mask:0xf bank_mask:0xf
	s_nop 0
	v_fmac_f32_dpp v115, v93, v123 row_shr:2 row_mask:0xf bank_mask:0xf
	s_nop 0
	v_fmac_f32_dpp v115, v97, v127 row_shl:15 row_mask:0xf bank_mask:0xf
	s_nop 0
	v_fmac_f32_dpp v115, v97, v123 row_shl:14 row_mask:0xf bank_mask:0xf
	v_fmac_f32_dpp v92, v90, v128 row_shr:1 row_mask:0xf bank_mask:0xf
	v_fma_f32 v93, v91, v145, v113
	v_fmac_f32_dpp v92, v90, v124 row_shr:2 row_mask:0xf bank_mask:0xf
	s_nop 0
	v_fmac_f32_dpp v92, v94, v128 row_shl:15 row_mask:0xf bank_mask:0xf
	s_nop 0
	v_fmac_f32_dpp v92, v94, v124 row_shl:14 row_mask:0xf bank_mask:0xf
	v_fmac_f32_dpp v93, v91, v129 row_shr:1 row_mask:0xf bank_mask:0xf
	s_nop 0
	v_fmac_f32_dpp v93, v91, v125 row_shr:2 row_mask:0xf bank_mask:0xf
	s_nop 0
	v_fmac_f32_dpp v93, v95, v129 row_shl:15 row_mask:0xf bank_mask:0xf
	s_nop 0
	v_fmac_f32_dpp v93, v95, v125 row_shl:14 row_mask:0xf bank_mask:0xf
	s_nop 0
	s_nop 0
	s_nop 0
	s_nop 0
	s_nop 0
	s_nop 0
	s_nop 0
	v_pk_mul_f32 v[244:245], v[92:93], s[100:101]
	v_exp_f32_e32 v244, v244
	v_exp_f32_e32 v245, v245
	s_nop 0
	v_pk_add_f32 v[244:245], v[244:245], s[98:99]
	v_rcp_f32_e32 v116, v244
	v_rcp_f32_e32 v117, v245
	v_pk_mul_f32 v[244:245], v[114:115], s[100:101]
	v_exp_f32_e32 v244, v244
	v_exp_f32_e32 v245, v245
	s_nop 0
	v_pk_add_f32 v[244:245], v[244:245], s[98:99]
	v_rcp_f32_e32 v90, v244
	v_rcp_f32_e32 v91, v245
	v_pk_mul_f32 v[92:93], v[108:109], v[92:93]
	v_pk_mul_f32 v[106:107], v[106:107], v[114:115]
	v_pk_mul_f32 v[92:93], v[92:93], v[116:117]
	v_pk_mul_f32 v[90:91], v[106:107], v[90:91]
	v_pk_fma_f32 v[106:107], v[96:97], v[142:143], v[110:111]
	v_fmac_f32_dpp v106, v96, v126 row_shr:1 row_mask:0xf bank_mask:0xf
	s_nop 0
	v_fmac_f32_dpp v106, v96, v122 row_shr:2 row_mask:0xf bank_mask:0xf
	v_fma_f32 v96, v94, v144, v112
	v_fmac_f32_dpp v106, v148, v126 row_shl:15 row_mask:0xf bank_mask:0xf
	s_nop 0
	v_fmac_f32_dpp v106, v148, v122 row_shl:14 row_mask:0xf bank_mask:0xf
	v_fmac_f32_dpp v107, v97, v127 row_shr:1 row_mask:0xf bank_mask:0xf
	s_nop 0
	v_fmac_f32_dpp v107, v97, v123 row_shr:2 row_mask:0xf bank_mask:0xf
	s_nop 0
	v_fmac_f32_dpp v107, v149, v127 row_shl:15 row_mask:0xf bank_mask:0xf
	s_nop 0
	v_fmac_f32_dpp v107, v149, v123 row_shl:14 row_mask:0xf bank_mask:0xf
	v_fmac_f32_dpp v96, v94, v128 row_shr:1 row_mask:0xf bank_mask:0xf
	v_fma_f32 v97, v95, v145, v113
	v_fmac_f32_dpp v96, v94, v124 row_shr:2 row_mask:0xf bank_mask:0xf
	s_nop 0
	v_fmac_f32_dpp v96, v146, v128 row_shl:15 row_mask:0xf bank_mask:0xf
	s_nop 0
	v_fmac_f32_dpp v96, v146, v124 row_shl:14 row_mask:0xf bank_mask:0xf
	v_fmac_f32_dpp v97, v95, v129 row_shr:1 row_mask:0xf bank_mask:0xf
	s_nop 0
	v_fmac_f32_dpp v97, v95, v125 row_shr:2 row_mask:0xf bank_mask:0xf
	s_nop 0
	v_fmac_f32_dpp v97, v147, v129 row_shl:15 row_mask:0xf bank_mask:0xf
	s_nop 0
	v_fmac_f32_dpp v97, v147, v125 row_shl:14 row_mask:0xf bank_mask:0xf
	s_nop 0
	s_nop 0
	s_nop 0
	s_nop 0
	s_nop 0
	s_nop 0
	s_nop 0
	v_pk_mul_f32 v[244:245], v[96:97], s[100:101]
	v_exp_f32_e32 v244, v244
	v_exp_f32_e32 v245, v245
	s_nop 0
	v_pk_add_f32 v[244:245], v[244:245], s[98:99]
	v_rcp_f32_e32 v108, v244
	v_rcp_f32_e32 v109, v245
	v_pk_mul_f32 v[244:245], v[106:107], s[100:101]
	v_exp_f32_e32 v244, v244
	v_exp_f32_e32 v245, v245
	s_nop 0
	v_pk_add_f32 v[244:245], v[244:245], s[98:99]
	v_rcp_f32_e32 v94, v244
	v_rcp_f32_e32 v95, v245
	v_pk_mul_f32 v[96:97], v[104:105], v[96:97]
	v_pk_mul_f32 v[102:103], v[102:103], v[106:107]
	v_pk_mul_f32 v[96:97], v[96:97], v[108:109]
	v_pk_mul_f32 v[94:95], v[102:103], v[94:95]
	v_pk_fma_f32 v[102:103], v[148:149], v[142:143], v[110:111]
	v_fmac_f32_dpp v102, v148, v126 row_shr:1 row_mask:0xf bank_mask:0xf
	s_nop 0
	v_fmac_f32_dpp v102, v148, v122 row_shr:2 row_mask:0xf bank_mask:0xf
	v_pk_fma_f32 v[112:113], v[146:147], v[144:145], v[112:113]
	v_fmac_f32_dpp v102, v134, v126 row_shl:15 row_mask:0xf bank_mask:0xf
	s_nop 0
	v_fmac_f32_dpp v102, v134, v122 row_shl:14 row_mask:0xf bank_mask:0xf
	v_fmac_f32_dpp v103, v149, v127 row_shr:1 row_mask:0xf bank_mask:0xf
	v_mov_b32_e32 v122, 0
	v_fmac_f32_dpp v103, v149, v123 row_shr:2 row_mask:0xf bank_mask:0xf
	v_mul_f32_e32 v1, 0xbfb8aa3b, v102
	v_fmac_f32_dpp v103, v135, v127 row_shl:15 row_mask:0xf bank_mask:0xf
	v_exp_f32_e32 v1, v1
	v_fmac_f32_dpp v103, v135, v123 row_shl:14 row_mask:0xf bank_mask:0xf
	v_fmac_f32_dpp v112, v146, v128 row_shr:1 row_mask:0xf bank_mask:0xf
	v_mov_b32_e32 v123, 0
	v_fmac_f32_dpp v112, v146, v124 row_shr:2 row_mask:0xf bank_mask:0xf
	v_add_f32_e32 v1, 1.0, v1
	v_fmac_f32_dpp v112, v136, v128 row_shl:15 row_mask:0xf bank_mask:0xf
	v_rcp_f32_e32 v106, v1
	v_fmac_f32_dpp v112, v136, v124 row_shl:14 row_mask:0xf bank_mask:0xf
	v_fmac_f32_dpp v113, v147, v129 row_shr:1 row_mask:0xf bank_mask:0xf
	v_mul_f32_e32 v1, 0xbfb8aa3b, v103
	v_fmac_f32_dpp v113, v147, v125 row_shr:2 row_mask:0xf bank_mask:0xf
	s_nop 0
	v_fmac_f32_dpp v113, v137, v129 row_shl:15 row_mask:0xf bank_mask:0xf
	v_exp_f32_e32 v1, v1
	v_fmac_f32_dpp v113, v137, v125 row_shl:14 row_mask:0xf bank_mask:0xf
	s_nop 0
	s_nop 0
	s_nop 0
	v_add_f32_e32 v1, 1.0, v1
	s_nop 0
	s_nop 0
	s_nop 0
	v_pk_mul_f32 v[244:245], v[112:113], s[100:101]
	v_exp_f32_e32 v244, v244
	v_exp_f32_e32 v245, v245
	s_nop 0
	v_pk_add_f32 v[244:245], v[244:245], s[98:99]
	v_rcp_f32_e32 v104, v244
	v_rcp_f32_e32 v105, v245
	v_rcp_f32_e32 v107, v1
	v_pk_mul_f32 v[108:109], v[132:133], v[112:113]
	v_pk_mul_f32 v[102:103], v[130:131], v[102:103]
	v_pk_mul_f32 v[104:105], v[108:109], v[104:105]
	v_pk_mul_f32 v[102:103], v[102:103], v[106:107]
	v_mov_b32_e32 v124, 0
	ds_read_b128 v[114:117], v223 offset:528
	ds_read_b128 v[118:121], v223 offset:1552
	ds_read_b128 v[126:129], v223 offset:2576
	ds_read_b128 v[106:109], v223 offset:3600
	v_mov_b32_e32 v125, 0
	s_and_saveexec_b64 s[48:49], s[30:31]
	v_add_u32_e32 v1, s91, v217
	ds_read_b128 v[122:125], v1 offset:512
	s_or_b64 exec, exec, s[48:49]
	s_nop 0
	s_nop 0
	v_pk_fma_f32 v[76:77], v[76:77], v[194:195], v[56:57] op_sel_hi:[1,0,1]
	s_nop 0
	s_nop 0
	v_pk_fma_f32 v[130:131], v[72:73], v[196:197], v[56:57] op_sel_hi:[1,0,1]
	s_waitcnt lgkmcnt(0)
	v_pk_fma_f32 v[110:111], v[98:99], v[126:127], v[106:107]
	s_nop 4
	v_fmac_f32_dpp v110, v98, v118 row_shr:1 row_mask:0xf bank_mask:0xf
	v_pk_fma_f32 v[66:67], v[66:67], v[198:199], v[54:55]
	v_fmac_f32_dpp v110, v98, v114 row_shr:2 row_mask:0xf bank_mask:0xf
	s_nop 0
	v_fmac_f32_dpp v110, v66, v118 row_shl:15 row_mask:0xf bank_mask:0xf
	v_pk_fma_f32 v[112:113], v[100:101], v[128:129], v[108:109]
	v_fmac_f32_dpp v110, v66, v114 row_shl:14 row_mask:0xf bank_mask:0xf
	v_fmac_f32_dpp v111, v99, v119 row_shr:1 row_mask:0xf bank_mask:0xf
	v_pk_fma_f32 v[132:133], v[70:71], v[196:197], v[54:55]
	v_fmac_f32_dpp v111, v99, v115 row_shr:2 row_mask:0xf bank_mask:0xf
	s_nop 0
	v_fmac_f32_dpp v111, v67, v119 row_shl:15 row_mask:0xf bank_mask:0xf
	s_nop 0
	v_fmac_f32_dpp v111, v67, v115 row_shl:14 row_mask:0xf bank_mask:0xf
	v_fmac_f32_dpp v112, v100, v120 row_shr:1 row_mask:0xf bank_mask:0xf
	v_pk_fma_f32 v[68:69], v[68:69], v[198:199], v[56:57] op_sel_hi:[1,0,1]
	v_fmac_f32_dpp v112, v100, v116 row_shr:2 row_mask:0xf bank_mask:0xf
	s_nop 0
	v_fmac_f32_dpp v112, v68, v120 row_shl:15 row_mask:0xf bank_mask:0xf
	v_pk_fma_f32 v[70:71], v[66:67], v[126:127], v[106:107]
	v_fmac_f32_dpp v112, v68, v116 row_shl:14 row_mask:0xf bank_mask:0xf
	v_fmac_f32_dpp v113, v101, v121 row_shr:1 row_mask:0xf bank_mask:0xf
	s_nop 0
	v_fmac_f32_dpp v113, v101, v117 row_shr:2 row_mask:0xf bank_mask:0xf
	v_pk_fma_f32 v[72:73], v[68:69], v[128:129], v[108:109]
	v_fmac_f32_dpp v113, v69, v121 row_shl:15 row_mask:0xf bank_mask:0xf
	s_nop 0
	v_fmac_f32_dpp v113, v69, v117 row_shl:14 row_mask:0xf bank_mask:0xf
	v_pk_fma_f32 v[74:75], v[74:75], v[194:195], v[54:55]
	v_fmac_f32_dpp v70, v66, v118 row_shr:1 row_mask:0xf bank_mask:0xf
	s_nop 0
	v_fmac_f32_dpp v70, v66, v114 row_shr:2 row_mask:0xf bank_mask:0xf
	v_fma_f32 v66, v132, v126, v106
	v_fmac_f32_dpp v70, v132, v118 row_shl:15 row_mask:0xf bank_mask:0xf
	s_nop 0
	v_fmac_f32_dpp v70, v132, v114 row_shl:14 row_mask:0xf bank_mask:0xf
	v_fmac_f32_dpp v71, v67, v119 row_shr:1 row_mask:0xf bank_mask:0xf
	s_nop 0
	v_fmac_f32_dpp v71, v67, v115 row_shr:2 row_mask:0xf bank_mask:0xf
	v_fma_f32 v67, v133, v127, v107
	v_fmac_f32_dpp v71, v133, v119 row_shl:15 row_mask:0xf bank_mask:0xf
	v_pk_fma_f32 v[106:107], v[74:75], v[126:127], v[106:107]
	v_fmac_f32_dpp v71, v133, v115 row_shl:14 row_mask:0xf bank_mask:0xf
	v_fmac_f32_dpp v72, v68, v120 row_shr:1 row_mask:0xf bank_mask:0xf
	s_nop 0
	v_fmac_f32_dpp v72, v68, v116 row_shr:2 row_mask:0xf bank_mask:0xf
	v_fma_f32 v68, v130, v128, v108
	v_fmac_f32_dpp v72, v130, v120 row_shl:15 row_mask:0xf bank_mask:0xf
	s_nop 0
	v_fmac_f32_dpp v72, v130, v116 row_shl:14 row_mask:0xf bank_mask:0xf
	v_fmac_f32_dpp v73, v69, v121 row_shr:1 row_mask:0xf bank_mask:0xf
	s_nop 0
	v_fmac_f32_dpp v73, v69, v117 row_shr:2 row_mask:0xf bank_mask:0xf
	v_fma_f32 v69, v131, v129, v109
	v_fmac_f32_dpp v73, v131, v121 row_shl:15 row_mask:0xf bank_mask:0xf
	v_pk_fma_f32 v[108:109], v[76:77], v[128:129], v[108:109]
	v_fmac_f32_dpp v73, v131, v117 row_shl:14 row_mask:0xf bank_mask:0xf
	s_nop 0
	v_fmac_f32_dpp v66, v132, v118 row_shr:1 row_mask:0xf bank_mask:0xf
	s_nop 0
	v_fmac_f32_dpp v66, v132, v114 row_shr:2 row_mask:0xf bank_mask:0xf
	s_nop 0
	v_fmac_f32_dpp v66, v74, v118 row_shl:15 row_mask:0xf bank_mask:0xf
	s_nop 0
	v_fmac_f32_dpp v66, v74, v114 row_shl:14 row_mask:0xf bank_mask:0xf
	v_fmac_f32_dpp v67, v133, v119 row_shr:1 row_mask:0xf bank_mask:0xf
	s_nop 0
	v_fmac_f32_dpp v67, v133, v115 row_shr:2 row_mask:0xf bank_mask:0xf
	s_nop 0
	v_fmac_f32_dpp v67, v75, v119 row_shl:15 row_mask:0xf bank_mask:0xf
	s_nop 0
	v_fmac_f32_dpp v67, v75, v115 row_shl:14 row_mask:0xf bank_mask:0xf
	v_fmac_f32_dpp v68, v130, v120 row_shr:1 row_mask:0xf bank_mask:0xf
	s_nop 0
	v_fmac_f32_dpp v68, v130, v116 row_shr:2 row_mask:0xf bank_mask:0xf
	s_nop 0
	v_fmac_f32_dpp v68, v76, v120 row_shl:15 row_mask:0xf bank_mask:0xf
	s_nop 0
	v_fmac_f32_dpp v68, v76, v116 row_shl:14 row_mask:0xf bank_mask:0xf
	v_fmac_f32_dpp v69, v131, v121 row_shr:1 row_mask:0xf bank_mask:0xf
	s_nop 0
	v_fmac_f32_dpp v69, v131, v117 row_shr:2 row_mask:0xf bank_mask:0xf
	s_nop 0
	v_fmac_f32_dpp v69, v77, v121 row_shl:15 row_mask:0xf bank_mask:0xf
	s_nop 0
	v_fmac_f32_dpp v69, v77, v117 row_shl:14 row_mask:0xf bank_mask:0xf
	s_nop 0
	v_fmac_f32_dpp v106, v74, v118 row_shr:1 row_mask:0xf bank_mask:0xf
	s_nop 0
	v_fmac_f32_dpp v106, v74, v114 row_shr:2 row_mask:0xf bank_mask:0xf
	s_nop 0
	v_fmac_f32_dpp v106, v122, v118 row_shl:15 row_mask:0xf bank_mask:0xf
	s_nop 0
	v_fmac_f32_dpp v106, v122, v114 row_shl:14 row_mask:0xf bank_mask:0xf
	v_fmac_f32_dpp v107, v75, v119 row_shr:1 row_mask:0xf bank_mask:0xf
	s_nop 0
	v_fmac_f32_dpp v107, v75, v115 row_shr:2 row_mask:0xf bank_mask:0xf
	s_nop 0
	v_fmac_f32_dpp v107, v123, v119 row_shl:15 row_mask:0xf bank_mask:0xf
	s_nop 0
	v_fmac_f32_dpp v107, v123, v115 row_shl:14 row_mask:0xf bank_mask:0xf
	v_fmac_f32_dpp v108, v76, v120 row_shr:1 row_mask:0xf bank_mask:0xf
	s_nop 0
	v_fmac_f32_dpp v108, v76, v116 row_shr:2 row_mask:0xf bank_mask:0xf
	s_nop 0
	v_fmac_f32_dpp v108, v124, v120 row_shl:15 row_mask:0xf bank_mask:0xf
	s_nop 0
	v_fmac_f32_dpp v108, v124, v116 row_shl:14 row_mask:0xf bank_mask:0xf
	v_fmac_f32_dpp v109, v77, v121 row_shr:1 row_mask:0xf bank_mask:0xf
	s_nop 0
	v_fmac_f32_dpp v109, v77, v117 row_shr:2 row_mask:0xf bank_mask:0xf
	s_nop 0
	v_fmac_f32_dpp v109, v125, v121 row_shl:15 row_mask:0xf bank_mask:0xf
	s_nop 0
	v_fmac_f32_dpp v109, v125, v117 row_shl:14 row_mask:0xf bank_mask:0xf
	s_and_saveexec_b64 s[48:49], s[34:35]
	s_cbranch_execz .LBB0_579
	v_or_b32_e32 v74, 4, v200
	v_ashrrev_i32_e32 v75, 31, v74
	v_lshl_add_u64 v[74:75], v[74:75], 2, v[168:169]
	v_add_co_u32_e32 v74, vcc, 0x2000, v74
	s_nop 1
	v_addc_co_u32_e32 v75, vcc, 0, v75, vcc
	global_store_dwordx4 v[74:75], v[106:109], off offset:3072
.LBB0_579:
	s_or_b64 exec, exec, s[48:49]
	s_nop 0
	ds_read_b128 v[98:101], v223 offset:16
	ds_read_b128 v[114:117], v223 offset:1040
	ds_read_b128 v[122:125], v223 offset:2064
	ds_read_b128 v[74:77], v223 offset:3088
	v_mov_b32_e32 v118, 0
	v_mov_b32_e32 v119, 0
	v_mov_b32_e32 v120, 0
	v_mov_b32_e32 v121, 0
	s_and_saveexec_b64 s[48:49], s[30:31]
	v_add_u32_e32 v1, 0, v217
	v_add_u32_e32 v1, 0x20000, v1
	ds_read_b128 v[118:121], v1
	s_or_b64 exec, exec, s[48:49]
	v_pk_fma_f32 v[128:129], v[42:43], v[194:195], v[30:31]
	s_nop 0
	s_nop 0
	v_pk_fma_f32 v[42:43], v[40:41], v[196:197], v[32:33] op_sel_hi:[1,0,1]
	v_pk_fma_f32 v[40:41], v[34:35], v[198:199], v[30:31]
	s_waitcnt lgkmcnt(0)
	v_pk_fma_f32 v[34:35], v[82:83], v[122:123], v[74:75]
	s_nop 4
	v_fmac_f32_dpp v34, v82, v114 row_shr:1 row_mask:0xf bank_mask:0xf
	s_nop 0
	v_fmac_f32_dpp v34, v82, v98 row_shr:2 row_mask:0xf bank_mask:0xf
	s_nop 0
	v_fmac_f32_dpp v34, v40, v114 row_shl:15 row_mask:0xf bank_mask:0xf
	s_nop 0
	v_fmac_f32_dpp v34, v40, v98 row_shl:14 row_mask:0xf bank_mask:0xf
	v_fmac_f32_dpp v35, v83, v115 row_shr:1 row_mask:0xf bank_mask:0xf
	v_pk_fma_f32 v[126:127], v[44:45], v[194:195], v[32:33] op_sel_hi:[1,0,1]
	v_pk_fma_f32 v[44:45], v[38:39], v[196:197], v[30:31]
	s_nop 0
	s_nop 0
	v_fmac_f32_dpp v35, v83, v99 row_shr:2 row_mask:0xf bank_mask:0xf
	v_pk_fma_f32 v[38:39], v[36:37], v[198:199], v[32:33] op_sel_hi:[1,0,1]
	v_fmac_f32_dpp v35, v41, v115 row_shl:15 row_mask:0xf bank_mask:0xf
	v_pk_fma_f32 v[36:37], v[84:85], v[124:125], v[76:77]
	v_fmac_f32_dpp v35, v41, v99 row_shl:14 row_mask:0xf bank_mask:0xf
	v_fmac_f32_dpp v36, v84, v116 row_shr:1 row_mask:0xf bank_mask:0xf
	s_nop 0
	v_fmac_f32_dpp v36, v84, v100 row_shr:2 row_mask:0xf bank_mask:0xf
	s_nop 0
	v_fmac_f32_dpp v36, v38, v116 row_shl:15 row_mask:0xf bank_mask:0xf
	s_nop 0
	v_fmac_f32_dpp v36, v38, v100 row_shl:14 row_mask:0xf bank_mask:0xf
	v_fmac_f32_dpp v37, v85, v117 row_shr:1 row_mask:0xf bank_mask:0xf
	s_nop 0
	v_fmac_f32_dpp v37, v85, v101 row_shr:2 row_mask:0xf bank_mask:0xf
	s_nop 0
	v_fmac_f32_dpp v37, v39, v117 row_shl:15 row_mask:0xf bank_mask:0xf
	s_nop 0
	v_fmac_f32_dpp v37, v39, v101 row_shl:14 row_mask:0xf bank_mask:0xf
	s_nop 0
	s_nop 0
	s_nop 0
	s_nop 0
	s_nop 0
	s_nop 0
	s_nop 0
	s_nop 0
	s_nop 0
	v_pk_mul_f32 v[244:245], v[36:37], s[100:101]
	v_exp_f32_e32 v244, v244
	v_exp_f32_e32 v245, v245
	s_nop 0
	v_pk_add_f32 v[244:245], v[244:245], s[98:99]
	v_rcp_f32_e32 v84, v244
	v_rcp_f32_e32 v85, v245
	v_pk_mul_f32 v[244:245], v[34:35], s[100:101]
	v_exp_f32_e32 v244, v244
	v_exp_f32_e32 v245, v245
	s_nop 0
	v_pk_add_f32 v[244:245], v[244:245], s[98:99]
	v_rcp_f32_e32 v82, v244
	v_rcp_f32_e32 v83, v245
	v_pk_mul_f32 v[36:37], v[112:113], v[36:37]
	v_pk_mul_f32 v[34:35], v[110:111], v[34:35]
	v_pk_mul_f32 v[36:37], v[36:37], v[84:85]
	v_pk_mul_f32 v[34:35], v[34:35], v[82:83]
	v_pk_fma_f32 v[82:83], v[40:41], v[122:123], v[74:75]
	v_fmac_f32_dpp v82, v40, v114 row_shr:1 row_mask:0xf bank_mask:0xf
	s_nop 0
	v_fmac_f32_dpp v82, v40, v98 row_shr:2 row_mask:0xf bank_mask:0xf
	v_fma_f32 v40, v38, v124, v76
	v_fmac_f32_dpp v82, v44, v114 row_shl:15 row_mask:0xf bank_mask:0xf
	s_nop 0
	v_fmac_f32_dpp v82, v44, v98 row_shl:14 row_mask:0xf bank_mask:0xf
	v_fmac_f32_dpp v83, v41, v115 row_shr:1 row_mask:0xf bank_mask:0xf
	s_nop 0
	v_fmac_f32_dpp v83, v41, v99 row_shr:2 row_mask:0xf bank_mask:0xf
	s_nop 0
	v_fmac_f32_dpp v83, v45, v115 row_shl:15 row_mask:0xf bank_mask:0xf
	s_nop 0
	v_fmac_f32_dpp v83, v45, v99 row_shl:14 row_mask:0xf bank_mask:0xf
	v_fmac_f32_dpp v40, v38, v116 row_shr:1 row_mask:0xf bank_mask:0xf
	v_fma_f32 v41, v39, v125, v77
	v_fmac_f32_dpp v40, v38, v100 row_shr:2 row_mask:0xf bank_mask:0xf
	s_nop 0
	v_fmac_f32_dpp v40, v42, v116 row_shl:15 row_mask:0xf bank_mask:0xf
	s_nop 0
	v_fmac_f32_dpp v40, v42, v100 row_shl:14 row_mask:0xf bank_mask:0xf
	v_fmac_f32_dpp v41, v39, v117 row_shr:1 row_mask:0xf bank_mask:0xf
	s_nop 0
	v_fmac_f32_dpp v41, v39, v101 row_shr:2 row_mask:0xf bank_mask:0xf
	s_nop 0
	v_fmac_f32_dpp v41, v43, v117 row_shl:15 row_mask:0xf bank_mask:0xf
	s_nop 0
	v_fmac_f32_dpp v41, v43, v101 row_shl:14 row_mask:0xf bank_mask:0xf
	s_nop 0
	s_nop 0
	s_nop 0
	s_nop 0
	s_nop 0
	s_nop 0
	s_nop 0
	v_pk_mul_f32 v[244:245], v[40:41], s[100:101]
	v_exp_f32_e32 v244, v244
	v_exp_f32_e32 v245, v245
	s_nop 0
	v_pk_add_f32 v[244:245], v[244:245], s[98:99]
	v_rcp_f32_e32 v84, v244
	v_rcp_f32_e32 v85, v245
	v_pk_mul_f32 v[244:245], v[82:83], s[100:101]
	v_exp_f32_e32 v244, v244
	v_exp_f32_e32 v245, v245
	s_nop 0
	v_pk_add_f32 v[244:245], v[244:245], s[98:99]
	v_rcp_f32_e32 v38, v244
	v_rcp_f32_e32 v39, v245
	v_pk_mul_f32 v[40:41], v[72:73], v[40:41]
	v_pk_mul_f32 v[70:71], v[70:71], v[82:83]
	v_pk_mul_f32 v[40:41], v[40:41], v[84:85]
	v_pk_mul_f32 v[38:39], v[70:71], v[38:39]
	v_pk_fma_f32 v[70:71], v[44:45], v[122:123], v[74:75]
	v_fmac_f32_dpp v70, v44, v114 row_shr:1 row_mask:0xf bank_mask:0xf
	s_nop 0
	v_fmac_f32_dpp v70, v44, v98 row_shr:2 row_mask:0xf bank_mask:0xf
	v_fma_f32 v44, v42, v124, v76
	v_fmac_f32_dpp v70, v128, v114 row_shl:15 row_mask:0xf bank_mask:0xf
	v_pk_fma_f32 v[74:75], v[128:129], v[122:123], v[74:75]
	v_fmac_f32_dpp v70, v128, v98 row_shl:14 row_mask:0xf bank_mask:0xf
	v_fmac_f32_dpp v71, v45, v115 row_shr:1 row_mask:0xf bank_mask:0xf
	s_nop 0
	v_fmac_f32_dpp v71, v45, v99 row_shr:2 row_mask:0xf bank_mask:0xf
	v_mul_f32_e32 v1, 0xbfb8aa3b, v70
	v_fmac_f32_dpp v71, v129, v115 row_shl:15 row_mask:0xf bank_mask:0xf
	v_exp_f32_e32 v1, v1
	v_fmac_f32_dpp v71, v129, v99 row_shl:14 row_mask:0xf bank_mask:0xf
	v_fmac_f32_dpp v44, v42, v116 row_shr:1 row_mask:0xf bank_mask:0xf
	v_fma_f32 v45, v43, v125, v77
	v_fmac_f32_dpp v44, v42, v100 row_shr:2 row_mask:0xf bank_mask:0xf
	v_add_f32_e32 v1, 1.0, v1
	v_fmac_f32_dpp v44, v126, v116 row_shl:15 row_mask:0xf bank_mask:0xf
	v_rcp_f32_e32 v42, v1
	v_fmac_f32_dpp v44, v126, v100 row_shl:14 row_mask:0xf bank_mask:0xf
	v_fmac_f32_dpp v45, v43, v117 row_shr:1 row_mask:0xf bank_mask:0xf
	v_mul_f32_e32 v1, 0xbfb8aa3b, v71
	v_fmac_f32_dpp v45, v43, v101 row_shr:2 row_mask:0xf bank_mask:0xf
	s_nop 0
	v_fmac_f32_dpp v45, v127, v117 row_shl:15 row_mask:0xf bank_mask:0xf
	s_nop 0
	v_fmac_f32_dpp v45, v127, v101 row_shl:14 row_mask:0xf bank_mask:0xf
	v_exp_f32_e32 v1, v1
	s_nop 0
	s_nop 0
	s_nop 0
	v_add_f32_e32 v1, 1.0, v1
	s_nop 0
	s_nop 0
	v_pk_mul_f32 v[244:245], v[44:45], s[100:101]
	v_exp_f32_e32 v244, v244
	v_exp_f32_e32 v245, v245
	s_nop 0
	v_pk_add_f32 v[244:245], v[244:245], s[98:99]
	v_rcp_f32_e32 v72, v244
	v_rcp_f32_e32 v73, v245
	v_rcp_f32_e32 v43, v1
	v_pk_mul_f32 v[44:45], v[68:69], v[44:45]
	v_pk_mul_f32 v[66:67], v[66:67], v[70:71]
	v_pk_mul_f32 v[44:45], v[44:45], v[72:73]
	v_pk_mul_f32 v[42:43], v[66:67], v[42:43]
	v_pk_fma_f32 v[76:77], v[126:127], v[124:125], v[76:77]
	v_fmac_f32_dpp v74, v128, v114 row_shr:1 row_mask:0xf bank_mask:0xf
	s_nop 0
	v_fmac_f32_dpp v74, v128, v98 row_shr:2 row_mask:0xf bank_mask:0xf
	s_nop 0
	v_fmac_f32_dpp v74, v118, v114 row_shl:15 row_mask:0xf bank_mask:0xf
	s_nop 0
	v_fmac_f32_dpp v74, v118, v98 row_shl:14 row_mask:0xf bank_mask:0xf
	v_fmac_f32_dpp v75, v129, v115 row_shr:1 row_mask:0xf bank_mask:0xf
	s_nop 0
	v_fmac_f32_dpp v75, v129, v99 row_shr:2 row_mask:0xf bank_mask:0xf
	s_nop 0
	v_fmac_f32_dpp v75, v119, v115 row_shl:15 row_mask:0xf bank_mask:0xf
	s_nop 0
	v_fmac_f32_dpp v75, v119, v99 row_shl:14 row_mask:0xf bank_mask:0xf
	v_fmac_f32_dpp v76, v126, v116 row_shr:1 row_mask:0xf bank_mask:0xf
	s_nop 0
	v_fmac_f32_dpp v76, v126, v100 row_shr:2 row_mask:0xf bank_mask:0xf
	s_nop 0
	v_fmac_f32_dpp v76, v120, v116 row_shl:15 row_mask:0xf bank_mask:0xf
	s_nop 0
	v_fmac_f32_dpp v76, v120, v100 row_shl:14 row_mask:0xf bank_mask:0xf
	v_fmac_f32_dpp v77, v127, v117 row_shr:1 row_mask:0xf bank_mask:0xf
	s_nop 0
	v_fmac_f32_dpp v77, v127, v101 row_shr:2 row_mask:0xf bank_mask:0xf
	s_nop 0
	v_fmac_f32_dpp v77, v121, v117 row_shl:15 row_mask:0xf bank_mask:0xf
	s_nop 0
	v_fmac_f32_dpp v77, v121, v101 row_shl:14 row_mask:0xf bank_mask:0xf
	s_and_saveexec_b64 s[48:49], s[34:35]
	s_cbranch_execz .LBB0_583
	global_store_dwordx4 v[166:167], v[74:77], off offset:16
.LBB0_583:
	s_or_b64 exec, exec, s[48:49]
	s_nop 0
	s_nop 0
	s_nop 0
	v_mul_f32_e32 v67, 0xbfb8aa3b, v76
	s_nop 0
	s_nop 0
	s_nop 0
	v_exp_f32_e32 v1, v67
	v_mul_f32_e32 v67, 0xbfb8aa3b, v77
	v_exp_f32_e32 v67, v67
	s_nop 0
	v_add_f32_e32 v1, 1.0, v1
	v_rcp_f32_e32 v68, v1
	v_add_f32_e32 v1, 1.0, v67
	v_rcp_f32_e32 v69, v1
	v_pk_mul_f32 v[244:245], v[74:75], s[100:101]
	v_exp_f32_e32 v244, v244
	v_exp_f32_e32 v245, v245
	s_nop 0
	v_pk_add_f32 v[244:245], v[244:245], s[98:99]
	v_rcp_f32_e32 v66, v244
	v_rcp_f32_e32 v67, v245
	v_pk_mul_f32 v[70:71], v[108:109], v[76:77]
	v_pk_mul_f32 v[72:73], v[106:107], v[74:75]
	v_pk_mul_f32 v[68:69], v[70:71], v[68:69]
	v_pk_mul_f32 v[66:67], v[72:73], v[66:67]
	v_mov_b32_e32 v74, 0
	ds_read_b128 v[98:101], v223 offset:528
	ds_read_b128 v[106:109], v223 offset:1552
	ds_read_b128 v[114:117], v223 offset:2576
	ds_read_b128 v[70:73], v223 offset:3600
	v_mov_b32_e32 v110, 0
	v_mov_b32_e32 v111, 0
	v_mov_b32_e32 v112, 0
	v_mov_b32_e32 v113, 0
	s_and_saveexec_b64 s[48:49], s[0:1]
	v_add_u32_e32 v1, s91, v218
	ds_read_b128 v[110:113], v1 offset:512
	s_or_b64 exec, exec, s[48:49]
	s_waitcnt lgkmcnt(0)
	v_pk_fma_f32 v[82:83], v[58:59], v[114:115], v[70:71]
	s_nop 4
	v_fmac_f32_dpp v82, v58, v106 row_shr:1 row_mask:0xf bank_mask:0xf
	v_pk_fma_f32 v[14:15], v[14:15], v[160:161], v[54:55]
	v_fmac_f32_dpp v82, v58, v98 row_shr:2 row_mask:0xf bank_mask:0xf
	s_nop 0
	v_fmac_f32_dpp v82, v14, v106 row_shl:15 row_mask:0xf bank_mask:0xf
	v_pk_fma_f32 v[84:85], v[60:61], v[116:117], v[72:73]
	v_fmac_f32_dpp v82, v14, v98 row_shl:14 row_mask:0xf bank_mask:0xf
	v_fmac_f32_dpp v83, v59, v107 row_shr:1 row_mask:0xf bank_mask:0xf
	v_mov_b32_e32 v122, v160
	v_fmac_f32_dpp v83, v59, v99 row_shr:2 row_mask:0xf bank_mask:0xf
	v_mov_b32_e32 v123, v160
	v_fmac_f32_dpp v83, v15, v107 row_shl:15 row_mask:0xf bank_mask:0xf
	v_pk_fma_f32 v[16:17], v[16:17], v[160:161], v[56:57] op_sel_hi:[1,0,1]
	v_fmac_f32_dpp v83, v15, v99 row_shl:14 row_mask:0xf bank_mask:0xf
	v_fmac_f32_dpp v84, v60, v108 row_shr:1 row_mask:0xf bank_mask:0xf
	s_nop 0
	v_fmac_f32_dpp v84, v60, v100 row_shr:2 row_mask:0xf bank_mask:0xf
	v_pk_fma_f32 v[124:125], v[18:19], v[162:163], v[54:55]
	v_fmac_f32_dpp v84, v16, v108 row_shl:15 row_mask:0xf bank_mask:0xf
	v_pk_fma_f32 v[18:19], v[14:15], v[114:115], v[70:71]
	v_fmac_f32_dpp v84, v16, v100 row_shl:14 row_mask:0xf bank_mask:0xf
	v_fmac_f32_dpp v85, v61, v109 row_shr:1 row_mask:0xf bank_mask:0xf
	s_nop 0
	v_fmac_f32_dpp v85, v61, v101 row_shr:2 row_mask:0xf bank_mask:0xf
	v_mov_b32_e32 v120, v162
	v_fmac_f32_dpp v85, v17, v109 row_shl:15 row_mask:0xf bank_mask:0xf
	v_mov_b32_e32 v121, v162
	v_fmac_f32_dpp v85, v17, v101 row_shl:14 row_mask:0xf bank_mask:0xf
	v_pk_fma_f32 v[76:77], v[20:21], v[162:163], v[56:57] op_sel_hi:[1,0,1]
	v_fmac_f32_dpp v18, v14, v106 row_shr:1 row_mask:0xf bank_mask:0xf
	v_pk_fma_f32 v[20:21], v[16:17], v[116:117], v[72:73]
	v_fmac_f32_dpp v18, v14, v98 row_shr:2 row_mask:0xf bank_mask:0xf
	s_nop 0
	v_fmac_f32_dpp v18, v124, v106 row_shl:15 row_mask:0xf bank_mask:0xf
	s_nop 0
	v_fmac_f32_dpp v18, v124, v98 row_shl:14 row_mask:0xf bank_mask:0xf
	v_fmac_f32_dpp v19, v15, v107 row_shr:1 row_mask:0xf bank_mask:0xf
	v_pk_fma_f32 v[22:23], v[22:23], v[158:159], v[54:55]
	v_fmac_f32_dpp v19, v15, v99 row_shr:2 row_mask:0xf bank_mask:0xf
	v_pk_fma_f32 v[14:15], v[124:125], v[114:115], v[70:71]
	v_fmac_f32_dpp v19, v125, v107 row_shl:15 row_mask:0xf bank_mask:0xf
	v_mov_b32_e32 v118, v158
	v_fmac_f32_dpp v19, v125, v99 row_shl:14 row_mask:0xf bank_mask:0xf
	v_fmac_f32_dpp v20, v16, v108 row_shr:1 row_mask:0xf bank_mask:0xf
	v_mov_b32_e32 v119, v158
	v_fmac_f32_dpp v20, v16, v100 row_shr:2 row_mask:0xf bank_mask:0xf
	s_nop 0
	v_fmac_f32_dpp v20, v76, v108 row_shl:15 row_mask:0xf bank_mask:0xf
	v_pk_fma_f32 v[24:25], v[24:25], v[158:159], v[56:57] op_sel_hi:[1,0,1]
	v_fmac_f32_dpp v20, v76, v100 row_shl:14 row_mask:0xf bank_mask:0xf
	v_fmac_f32_dpp v21, v17, v109 row_shr:1 row_mask:0xf bank_mask:0xf
	v_pk_fma_f32 v[70:71], v[22:23], v[114:115], v[70:71]
	v_fmac_f32_dpp v21, v17, v101 row_shr:2 row_mask:0xf bank_mask:0xf
	v_pk_fma_f32 v[16:17], v[76:77], v[116:117], v[72:73]
	v_fmac_f32_dpp v21, v77, v109 row_shl:15 row_mask:0xf bank_mask:0xf
	s_nop 0
	v_fmac_f32_dpp v21, v77, v101 row_shl:14 row_mask:0xf bank_mask:0xf
	v_pk_fma_f32 v[72:73], v[24:25], v[116:117], v[72:73]
	v_fmac_f32_dpp v14, v124, v106 row_shr:1 row_mask:0xf bank_mask:0xf
	s_nop 0
	v_fmac_f32_dpp v14, v124, v98 row_shr:2 row_mask:0xf bank_mask:0xf
	v_mov_b32_e32 v75, 0
	v_fmac_f32_dpp v14, v22, v106 row_shl:15 row_mask:0xf bank_mask:0xf
	s_nop 0
	v_fmac_f32_dpp v14, v22, v98 row_shl:14 row_mask:0xf bank_mask:0xf
	v_fmac_f32_dpp v15, v125, v107 row_shr:1 row_mask:0xf bank_mask:0xf
	s_nop 0
	v_fmac_f32_dpp v15, v125, v99 row_shr:2 row_mask:0xf bank_mask:0xf
	s_nop 0
	v_fmac_f32_dpp v15, v23, v107 row_shl:15 row_mask:0xf bank_mask:0xf
	s_nop 0
	v_fmac_f32_dpp v15, v23, v99 row_shl:14 row_mask:0xf bank_mask:0xf
	v_fmac_f32_dpp v16, v76, v108 row_shr:1 row_mask:0xf bank_mask:0xf
	s_nop 0
	v_fmac_f32_dpp v16, v76, v100 row_shr:2 row_mask:0xf bank_mask:0xf
	v_mov_b32_e32 v76, 0
	v_fmac_f32_dpp v16, v24, v108 row_shl:15 row_mask:0xf bank_mask:0xf
	s_nop 0
	v_fmac_f32_dpp v16, v24, v100 row_shl:14 row_mask:0xf bank_mask:0xf
	v_fmac_f32_dpp v17, v77, v109 row_shr:1 row_mask:0xf bank_mask:0xf
	s_nop 0
	v_fmac_f32_dpp v17, v77, v101 row_shr:2 row_mask:0xf bank_mask:0xf
	v_mov_b32_e32 v77, 0
	v_fmac_f32_dpp v17, v25, v109 row_shl:15 row_mask:0xf bank_mask:0xf
	s_nop 0
	v_fmac_f32_dpp v17, v25, v101 row_shl:14 row_mask:0xf bank_mask:0xf
	s_nop 0
	v_fmac_f32_dpp v70, v22, v106 row_shr:1 row_mask:0xf bank_mask:0xf
	s_nop 0
	v_fmac_f32_dpp v70, v22, v98 row_shr:2 row_mask:0xf bank_mask:0xf
	s_nop 0
	v_fmac_f32_dpp v70, v110, v106 row_shl:15 row_mask:0xf bank_mask:0xf
	s_nop 0
	v_fmac_f32_dpp v70, v110, v98 row_shl:14 row_mask:0xf bank_mask:0xf
	v_fmac_f32_dpp v71, v23, v107 row_shr:1 row_mask:0xf bank_mask:0xf
	s_nop 0
	v_fmac_f32_dpp v71, v23, v99 row_shr:2 row_mask:0xf bank_mask:0xf
	s_nop 0
	v_fmac_f32_dpp v71, v111, v107 row_shl:15 row_mask:0xf bank_mask:0xf
	s_nop 0
	v_fmac_f32_dpp v71, v111, v99 row_shl:14 row_mask:0xf bank_mask:0xf
	v_fmac_f32_dpp v72, v24, v108 row_shr:1 row_mask:0xf bank_mask:0xf
	s_nop 0
	v_fmac_f32_dpp v72, v24, v100 row_shr:2 row_mask:0xf bank_mask:0xf
	s_nop 0
	v_fmac_f32_dpp v72, v112, v108 row_shl:15 row_mask:0xf bank_mask:0xf
	s_nop 0
	v_fmac_f32_dpp v72, v112, v100 row_shl:14 row_mask:0xf bank_mask:0xf
	v_fmac_f32_dpp v73, v25, v109 row_shr:1 row_mask:0xf bank_mask:0xf
	s_nop 0
	v_fmac_f32_dpp v73, v25, v101 row_shr:2 row_mask:0xf bank_mask:0xf
	s_nop 0
	v_fmac_f32_dpp v73, v113, v109 row_shl:15 row_mask:0xf bank_mask:0xf
	s_nop 0
	v_fmac_f32_dpp v73, v113, v101 row_shl:14 row_mask:0xf bank_mask:0xf
	s_nop 0
	ds_read_b128 v[54:57], v223 offset:16
	ds_read_b128 v[58:61], v223 offset:1040
	ds_read_b128 v[98:101], v223 offset:2064
	ds_read_b128 v[22:25], v223 offset:3088
	s_and_saveexec_b64 s[48:49], s[0:1]
	v_add_u32_e32 v1, 0, v218
	v_add_u32_e32 v1, 0x20000, v1
	ds_read_b128 v[74:77], v1
	s_or_b64 exec, exec, s[48:49]
	v_pk_fma_f32 v[106:107], v[8:9], v[162:163], v[32:33] op_sel_hi:[1,0,1]
	v_pk_fma_f32 v[8:9], v[2:3], v[160:161], v[30:31]
	s_waitcnt lgkmcnt(0)
	v_pk_fma_f32 v[2:3], v[26:27], v[98:99], v[22:23]
	s_nop 4
	v_fmac_f32_dpp v2, v26, v58 row_shr:1 row_mask:0xf bank_mask:0xf
	s_nop 0
	v_fmac_f32_dpp v2, v26, v54 row_shr:2 row_mask:0xf bank_mask:0xf
	v_pk_fma_f32 v[108:109], v[6:7], v[162:163], v[30:31]
	v_fmac_f32_dpp v2, v8, v58 row_shl:15 row_mask:0xf bank_mask:0xf
	v_pk_fma_f32 v[6:7], v[4:5], v[160:161], v[32:33] op_sel_hi:[1,0,1]
	v_fmac_f32_dpp v2, v8, v54 row_shl:14 row_mask:0xf bank_mask:0xf
	v_fmac_f32_dpp v3, v27, v59 row_shr:1 row_mask:0xf bank_mask:0xf
	v_pk_fma_f32 v[4:5], v[28:29], v[100:101], v[24:25]
	v_fmac_f32_dpp v3, v27, v55 row_shr:2 row_mask:0xf bank_mask:0xf
	s_nop 0
	v_fmac_f32_dpp v3, v9, v59 row_shl:15 row_mask:0xf bank_mask:0xf
	s_nop 0
	v_fmac_f32_dpp v3, v9, v55 row_shl:14 row_mask:0xf bank_mask:0xf
	v_fmac_f32_dpp v4, v28, v60 row_shr:1 row_mask:0xf bank_mask:0xf
	s_nop 0
	v_fmac_f32_dpp v4, v28, v56 row_shr:2 row_mask:0xf bank_mask:0xf
	s_nop 0
	v_fmac_f32_dpp v4, v6, v60 row_shl:15 row_mask:0xf bank_mask:0xf
	s_nop 0
	v_fmac_f32_dpp v4, v6, v56 row_shl:14 row_mask:0xf bank_mask:0xf
	v_fmac_f32_dpp v5, v29, v61 row_shr:1 row_mask:0xf bank_mask:0xf
	s_nop 0
	v_fmac_f32_dpp v5, v29, v57 row_shr:2 row_mask:0xf bank_mask:0xf
	s_nop 0
	v_fmac_f32_dpp v5, v7, v61 row_shl:15 row_mask:0xf bank_mask:0xf
	s_nop 0
	v_fmac_f32_dpp v5, v7, v57 row_shl:14 row_mask:0xf bank_mask:0xf
	s_nop 0
	s_nop 0
	s_nop 0
	s_nop 0
	s_nop 0
	s_nop 0
	s_nop 0
	v_pk_mul_f32 v[244:245], v[4:5], s[100:101]
	v_exp_f32_e32 v244, v244
	v_exp_f32_e32 v245, v245
	s_nop 0
	v_pk_add_f32 v[244:245], v[244:245], s[98:99]
	v_rcp_f32_e32 v28, v244
	v_rcp_f32_e32 v29, v245
	v_pk_mul_f32 v[244:245], v[2:3], s[100:101]
	v_exp_f32_e32 v244, v244
	v_exp_f32_e32 v245, v245
	s_nop 0
	v_pk_add_f32 v[244:245], v[244:245], s[98:99]
	v_rcp_f32_e32 v26, v244
	v_rcp_f32_e32 v27, v245
	v_pk_mul_f32 v[4:5], v[84:85], v[4:5]
	v_pk_mul_f32 v[2:3], v[82:83], v[2:3]
	v_pk_mul_f32 v[4:5], v[4:5], v[28:29]
	v_pk_mul_f32 v[2:3], v[2:3], v[26:27]
	v_pk_fma_f32 v[26:27], v[8:9], v[98:99], v[22:23]
	v_fmac_f32_dpp v26, v8, v58 row_shr:1 row_mask:0xf bank_mask:0xf
	s_nop 0
	v_fmac_f32_dpp v26, v8, v54 row_shr:2 row_mask:0xf bank_mask:0xf
	v_fma_f32 v8, v6, v100, v24
	v_fmac_f32_dpp v26, v108, v58 row_shl:15 row_mask:0xf bank_mask:0xf
	v_pk_fma_f32 v[10:11], v[10:11], v[158:159], v[30:31]
	v_fmac_f32_dpp v26, v108, v54 row_shl:14 row_mask:0xf bank_mask:0xf
	v_fmac_f32_dpp v27, v9, v59 row_shr:1 row_mask:0xf bank_mask:0xf
	v_pk_fma_f32 v[12:13], v[12:13], v[158:159], v[32:33] op_sel_hi:[1,0,1]
	v_fmac_f32_dpp v27, v9, v55 row_shr:2 row_mask:0xf bank_mask:0xf
	s_nop 0
	v_fmac_f32_dpp v27, v109, v59 row_shl:15 row_mask:0xf bank_mask:0xf
	s_nop 0
	v_fmac_f32_dpp v27, v109, v55 row_shl:14 row_mask:0xf bank_mask:0xf
	v_fmac_f32_dpp v8, v6, v60 row_shr:1 row_mask:0xf bank_mask:0xf
	v_fma_f32 v9, v7, v101, v25
	v_fmac_f32_dpp v8, v6, v56 row_shr:2 row_mask:0xf bank_mask:0xf
	s_nop 0
	v_fmac_f32_dpp v8, v106, v60 row_shl:15 row_mask:0xf bank_mask:0xf
	s_nop 0
	v_fmac_f32_dpp v8, v106, v56 row_shl:14 row_mask:0xf bank_mask:0xf
	v_fmac_f32_dpp v9, v7, v61 row_shr:1 row_mask:0xf bank_mask:0xf
	s_nop 0
	v_fmac_f32_dpp v9, v7, v57 row_shr:2 row_mask:0xf bank_mask:0xf
	s_nop 0
	v_fmac_f32_dpp v9, v107, v61 row_shl:15 row_mask:0xf bank_mask:0xf
	s_nop 0
	v_fmac_f32_dpp v9, v107, v57 row_shl:14 row_mask:0xf bank_mask:0xf
	s_nop 0
	s_nop 0
	s_nop 0
	s_nop 0
	s_nop 0
	s_nop 0
	s_nop 0
	v_pk_mul_f32 v[244:245], v[8:9], s[100:101]
	v_exp_f32_e32 v244, v244
	v_exp_f32_e32 v245, v245
	s_nop 0
	v_pk_add_f32 v[244:245], v[244:245], s[98:99]
	v_rcp_f32_e32 v28, v244
	v_rcp_f32_e32 v29, v245
	v_pk_mul_f32 v[244:245], v[26:27], s[100:101]
	v_exp_f32_e32 v244, v244
	v_exp_f32_e32 v245, v245
	s_nop 0
	v_pk_add_f32 v[244:245], v[244:245], s[98:99]
	v_rcp_f32_e32 v6, v244
	v_rcp_f32_e32 v7, v245
	v_pk_mul_f32 v[8:9], v[20:21], v[8:9]
	v_pk_mul_f32 v[18:19], v[18:19], v[26:27]
	v_pk_mul_f32 v[8:9], v[8:9], v[28:29]
	v_pk_mul_f32 v[6:7], v[18:19], v[6:7]
	v_pk_fma_f32 v[18:19], v[108:109], v[98:99], v[22:23]
	v_fmac_f32_dpp v18, v108, v58 row_shr:1 row_mask:0xf bank_mask:0xf
	s_nop 0
	v_fmac_f32_dpp v18, v108, v54 row_shr:2 row_mask:0xf bank_mask:0xf
	v_pk_fma_f32 v[20:21], v[106:107], v[100:101], v[24:25]
	v_fmac_f32_dpp v18, v10, v58 row_shl:15 row_mask:0xf bank_mask:0xf
	s_nop 0
	v_fmac_f32_dpp v18, v10, v54 row_shl:14 row_mask:0xf bank_mask:0xf
	v_fmac_f32_dpp v19, v109, v59 row_shr:1 row_mask:0xf bank_mask:0xf
	v_pk_fma_f32 v[24:25], v[12:13], v[100:101], v[24:25]
	v_fmac_f32_dpp v19, v109, v55 row_shr:2 row_mask:0xf bank_mask:0xf
	s_nop 0
	v_fmac_f32_dpp v19, v11, v59 row_shl:15 row_mask:0xf bank_mask:0xf
	s_nop 0
	v_fmac_f32_dpp v19, v11, v55 row_shl:14 row_mask:0xf bank_mask:0xf
	v_fmac_f32_dpp v20, v106, v60 row_shr:1 row_mask:0xf bank_mask:0xf
	s_nop 0
	v_fmac_f32_dpp v20, v106, v56 row_shr:2 row_mask:0xf bank_mask:0xf
	s_nop 0
	v_fmac_f32_dpp v20, v12, v60 row_shl:15 row_mask:0xf bank_mask:0xf
	s_nop 0
	v_fmac_f32_dpp v20, v12, v56 row_shl:14 row_mask:0xf bank_mask:0xf
	v_fmac_f32_dpp v21, v107, v61 row_shr:1 row_mask:0xf bank_mask:0xf
	s_nop 0
	v_fmac_f32_dpp v21, v107, v57 row_shr:2 row_mask:0xf bank_mask:0xf
	s_nop 0
	v_fmac_f32_dpp v21, v13, v61 row_shl:15 row_mask:0xf bank_mask:0xf
	s_nop 0
	v_fmac_f32_dpp v21, v13, v57 row_shl:14 row_mask:0xf bank_mask:0xf
	s_nop 0
	s_nop 0
	s_nop 0
	s_nop 0
	s_nop 0
	s_nop 0
	s_nop 0
	v_pk_mul_f32 v[244:245], v[20:21], s[100:101]
	v_exp_f32_e32 v244, v244
	v_exp_f32_e32 v245, v245
	s_nop 0
	v_pk_add_f32 v[244:245], v[244:245], s[98:99]
	v_rcp_f32_e32 v28, v244
	v_rcp_f32_e32 v29, v245
	v_pk_mul_f32 v[244:245], v[18:19], s[100:101]
	v_exp_f32_e32 v244, v244
	v_exp_f32_e32 v245, v245
	s_nop 0
	v_pk_add_f32 v[244:245], v[244:245], s[98:99]
	v_rcp_f32_e32 v26, v244
	v_rcp_f32_e32 v27, v245
	v_pk_mul_f32 v[16:17], v[16:17], v[20:21]
	v_pk_mul_f32 v[14:15], v[14:15], v[18:19]
	v_pk_mul_f32 v[16:17], v[16:17], v[28:29]
	v_pk_mul_f32 v[14:15], v[14:15], v[26:27]
	v_pk_fma_f32 v[18:19], v[10:11], v[98:99], v[22:23]
	v_fmac_f32_dpp v18, v10, v58 row_shr:1 row_mask:0xf bank_mask:0xf
	s_nop 0
	v_fmac_f32_dpp v18, v10, v54 row_shr:2 row_mask:0xf bank_mask:0xf
	v_mov_b64_e32 v[22:23], s[66:67]
	v_fmac_f32_dpp v18, v74, v58 row_shl:15 row_mask:0xf bank_mask:0xf
	s_ashr_i32 s47, s46, 31
	v_fmac_f32_dpp v18, v74, v54 row_shl:14 row_mask:0xf bank_mask:0xf
	v_fmac_f32_dpp v19, v11, v59 row_shr:1 row_mask:0xf bank_mask:0xf
	s_andn2_b64 vcc, exec, s[4:5]
	v_fmac_f32_dpp v19, v11, v55 row_shr:2 row_mask:0xf bank_mask:0xf
	s_nop 0
	v_fmac_f32_dpp v19, v75, v59 row_shl:15 row_mask:0xf bank_mask:0xf
	s_nop 0
	v_fmac_f32_dpp v19, v75, v55 row_shl:14 row_mask:0xf bank_mask:0xf
	v_fmac_f32_dpp v24, v12, v60 row_shr:1 row_mask:0xf bank_mask:0xf
	s_mov_b64 s[4:5], -1
	v_fmac_f32_dpp v24, v12, v56 row_shr:2 row_mask:0xf bank_mask:0xf
	s_nop 0
	v_fmac_f32_dpp v24, v76, v60 row_shl:15 row_mask:0xf bank_mask:0xf
	s_nop 0
	v_fmac_f32_dpp v24, v76, v56 row_shl:14 row_mask:0xf bank_mask:0xf
	v_fmac_f32_dpp v25, v13, v61 row_shr:1 row_mask:0xf bank_mask:0xf
	s_nop 0
	v_fmac_f32_dpp v25, v13, v57 row_shr:2 row_mask:0xf bank_mask:0xf
	s_nop 0
	v_fmac_f32_dpp v25, v77, v61 row_shl:15 row_mask:0xf bank_mask:0xf
	s_nop 0
	v_fmac_f32_dpp v25, v77, v57 row_shl:14 row_mask:0xf bank_mask:0xf
	s_nop 0
	s_nop 0
	s_nop 0
	s_nop 0
	s_nop 0
	s_nop 0
	s_nop 0
	v_pk_mul_f32 v[244:245], v[24:25], s[100:101]
	v_exp_f32_e32 v244, v244
	v_exp_f32_e32 v245, v245
	s_nop 0
	v_pk_add_f32 v[244:245], v[244:245], s[98:99]
	v_rcp_f32_e32 v12, v244
	v_rcp_f32_e32 v13, v245
	v_pk_mul_f32 v[244:245], v[18:19], s[100:101]
	v_exp_f32_e32 v244, v244
	v_exp_f32_e32 v245, v245
	s_nop 0
	v_pk_add_f32 v[244:245], v[244:245], s[98:99]
	v_rcp_f32_e32 v10, v244
	v_rcp_f32_e32 v11, v245
	v_lshl_add_u32 v1, s28, 8, v185
	v_pk_mul_f32 v[20:21], v[72:73], v[24:25]
	v_mad_i64_i32 v[24:25], s[28:29], v1, s12, v[22:23]
	s_lshl_b64 s[28:29], s[46:47], 1
	v_pk_mul_f32 v[18:19], v[70:71], v[18:19]
	v_lshl_add_u64 v[24:25], v[24:25], 0, s[28:29]
	v_pk_mul_f32 v[12:13], v[20:21], v[12:13]
	v_pk_mul_f32 v[10:11], v[18:19], v[10:11]
	v_lshl_add_u64 v[24:25], v[24:25], 0, v[182:183]
	v_cvt_pk_bf16_f32 v18, v78, v79
	v_cvt_pk_bf16_f32 v19, v80, v81
	v_cvt_pk_bf16_f32 v20, v66, v67
	v_cvt_pk_bf16_f32 v21, v68, v69
	global_store_dwordx4 v[24:25], v[18:21], off
	v_or_b32_e32 v24, 16, v1
	v_mad_i64_i32 v[24:25], s[46:47], v24, s12, v[22:23]
	v_lshl_add_u64 v[24:25], v[24:25], 0, s[28:29]
	v_lshl_add_u64 v[24:25], v[24:25], 0, v[182:183]
	v_cvt_pk_bf16_f32 v18, v62, v63
	v_cvt_pk_bf16_f32 v19, v64, v65
	v_cvt_pk_bf16_f32 v20, v42, v43
	v_cvt_pk_bf16_f32 v21, v44, v45
	global_store_dwordx4 v[24:25], v[18:21], off
	v_or_b32_e32 v24, 32, v1
	v_mad_i64_i32 v[24:25], s[46:47], v24, s12, v[22:23]
	v_lshl_add_u64 v[24:25], v[24:25], 0, s[28:29]
	v_lshl_add_u64 v[24:25], v[24:25], 0, v[182:183]
	v_cvt_pk_bf16_f32 v18, v50, v51
	v_cvt_pk_bf16_f32 v19, v52, v53
	v_cvt_pk_bf16_f32 v20, v38, v39
	v_cvt_pk_bf16_f32 v21, v40, v41
	global_store_dwordx4 v[24:25], v[18:21], off
	v_or_b32_e32 v24, 48, v1
	v_mad_i64_i32 v[24:25], s[46:47], v24, s12, v[22:23]
	v_lshl_add_u64 v[24:25], v[24:25], 0, s[28:29]
	v_lshl_add_u64 v[24:25], v[24:25], 0, v[182:183]
	v_cvt_pk_bf16_f32 v18, v46, v47
	v_cvt_pk_bf16_f32 v19, v48, v49
	v_cvt_pk_bf16_f32 v20, v34, v35
	v_cvt_pk_bf16_f32 v21, v36, v37
	global_store_dwordx4 v[24:25], v[18:21], off
	v_add_u32_e32 v24, 0x80, v1
	s_nop 0
	v_cvt_pk_bf16_f32 v18, v102, v103
	v_cvt_pk_bf16_f32 v19, v104, v105
	v_cvt_pk_bf16_f32 v20, v10, v11
	v_mad_i64_i32 v[10:11], s[46:47], v24, s12, v[22:23]
	v_lshl_add_u64 v[10:11], v[10:11], 0, s[28:29]
	v_lshl_add_u64 v[10:11], v[10:11], 0, v[182:183]
	v_cvt_pk_bf16_f32 v21, v12, v13
	global_store_dwordx4 v[10:11], v[18:21], off
	v_cvt_pk_bf16_f32 v10, v94, v95
	v_cvt_pk_bf16_f32 v11, v96, v97
	v_cvt_pk_bf16_f32 v12, v14, v15
	v_add_u32_e32 v14, 0x90, v1
	v_mad_i64_i32 v[14:15], s[46:47], v14, s12, v[22:23]
	v_lshl_add_u64 v[14:15], v[14:15], 0, s[28:29]
	v_lshl_add_u64 v[14:15], v[14:15], 0, v[182:183]
	v_cvt_pk_bf16_f32 v13, v16, v17
	global_store_dwordx4 v[14:15], v[10:13], off
	s_nop 1
	v_cvt_pk_bf16_f32 v10, v90, v91
	v_cvt_pk_bf16_f32 v11, v92, v93
	v_cvt_pk_bf16_f32 v12, v6, v7
	v_add_u32_e32 v6, 0xa0, v1
	v_mad_i64_i32 v[6:7], s[46:47], v6, s12, v[22:23]
	v_lshl_add_u64 v[6:7], v[6:7], 0, s[28:29]
	v_lshl_add_u64 v[6:7], v[6:7], 0, v[182:183]
	v_add_u32_e32 v1, 0xb0, v1
	v_cvt_pk_bf16_f32 v13, v8, v9
	global_store_dwordx4 v[6:7], v[10:13], off
	v_cvt_pk_bf16_f32 v6, v86, v87
	v_cvt_pk_bf16_f32 v7, v88, v89
	v_cvt_pk_bf16_f32 v8, v2, v3
	v_mad_i64_i32 v[2:3], s[46:47], v1, s12, v[22:23]
	v_lshl_add_u64 v[2:3], v[2:3], 0, s[28:29]
	v_lshl_add_u64 v[2:3], v[2:3], 0, v[182:183]
	v_cvt_pk_bf16_f32 v9, v4, v5
	global_store_dwordx4 v[2:3], v[6:9], off
	s_cbranch_vccnz .LBB0_553
	s_andn2_b64 vcc, exec, s[16:17]
	s_mov_b32 s3, s40
	s_mov_b64 s[28:29], s[94:95]
	s_mov_b64 s[4:5], s[36:37]
	s_cbranch_vccnz .LBB0_590
	s_ashr_i32 s3, s40, 5
	s_mul_hi_i32 s4, s3, 0x5800
	s_mulk_i32 s3, 0x5800
	v_readlane_b32 s5, v255, 14
	s_add_u32 s28, s5, s3
	v_readlane_b32 s3, v255, 15
	s_addc_u32 s29, s3, s4
	s_mov_b32 s3, s38
	s_mov_b64 s[4:5], s[62:63]

.LBB0_1320:
	s_mov_b32 s98, 1.0
	s_mov_b32 s99, 1.0
	s_mov_b32 s100, 0xbfb8aa3b
	s_mov_b32 s101, 0xbfb8aa3b
	s_bitcmp1_b32 s31, 0
	s_cselect_b32 s8, 0x1800, 0
	s_add_i32 s8, s8, 0
	s_add_i32 s8, s8, 0x22100
	s_add_i32 s9, s8, s72
	v_lshl_add_u32 v30, v1, 2, s9
	v_add_u32_e32 v151, 0x1000, v30
	ds_read2_b32 v[146:147], v151 offset0:32 offset1:48
	v_lshl_add_u32 v223, v186, 2, s8
	ds_read_b128 v[118:121], v223 offset:5120
	ds_read_b128 v[30:33], v223 offset:5136
	s_waitcnt lgkmcnt(0)
	v_fmamk_f32 v54, v147, 0x3a800000, v222
	v_rsq_f32_e32 v150, v54
	ds_read_b128 v[122:125], v223 offset:5632
	ds_read_b128 v[54:57], v223 offset:5648
	ds_read2_b32 v[148:149], v151 offset1:16
	ds_read2_b32 v[204:205], v151 offset0:160 offset1:176
	ds_read2_b32 v[206:207], v151 offset0:128 offset1:144
	s_waitcnt lgkmcnt(0)
	v_pk_fma_f32 v[166:167], v[138:139], v[150:151], v[122:123] op_sel_hi:[1,0,1]
	v_pk_fma_f32 v[144:145], v[144:145], v[150:151], v[120:121] op_sel_hi:[1,0,1]
	v_pk_fma_f32 v[142:143], v[142:143], v[150:151], v[118:119] op_sel_hi:[1,0,1]
	v_fmamk_f32 v138, v205, 0x3a800000, v222
	v_rsq_f32_e32 v138, v138
	v_pk_fma_f32 v[84:85], v[84:85], v[150:151], v[32:33] op_sel_hi:[1,0,1]
	v_pk_fma_f32 v[82:83], v[82:83], v[150:151], v[30:31] op_sel_hi:[1,0,1]
	v_pk_fma_f32 v[168:169], v[140:141], v[150:151], v[124:125] op_sel_hi:[1,0,1]
	v_pk_fma_f32 v[116:117], v[116:117], v[138:139], v[120:121] op_sel_hi:[1,0,1]
	v_pk_fma_f32 v[114:115], v[114:115], v[138:139], v[118:119] op_sel_hi:[1,0,1]
	v_pk_fma_f32 v[28:29], v[28:29], v[138:139], v[32:33] op_sel_hi:[1,0,1]
	v_pk_fma_f32 v[26:27], v[26:27], v[138:139], v[30:31] op_sel_hi:[1,0,1]
	v_pk_fma_f32 v[128:129], v[128:129], v[138:139], v[124:125] op_sel_hi:[1,0,1]
	v_pk_fma_f32 v[126:127], v[126:127], v[138:139], v[122:123] op_sel_hi:[1,0,1]
	v_pk_fma_f32 v[60:61], v[60:61], v[138:139], v[56:57] op_sel_hi:[1,0,1]
	v_pk_fma_f32 v[58:59], v[58:59], v[138:139], v[54:55] op_sel_hi:[1,0,1]
	v_cndmask_b32_e64 v138, 0, 1, s[24:25]
	v_pk_fma_f32 v[100:101], v[100:101], v[150:151], v[56:57] op_sel_hi:[1,0,1]
	v_pk_fma_f32 v[98:99], v[98:99], v[150:151], v[54:55] op_sel_hi:[1,0,1]
	v_cmp_ne_u32_e64 s[8:9], 1, v138
	s_and_saveexec_b64 s[52:53], s[0:1]
	s_cbranch_execz .LBB0_1323
	v_add_u32_e32 v138, s77, v212
	ds_write_b128 v138, v[142:145]
	v_add_u32_e32 v138, s78, v212
	ds_write_b128 v138, v[82:85]
	v_add_u32_e32 v138, s79, v212
	ds_write_b128 v138, v[166:169]
	v_add_u32_e32 v138, s80, v212
	ds_write_b128 v138, v[98:101]
	v_add_u32_e32 v138, s77, v213
	ds_write_b128 v138, v[114:117]
	v_add_u32_e32 v138, s78, v213
	ds_write_b128 v138, v[26:29]
	v_add_u32_e32 v138, s79, v213
	ds_write_b128 v138, v[126:129]
	v_add_u32_e32 v138, s80, v213
	s_and_b64 vcc, exec, s[8:9]
	ds_write_b128 v138, v[58:61]
	s_cbranch_vccnz .LBB0_1323
	v_lshl_add_u32 v140, s30, 1, v214
	s_lshl_b32 s54, s50, 7
	v_mov_b64_e32 v[138:139], s[26:27]
	s_ashr_i32 s55, s54, 31
	v_mad_i64_i32 v[138:139], s[84:85], v140, s65, v[138:139]
	v_lshl_add_u64 v[138:139], s[54:55], 2, v[138:139]
	v_lshlrev_b32_e32 v140, 2, v186
	v_mov_b32_e32 v141, v185
	v_lshl_add_u64 v[138:139], v[138:139], 0, v[140:141]
	global_store_dwordx4 v[138:139], v[114:117], off
	global_store_dwordx4 v[138:139], v[26:29], off offset:16
	v_add_co_u32_e32 v138, vcc, 0x2000, v138
	s_nop 1
	v_addc_co_u32_e32 v139, vcc, 0, v139, vcc
	global_store_dwordx4 v[138:139], v[126:129], off offset:3072
	global_store_dwordx4 v[138:139], v[58:61], off offset:3088

.LBB0_1327:
	s_or_b64 exec, exec, s[52:53]
	s_nop 0
	ds_read_b128 v[150:153], v223
	ds_read_b128 v[154:157], v223 offset:1024
	ds_read_b128 v[162:165], v223 offset:2048
	ds_read_b128 v[134:137], v223 offset:3072
	v_mov_b32_e32 v158, 0
	v_mov_b32_e32 v159, 0
	v_mov_b32_e32 v160, 0
	v_mov_b32_e32 v161, 0
	s_and_saveexec_b64 s[52:53], s[36:37]
	v_add_u32_e32 v158, 0, v215
	v_add_u32_e32 v158, 0x20000, v158
	ds_read_b128 v[158:161], v158
	s_or_b64 exec, exec, s[52:53]
	v_mov_b32_e32 v197, v196
	v_mov_b32_e32 v201, v200
	v_pk_fma_f32 v[210:211], v[62:63], v[196:197], v[118:119] op_sel_hi:[1,0,1]
	s_nop 0
	s_nop 0
	v_pk_fma_f32 v[62:63], v[52:53], v[198:199], v[120:121] op_sel_hi:[1,0,1]
	v_pk_fma_f32 v[52:53], v[46:47], v[200:201], v[118:119] op_sel_hi:[1,0,1]
	s_waitcnt lgkmcnt(0)
	v_pk_fma_f32 v[46:47], v[142:143], v[162:163], v[134:135]
	s_nop 4
	v_fmac_f32_dpp v46, v142, v154 row_shr:1 row_mask:0xf bank_mask:0xf
	s_nop 0
	v_fmac_f32_dpp v46, v142, v150 row_shr:2 row_mask:0xf bank_mask:0xf
	v_mov_b32_e32 v199, v198
	v_fmac_f32_dpp v46, v52, v154 row_shl:15 row_mask:0xf bank_mask:0xf
	s_nop 0
	s_nop 0
	v_fmac_f32_dpp v46, v52, v150 row_shl:14 row_mask:0xf bank_mask:0xf
	v_fmac_f32_dpp v47, v143, v155 row_shr:1 row_mask:0xf bank_mask:0xf
	v_pk_fma_f32 v[208:209], v[64:65], v[196:197], v[120:121] op_sel_hi:[1,0,1]
	v_pk_fma_f32 v[64:65], v[50:51], v[198:199], v[118:119] op_sel_hi:[1,0,1]
	s_nop 0
	s_nop 0
	v_fmac_f32_dpp v47, v143, v151 row_shr:2 row_mask:0xf bank_mask:0xf
	v_pk_fma_f32 v[50:51], v[48:49], v[200:201], v[120:121] op_sel_hi:[1,0,1]
	v_fmac_f32_dpp v47, v53, v155 row_shl:15 row_mask:0xf bank_mask:0xf
	v_pk_fma_f32 v[48:49], v[144:145], v[164:165], v[136:137]
	v_fmac_f32_dpp v47, v53, v151 row_shl:14 row_mask:0xf bank_mask:0xf
	v_fmac_f32_dpp v48, v144, v156 row_shr:1 row_mask:0xf bank_mask:0xf
	s_nop 0
	v_fmac_f32_dpp v48, v144, v152 row_shr:2 row_mask:0xf bank_mask:0xf
	s_nop 0
	v_fmac_f32_dpp v48, v50, v156 row_shl:15 row_mask:0xf bank_mask:0xf
	s_nop 0
	v_fmac_f32_dpp v48, v50, v152 row_shl:14 row_mask:0xf bank_mask:0xf
	v_fmac_f32_dpp v49, v145, v157 row_shr:1 row_mask:0xf bank_mask:0xf
	s_nop 0
	v_fmac_f32_dpp v49, v145, v153 row_shr:2 row_mask:0xf bank_mask:0xf
	s_nop 0
	v_fmac_f32_dpp v49, v51, v157 row_shl:15 row_mask:0xf bank_mask:0xf
	s_nop 0
	v_fmac_f32_dpp v49, v51, v153 row_shl:14 row_mask:0xf bank_mask:0xf
	s_nop 0
	s_nop 0
	s_nop 0
	s_nop 0
	s_nop 0
	s_nop 0
	s_nop 0
	s_nop 0
	s_nop 0
	v_pk_mul_f32 v[244:245], v[48:49], s[100:101]
	v_exp_f32_e32 v244, v244
	v_exp_f32_e32 v245, v245
	s_nop 0
	v_pk_add_f32 v[244:245], v[244:245], s[98:99]
	v_rcp_f32_e32 v144, v244
	v_rcp_f32_e32 v145, v245
	v_pk_mul_f32 v[244:245], v[46:47], s[100:101]
	v_exp_f32_e32 v244, v244
	v_exp_f32_e32 v245, v245
	s_nop 0
	v_pk_add_f32 v[244:245], v[244:245], s[98:99]
	v_rcp_f32_e32 v142, v244
	v_rcp_f32_e32 v143, v245
	v_pk_mul_f32 v[48:49], v[148:149], v[48:49]
	v_pk_mul_f32 v[46:47], v[146:147], v[46:47]
	v_pk_mul_f32 v[48:49], v[48:49], v[144:145]
	v_pk_mul_f32 v[46:47], v[46:47], v[142:143]
	v_pk_fma_f32 v[142:143], v[52:53], v[162:163], v[134:135]
	v_fmac_f32_dpp v142, v52, v154 row_shr:1 row_mask:0xf bank_mask:0xf
	s_nop 0
	v_fmac_f32_dpp v142, v52, v150 row_shr:2 row_mask:0xf bank_mask:0xf
	s_nop 0
	v_fmac_f32_dpp v142, v64, v154 row_shl:15 row_mask:0xf bank_mask:0xf
	s_nop 0
	v_fmac_f32_dpp v142, v64, v150 row_shl:14 row_mask:0xf bank_mask:0xf
	v_fmac_f32_dpp v143, v53, v155 row_shr:1 row_mask:0xf bank_mask:0xf
	s_nop 0
	v_fmac_f32_dpp v143, v53, v151 row_shr:2 row_mask:0xf bank_mask:0xf
	v_pk_fma_f32 v[52:53], v[50:51], v[164:165], v[136:137]
	v_fmac_f32_dpp v143, v65, v155 row_shl:15 row_mask:0xf bank_mask:0xf
	s_nop 0
	v_fmac_f32_dpp v143, v65, v151 row_shl:14 row_mask:0xf bank_mask:0xf
	v_fmac_f32_dpp v52, v50, v156 row_shr:1 row_mask:0xf bank_mask:0xf
	s_nop 0
	v_fmac_f32_dpp v52, v50, v152 row_shr:2 row_mask:0xf bank_mask:0xf
	s_nop 0
	v_fmac_f32_dpp v52, v62, v156 row_shl:15 row_mask:0xf bank_mask:0xf
	s_nop 0
	v_fmac_f32_dpp v52, v62, v152 row_shl:14 row_mask:0xf bank_mask:0xf
	v_fmac_f32_dpp v53, v51, v157 row_shr:1 row_mask:0xf bank_mask:0xf
	v_pk_mul_f32 v[130:131], v[130:131], v[142:143]
	v_fmac_f32_dpp v53, v51, v153 row_shr:2 row_mask:0xf bank_mask:0xf
	s_nop 0
	v_fmac_f32_dpp v53, v63, v157 row_shl:15 row_mask:0xf bank_mask:0xf
	s_nop 0
	v_fmac_f32_dpp v53, v63, v153 row_shl:14 row_mask:0xf bank_mask:0xf
	s_nop 0
	s_nop 0
	s_nop 0
	s_nop 0
	s_nop 0
	s_nop 0
	s_nop 0
	s_nop 0
	s_nop 0
	s_nop 0
	v_pk_mul_f32 v[244:245], v[52:53], s[100:101]
	v_exp_f32_e32 v244, v244
	v_exp_f32_e32 v245, v245
	s_nop 0
	v_pk_add_f32 v[244:245], v[244:245], s[98:99]
	v_rcp_f32_e32 v144, v244
	v_rcp_f32_e32 v145, v245
	v_pk_mul_f32 v[244:245], v[142:143], s[100:101]
	v_exp_f32_e32 v244, v244
	v_exp_f32_e32 v245, v245
	s_nop 0
	v_pk_add_f32 v[244:245], v[244:245], s[98:99]
	v_rcp_f32_e32 v50, v244
	v_rcp_f32_e32 v51, v245
	v_pk_mul_f32 v[52:53], v[132:133], v[52:53]
	v_pk_mul_f32 v[50:51], v[130:131], v[50:51]
	v_pk_mul_f32 v[52:53], v[52:53], v[144:145]
	v_pk_fma_f32 v[130:131], v[64:65], v[162:163], v[134:135]
	v_fmac_f32_dpp v130, v64, v154 row_shr:1 row_mask:0xf bank_mask:0xf
	s_nop 0
	v_fmac_f32_dpp v130, v64, v150 row_shr:2 row_mask:0xf bank_mask:0xf
	s_nop 0
	v_fmac_f32_dpp v130, v210, v154 row_shl:15 row_mask:0xf bank_mask:0xf
	v_pk_fma_f32 v[134:135], v[210:211], v[162:163], v[134:135]
	v_fmac_f32_dpp v130, v210, v150 row_shl:14 row_mask:0xf bank_mask:0xf
	v_fmac_f32_dpp v131, v65, v155 row_shr:1 row_mask:0xf bank_mask:0xf
	s_nop 0
	v_fmac_f32_dpp v131, v65, v151 row_shr:2 row_mask:0xf bank_mask:0xf
	v_pk_fma_f32 v[64:65], v[62:63], v[164:165], v[136:137]
	v_fmac_f32_dpp v131, v211, v155 row_shl:15 row_mask:0xf bank_mask:0xf
	v_pk_fma_f32 v[136:137], v[208:209], v[164:165], v[136:137]
	v_fmac_f32_dpp v131, v211, v151 row_shl:14 row_mask:0xf bank_mask:0xf
	v_fmac_f32_dpp v64, v62, v156 row_shr:1 row_mask:0xf bank_mask:0xf
	s_nop 0
	v_fmac_f32_dpp v64, v62, v152 row_shr:2 row_mask:0xf bank_mask:0xf
	s_nop 0
	v_fmac_f32_dpp v64, v208, v156 row_shl:15 row_mask:0xf bank_mask:0xf
	s_nop 0
	v_fmac_f32_dpp v64, v208, v152 row_shl:14 row_mask:0xf bank_mask:0xf
	v_fmac_f32_dpp v65, v63, v157 row_shr:1 row_mask:0xf bank_mask:0xf
	v_pk_mul_f32 v[78:79], v[78:79], v[130:131]
	v_fmac_f32_dpp v65, v63, v153 row_shr:2 row_mask:0xf bank_mask:0xf
	s_nop 0
	v_fmac_f32_dpp v65, v209, v157 row_shl:15 row_mask:0xf bank_mask:0xf
	s_nop 0
	v_fmac_f32_dpp v65, v209, v153 row_shl:14 row_mask:0xf bank_mask:0xf
	s_nop 0
	s_nop 0
	s_nop 0
	s_nop 0
	s_nop 0
	s_nop 0
	s_nop 0
	s_nop 0
	s_nop 0
	s_nop 0
	v_pk_mul_f32 v[244:245], v[64:65], s[100:101]
	v_exp_f32_e32 v244, v244
	v_exp_f32_e32 v245, v245
	s_nop 0
	v_pk_add_f32 v[244:245], v[244:245], s[98:99]
	v_rcp_f32_e32 v132, v244
	v_rcp_f32_e32 v133, v245
	v_pk_mul_f32 v[244:245], v[130:131], s[100:101]
	v_exp_f32_e32 v244, v244
	v_exp_f32_e32 v245, v245
	s_nop 0
	v_pk_add_f32 v[244:245], v[244:245], s[98:99]
	v_rcp_f32_e32 v62, v244
	v_rcp_f32_e32 v63, v245
	v_pk_mul_f32 v[64:65], v[80:81], v[64:65]
	v_pk_mul_f32 v[62:63], v[78:79], v[62:63]
	v_pk_mul_f32 v[64:65], v[64:65], v[132:133]
	s_nop 0
	v_fmac_f32_dpp v134, v210, v154 row_shr:1 row_mask:0xf bank_mask:0xf
	s_nop 0
	v_fmac_f32_dpp v134, v210, v150 row_shr:2 row_mask:0xf bank_mask:0xf
	s_nop 0
	v_fmac_f32_dpp v134, v158, v154 row_shl:15 row_mask:0xf bank_mask:0xf
	s_nop 0
	v_fmac_f32_dpp v134, v158, v150 row_shl:14 row_mask:0xf bank_mask:0xf
	v_fmac_f32_dpp v135, v211, v155 row_shr:1 row_mask:0xf bank_mask:0xf
	s_nop 0
	v_fmac_f32_dpp v135, v211, v151 row_shr:2 row_mask:0xf bank_mask:0xf
	s_nop 0
	v_fmac_f32_dpp v135, v159, v155 row_shl:15 row_mask:0xf bank_mask:0xf
	s_nop 0
	v_fmac_f32_dpp v135, v159, v151 row_shl:14 row_mask:0xf bank_mask:0xf
	v_fmac_f32_dpp v136, v208, v156 row_shr:1 row_mask:0xf bank_mask:0xf
	s_nop 0
	v_fmac_f32_dpp v136, v208, v152 row_shr:2 row_mask:0xf bank_mask:0xf
	s_nop 0
	v_fmac_f32_dpp v136, v160, v156 row_shl:15 row_mask:0xf bank_mask:0xf
	s_nop 0
	v_fmac_f32_dpp v136, v160, v152 row_shl:14 row_mask:0xf bank_mask:0xf
	v_fmac_f32_dpp v137, v209, v157 row_shr:1 row_mask:0xf bank_mask:0xf
	s_nop 0
	v_fmac_f32_dpp v137, v209, v153 row_shr:2 row_mask:0xf bank_mask:0xf
	s_nop 0
	v_fmac_f32_dpp v137, v161, v157 row_shl:15 row_mask:0xf bank_mask:0xf
	s_nop 0
	v_fmac_f32_dpp v137, v161, v153 row_shl:14 row_mask:0xf bank_mask:0xf
	s_and_saveexec_b64 s[52:53], s[38:39]
	s_cbranch_execz .LBB0_1331
	global_store_dwordx4 v[166:167], v[134:137], off
.LBB0_1331:
	s_or_b64 exec, exec, s[52:53]
	s_nop 0
	s_nop 0
	s_nop 0
	s_nop 0
	s_nop 0
	s_nop 0
	s_nop 0
	s_nop 0
	s_nop 0
	s_nop 0
	s_nop 0
	s_nop 0
	s_nop 0
	s_nop 0
	v_pk_mul_f32 v[244:245], v[136:137], s[100:101]
	v_exp_f32_e32 v244, v244
	v_exp_f32_e32 v245, v245
	s_nop 0
	v_pk_add_f32 v[244:245], v[244:245], s[98:99]
	v_rcp_f32_e32 v80, v244
	v_rcp_f32_e32 v81, v245
	v_pk_mul_f32 v[244:245], v[134:135], s[100:101]
	v_exp_f32_e32 v244, v244
	v_exp_f32_e32 v245, v245
	s_nop 0
	v_pk_add_f32 v[244:245], v[244:245], s[98:99]
	v_rcp_f32_e32 v78, v244
	v_rcp_f32_e32 v79, v245
	v_pk_mul_f32 v[130:131], v[140:141], v[136:137]
	v_pk_mul_f32 v[132:133], v[138:139], v[134:135]
	v_pk_mul_f32 v[80:81], v[130:131], v[80:81]
	v_pk_mul_f32 v[78:79], v[132:133], v[78:79]
	v_mov_b32_e32 v134, 0
	ds_read_b128 v[142:145], v223 offset:512
	ds_read_b128 v[146:149], v223 offset:1536
	ds_read_b128 v[154:157], v223 offset:2560
	ds_read_b128 v[130:133], v223 offset:3584
	v_mov_b32_e32 v150, 0
	v_mov_b32_e32 v151, 0
	v_mov_b32_e32 v152, 0
	v_mov_b32_e32 v153, 0
	s_and_saveexec_b64 s[52:53], s[0:1]
	v_add_u32_e32 v135, s77, v216
	ds_read_b128 v[150:153], v135 offset:512
	s_or_b64 exec, exec, s[52:53]
	v_fmamk_f32 v136, v204, 0x3a800000, v222
	v_rsq_f32_e32 v160, v136
	s_waitcnt lgkmcnt(0)
	v_pk_fma_f32 v[138:139], v[126:127], v[154:155], v[130:131]
	s_nop 4
	v_fmac_f32_dpp v138, v126, v146 row_shr:1 row_mask:0xf bank_mask:0xf
	v_pk_fma_f32 v[102:103], v[102:103], v[160:161], v[122:123] op_sel_hi:[1,0,1]
	v_fmac_f32_dpp v138, v126, v142 row_shr:2 row_mask:0xf bank_mask:0xf
	s_nop 0
	v_fmac_f32_dpp v138, v102, v146 row_shl:15 row_mask:0xf bank_mask:0xf
	v_pk_fma_f32 v[140:141], v[128:129], v[156:157], v[132:133]
	v_fmac_f32_dpp v138, v102, v142 row_shl:14 row_mask:0xf bank_mask:0xf
	v_fmac_f32_dpp v139, v127, v147 row_shr:1 row_mask:0xf bank_mask:0xf
	v_fmamk_f32 v135, v206, 0x3a800000, v222
	v_fmac_f32_dpp v139, v127, v143 row_shr:2 row_mask:0xf bank_mask:0xf
	v_rsq_f32_e32 v158, v135
	v_fmac_f32_dpp v139, v103, v147 row_shl:15 row_mask:0xf bank_mask:0xf
	v_fmamk_f32 v135, v207, 0x3a800000, v222
	v_fmac_f32_dpp v139, v103, v143 row_shl:14 row_mask:0xf bank_mask:0xf
	v_fmac_f32_dpp v140, v128, v148 row_shr:1 row_mask:0xf bank_mask:0xf
	v_rsq_f32_e32 v162, v135
	v_fmac_f32_dpp v140, v128, v144 row_shr:2 row_mask:0xf bank_mask:0xf
	v_pk_fma_f32 v[104:105], v[104:105], v[160:161], v[124:125] op_sel_hi:[1,0,1]
	s_nop 0
	v_fmac_f32_dpp v140, v104, v148 row_shl:15 row_mask:0xf bank_mask:0xf
	v_pk_fma_f32 v[164:165], v[106:107], v[162:163], v[122:123] op_sel_hi:[1,0,1]
	v_fmac_f32_dpp v140, v104, v144 row_shl:14 row_mask:0xf bank_mask:0xf
	v_fmac_f32_dpp v141, v129, v149 row_shr:1 row_mask:0xf bank_mask:0xf
	v_pk_fma_f32 v[106:107], v[102:103], v[154:155], v[130:131]
	v_fmac_f32_dpp v141, v129, v145 row_shr:2 row_mask:0xf bank_mask:0xf
	s_nop 0
	v_fmac_f32_dpp v141, v105, v149 row_shl:15 row_mask:0xf bank_mask:0xf
	v_pk_fma_f32 v[136:137], v[108:109], v[162:163], v[124:125] op_sel_hi:[1,0,1]
	v_fmac_f32_dpp v141, v105, v145 row_shl:14 row_mask:0xf bank_mask:0xf
	v_pk_fma_f32 v[108:109], v[104:105], v[156:157], v[132:133]
	v_fmac_f32_dpp v106, v102, v146 row_shr:1 row_mask:0xf bank_mask:0xf
	s_nop 0
	v_fmac_f32_dpp v106, v102, v142 row_shr:2 row_mask:0xf bank_mask:0xf
	s_nop 0
	v_fmac_f32_dpp v106, v164, v146 row_shl:15 row_mask:0xf bank_mask:0xf
	v_pk_fma_f32 v[110:111], v[110:111], v[158:159], v[122:123] op_sel_hi:[1,0,1]
	v_fmac_f32_dpp v106, v164, v142 row_shl:14 row_mask:0xf bank_mask:0xf
	v_fmac_f32_dpp v107, v103, v147 row_shr:1 row_mask:0xf bank_mask:0xf
	v_pk_fma_f32 v[112:113], v[112:113], v[158:159], v[124:125] op_sel_hi:[1,0,1]
	v_fmac_f32_dpp v107, v103, v143 row_shr:2 row_mask:0xf bank_mask:0xf
	v_pk_fma_f32 v[102:103], v[164:165], v[154:155], v[130:131]
	v_fmac_f32_dpp v107, v165, v147 row_shl:15 row_mask:0xf bank_mask:0xf
	v_pk_fma_f32 v[130:131], v[110:111], v[154:155], v[130:131]
	v_fmac_f32_dpp v107, v165, v143 row_shl:14 row_mask:0xf bank_mask:0xf
	v_fmac_f32_dpp v108, v104, v148 row_shr:1 row_mask:0xf bank_mask:0xf
	s_nop 0
	v_fmac_f32_dpp v108, v104, v144 row_shr:2 row_mask:0xf bank_mask:0xf
	v_fma_f32 v104, v136, v156, v132
	v_fmac_f32_dpp v108, v136, v148 row_shl:15 row_mask:0xf bank_mask:0xf
	s_nop 0
	v_fmac_f32_dpp v108, v136, v144 row_shl:14 row_mask:0xf bank_mask:0xf
	v_fmac_f32_dpp v109, v105, v149 row_shr:1 row_mask:0xf bank_mask:0xf
	v_mov_b32_e32 v135, 0
	v_fmac_f32_dpp v109, v105, v145 row_shr:2 row_mask:0xf bank_mask:0xf
	v_fma_f32 v105, v137, v157, v133
	v_fmac_f32_dpp v109, v137, v149 row_shl:15 row_mask:0xf bank_mask:0xf
	v_pk_fma_f32 v[132:133], v[112:113], v[156:157], v[132:133]
	v_fmac_f32_dpp v109, v137, v145 row_shl:14 row_mask:0xf bank_mask:0xf
	s_nop 0
	v_fmac_f32_dpp v102, v164, v146 row_shr:1 row_mask:0xf bank_mask:0xf
	s_nop 0
	v_fmac_f32_dpp v102, v164, v142 row_shr:2 row_mask:0xf bank_mask:0xf
	s_nop 0
	v_fmac_f32_dpp v102, v110, v146 row_shl:15 row_mask:0xf bank_mask:0xf
	s_nop 0
	v_fmac_f32_dpp v102, v110, v142 row_shl:14 row_mask:0xf bank_mask:0xf
	v_fmac_f32_dpp v103, v165, v147 row_shr:1 row_mask:0xf bank_mask:0xf
	s_nop 0
	v_fmac_f32_dpp v103, v165, v143 row_shr:2 row_mask:0xf bank_mask:0xf
	s_nop 0
	v_fmac_f32_dpp v103, v111, v147 row_shl:15 row_mask:0xf bank_mask:0xf
	s_nop 0
	v_fmac_f32_dpp v103, v111, v143 row_shl:14 row_mask:0xf bank_mask:0xf
	v_fmac_f32_dpp v104, v136, v148 row_shr:1 row_mask:0xf bank_mask:0xf
	s_nop 0
	v_fmac_f32_dpp v104, v136, v144 row_shr:2 row_mask:0xf bank_mask:0xf
	v_mov_b32_e32 v136, 0
	v_fmac_f32_dpp v104, v112, v148 row_shl:15 row_mask:0xf bank_mask:0xf
	s_nop 0
	v_fmac_f32_dpp v104, v112, v144 row_shl:14 row_mask:0xf bank_mask:0xf
	v_fmac_f32_dpp v105, v137, v149 row_shr:1 row_mask:0xf bank_mask:0xf
	s_nop 0
	v_fmac_f32_dpp v105, v137, v145 row_shr:2 row_mask:0xf bank_mask:0xf
	v_mov_b32_e32 v137, 0
	v_fmac_f32_dpp v105, v113, v149 row_shl:15 row_mask:0xf bank_mask:0xf
	s_nop 0
	v_fmac_f32_dpp v105, v113, v145 row_shl:14 row_mask:0xf bank_mask:0xf
	s_nop 0
	v_fmac_f32_dpp v130, v110, v146 row_shr:1 row_mask:0xf bank_mask:0xf
	s_nop 0
	v_fmac_f32_dpp v130, v110, v142 row_shr:2 row_mask:0xf bank_mask:0xf
	s_nop 0
	v_fmac_f32_dpp v130, v150, v146 row_shl:15 row_mask:0xf bank_mask:0xf
	s_nop 0
	v_fmac_f32_dpp v130, v150, v142 row_shl:14 row_mask:0xf bank_mask:0xf
	v_fmac_f32_dpp v131, v111, v147 row_shr:1 row_mask:0xf bank_mask:0xf
	s_nop 0
	v_fmac_f32_dpp v131, v111, v143 row_shr:2 row_mask:0xf bank_mask:0xf
	s_nop 0
	v_fmac_f32_dpp v131, v151, v147 row_shl:15 row_mask:0xf bank_mask:0xf
	s_nop 0
	v_fmac_f32_dpp v131, v151, v143 row_shl:14 row_mask:0xf bank_mask:0xf
	v_fmac_f32_dpp v132, v112, v148 row_shr:1 row_mask:0xf bank_mask:0xf
	s_nop 0
	v_fmac_f32_dpp v132, v112, v144 row_shr:2 row_mask:0xf bank_mask:0xf
	s_nop 0
	v_fmac_f32_dpp v132, v152, v148 row_shl:15 row_mask:0xf bank_mask:0xf
	s_nop 0
	v_fmac_f32_dpp v132, v152, v144 row_shl:14 row_mask:0xf bank_mask:0xf
	v_fmac_f32_dpp v133, v113, v149 row_shr:1 row_mask:0xf bank_mask:0xf
	s_nop 0
	v_fmac_f32_dpp v133, v113, v145 row_shr:2 row_mask:0xf bank_mask:0xf
	s_nop 0
	v_fmac_f32_dpp v133, v153, v149 row_shl:15 row_mask:0xf bank_mask:0xf
	s_nop 0
	v_fmac_f32_dpp v133, v153, v145 row_shl:14 row_mask:0xf bank_mask:0xf
	s_nop 0
	ds_read_b128 v[122:125], v223
	ds_read_b128 v[126:129], v223 offset:1024
	ds_read_b128 v[142:145], v223 offset:2048
	ds_read_b128 v[110:113], v223 offset:3072
	s_and_saveexec_b64 s[52:53], s[0:1]
	v_add_u32_e32 v134, 0, v216
	v_add_u32_e32 v134, 0x20000, v134
	ds_read_b128 v[134:137], v134
	s_or_b64 exec, exec, s[52:53]
	v_mov_b32_e32 v159, v158
	v_mov_b32_e32 v161, v160
	v_pk_fma_f32 v[148:149], v[94:95], v[158:159], v[118:119] op_sel_hi:[1,0,1]
	s_nop 0
	s_nop 0
	v_pk_fma_f32 v[94:95], v[92:93], v[162:163], v[120:121] op_sel_hi:[1,0,1]
	v_pk_fma_f32 v[92:93], v[86:87], v[160:161], v[118:119] op_sel_hi:[1,0,1]
	s_waitcnt lgkmcnt(0)
	v_pk_fma_f32 v[86:87], v[114:115], v[142:143], v[110:111]
	s_nop 4
	v_fmac_f32_dpp v86, v114, v126 row_shr:1 row_mask:0xf bank_mask:0xf
	s_nop 0
	v_fmac_f32_dpp v86, v114, v122 row_shr:2 row_mask:0xf bank_mask:0xf
	v_mov_b32_e32 v163, v162
	v_fmac_f32_dpp v86, v92, v126 row_shl:15 row_mask:0xf bank_mask:0xf
	s_nop 0
	s_nop 0
	v_fmac_f32_dpp v86, v92, v122 row_shl:14 row_mask:0xf bank_mask:0xf
	v_fmac_f32_dpp v87, v115, v127 row_shr:1 row_mask:0xf bank_mask:0xf
	v_pk_fma_f32 v[146:147], v[96:97], v[158:159], v[120:121] op_sel_hi:[1,0,1]
	v_pk_fma_f32 v[96:97], v[90:91], v[162:163], v[118:119] op_sel_hi:[1,0,1]
	s_nop 0
	s_nop 0
	v_fmac_f32_dpp v87, v115, v123 row_shr:2 row_mask:0xf bank_mask:0xf
	v_pk_fma_f32 v[90:91], v[88:89], v[160:161], v[120:121] op_sel_hi:[1,0,1]
	v_fmac_f32_dpp v87, v93, v127 row_shl:15 row_mask:0xf bank_mask:0xf
	v_pk_fma_f32 v[88:89], v[116:117], v[144:145], v[112:113]
	v_fmac_f32_dpp v87, v93, v123 row_shl:14 row_mask:0xf bank_mask:0xf
	v_fmac_f32_dpp v88, v116, v128 row_shr:1 row_mask:0xf bank_mask:0xf
	s_nop 0
	v_fmac_f32_dpp v88, v116, v124 row_shr:2 row_mask:0xf bank_mask:0xf
	s_nop 0
	v_fmac_f32_dpp v88, v90, v128 row_shl:15 row_mask:0xf bank_mask:0xf
	s_nop 0
	v_fmac_f32_dpp v88, v90, v124 row_shl:14 row_mask:0xf bank_mask:0xf
	v_fmac_f32_dpp v89, v117, v129 row_shr:1 row_mask:0xf bank_mask:0xf
	s_nop 0
	v_fmac_f32_dpp v89, v117, v125 row_shr:2 row_mask:0xf bank_mask:0xf
	s_nop 0
	v_fmac_f32_dpp v89, v91, v129 row_shl:15 row_mask:0xf bank_mask:0xf
	s_nop 0
	v_fmac_f32_dpp v89, v91, v125 row_shl:14 row_mask:0xf bank_mask:0xf
	s_nop 0
	s_nop 0
	s_nop 0
	s_nop 0
	s_nop 0
	s_nop 0
	s_nop 0
	s_nop 0
	s_nop 0
	v_pk_mul_f32 v[244:245], v[88:89], s[100:101]
	v_exp_f32_e32 v244, v244
	v_exp_f32_e32 v245, v245
	s_nop 0
	v_pk_add_f32 v[244:245], v[244:245], s[98:99]
	v_rcp_f32_e32 v116, v244
	v_rcp_f32_e32 v117, v245
	v_pk_mul_f32 v[244:245], v[86:87], s[100:101]
	v_exp_f32_e32 v244, v244
	v_exp_f32_e32 v245, v245
	s_nop 0
	v_pk_add_f32 v[244:245], v[244:245], s[98:99]
	v_rcp_f32_e32 v114, v244
	v_rcp_f32_e32 v115, v245
	v_pk_mul_f32 v[88:89], v[140:141], v[88:89]
	v_pk_mul_f32 v[86:87], v[138:139], v[86:87]
	v_pk_mul_f32 v[88:89], v[88:89], v[116:117]
	v_pk_mul_f32 v[86:87], v[86:87], v[114:115]
	v_pk_fma_f32 v[114:115], v[92:93], v[142:143], v[110:111]
	v_fmac_f32_dpp v114, v92, v126 row_shr:1 row_mask:0xf bank_mask:0xf
	s_nop 0
	v_fmac_f32_dpp v114, v92, v122 row_shr:2 row_mask:0xf bank_mask:0xf
	s_nop 0
	v_fmac_f32_dpp v114, v96, v126 row_shl:15 row_mask:0xf bank_mask:0xf
	s_nop 0
	v_fmac_f32_dpp v114, v96, v122 row_shl:14 row_mask:0xf bank_mask:0xf
	v_fmac_f32_dpp v115, v93, v127 row_shr:1 row_mask:0xf bank_mask:0xf
	s_nop 0
	v_fmac_f32_dpp v115, v93, v123 row_shr:2 row_mask:0xf bank_mask:0xf
	v_pk_fma_f32 v[92:93], v[90:91], v[144:145], v[112:113]
	v_fmac_f32_dpp v115, v97, v127 row_shl:15 row_mask:0xf bank_mask:0xf
	s_nop 0
	v_fmac_f32_dpp v115, v97, v123 row_shl:14 row_mask:0xf bank_mask:0xf
	v_fmac_f32_dpp v92, v90, v128 row_shr:1 row_mask:0xf bank_mask:0xf
	s_nop 0
	v_fmac_f32_dpp v92, v90, v124 row_shr:2 row_mask:0xf bank_mask:0xf
	s_nop 0
	v_fmac_f32_dpp v92, v94, v128 row_shl:15 row_mask:0xf bank_mask:0xf
	s_nop 0
	v_fmac_f32_dpp v92, v94, v124 row_shl:14 row_mask:0xf bank_mask:0xf
	v_fmac_f32_dpp v93, v91, v129 row_shr:1 row_mask:0xf bank_mask:0xf
	v_pk_mul_f32 v[106:107], v[106:107], v[114:115]
	v_fmac_f32_dpp v93, v91, v125 row_shr:2 row_mask:0xf bank_mask:0xf
	s_nop 0
	v_fmac_f32_dpp v93, v95, v129 row_shl:15 row_mask:0xf bank_mask:0xf
	s_nop 0
	v_fmac_f32_dpp v93, v95, v125 row_shl:14 row_mask:0xf bank_mask:0xf
	s_nop 0
	s_nop 0
	s_nop 0
	s_nop 0
	s_nop 0
	s_nop 0
	s_nop 0
	s_nop 0
	s_nop 0
	s_nop 0
	v_pk_mul_f32 v[244:245], v[92:93], s[100:101]
	v_exp_f32_e32 v244, v244
	v_exp_f32_e32 v245, v245
	s_nop 0
	v_pk_add_f32 v[244:245], v[244:245], s[98:99]
	v_rcp_f32_e32 v116, v244
	v_rcp_f32_e32 v117, v245
	v_pk_mul_f32 v[244:245], v[114:115], s[100:101]
	v_exp_f32_e32 v244, v244
	v_exp_f32_e32 v245, v245
	s_nop 0
	v_pk_add_f32 v[244:245], v[244:245], s[98:99]
	v_rcp_f32_e32 v90, v244
	v_rcp_f32_e32 v91, v245
	v_pk_mul_f32 v[92:93], v[108:109], v[92:93]
	v_pk_mul_f32 v[90:91], v[106:107], v[90:91]
	v_pk_mul_f32 v[92:93], v[92:93], v[116:117]
	v_pk_fma_f32 v[106:107], v[96:97], v[142:143], v[110:111]
	v_fmac_f32_dpp v106, v96, v126 row_shr:1 row_mask:0xf bank_mask:0xf
	s_nop 0
	v_fmac_f32_dpp v106, v96, v122 row_shr:2 row_mask:0xf bank_mask:0xf
	v_fma_f32 v96, v94, v144, v112
	v_fmac_f32_dpp v106, v148, v126 row_shl:15 row_mask:0xf bank_mask:0xf
	s_nop 0
	v_fmac_f32_dpp v106, v148, v122 row_shl:14 row_mask:0xf bank_mask:0xf
	v_fmac_f32_dpp v107, v97, v127 row_shr:1 row_mask:0xf bank_mask:0xf
	s_nop 0
	v_fmac_f32_dpp v107, v97, v123 row_shr:2 row_mask:0xf bank_mask:0xf
	v_fma_f32 v97, v95, v145, v113
	v_fmac_f32_dpp v107, v149, v127 row_shl:15 row_mask:0xf bank_mask:0xf
	v_pk_fma_f32 v[112:113], v[146:147], v[144:145], v[112:113]
	v_fmac_f32_dpp v107, v149, v123 row_shl:14 row_mask:0xf bank_mask:0xf
	v_fmac_f32_dpp v96, v94, v128 row_shr:1 row_mask:0xf bank_mask:0xf
	s_nop 0
	v_fmac_f32_dpp v96, v94, v124 row_shr:2 row_mask:0xf bank_mask:0xf
	s_nop 0
	v_fmac_f32_dpp v96, v146, v128 row_shl:15 row_mask:0xf bank_mask:0xf
	s_nop 0
	v_fmac_f32_dpp v96, v146, v124 row_shl:14 row_mask:0xf bank_mask:0xf
	v_fmac_f32_dpp v97, v95, v129 row_shr:1 row_mask:0xf bank_mask:0xf
	v_pk_mul_f32 v[102:103], v[102:103], v[106:107]
	v_fmac_f32_dpp v97, v95, v125 row_shr:2 row_mask:0xf bank_mask:0xf
	s_nop 0
	v_fmac_f32_dpp v97, v147, v129 row_shl:15 row_mask:0xf bank_mask:0xf
	s_nop 0
	v_fmac_f32_dpp v97, v147, v125 row_shl:14 row_mask:0xf bank_mask:0xf
	s_nop 0
	s_nop 0
	s_nop 0
	s_nop 0
	s_nop 0
	s_nop 0
	s_nop 0
	s_nop 0
	s_nop 0
	s_nop 0
	v_pk_mul_f32 v[244:245], v[96:97], s[100:101]
	v_exp_f32_e32 v244, v244
	v_exp_f32_e32 v245, v245
	s_nop 0
	v_pk_add_f32 v[244:245], v[244:245], s[98:99]
	v_rcp_f32_e32 v108, v244
	v_rcp_f32_e32 v109, v245
	v_pk_mul_f32 v[244:245], v[106:107], s[100:101]
	v_exp_f32_e32 v244, v244
	v_exp_f32_e32 v245, v245
	s_nop 0
	v_pk_add_f32 v[244:245], v[244:245], s[98:99]
	v_rcp_f32_e32 v94, v244
	v_rcp_f32_e32 v95, v245
	v_pk_mul_f32 v[96:97], v[104:105], v[96:97]
	v_pk_mul_f32 v[94:95], v[102:103], v[94:95]
	v_pk_mul_f32 v[96:97], v[96:97], v[108:109]
	v_pk_fma_f32 v[102:103], v[148:149], v[142:143], v[110:111]
	v_fmac_f32_dpp v102, v148, v126 row_shr:1 row_mask:0xf bank_mask:0xf
	s_nop 0
	v_fmac_f32_dpp v102, v148, v122 row_shr:2 row_mask:0xf bank_mask:0xf
	s_nop 0
	v_fmac_f32_dpp v102, v134, v126 row_shl:15 row_mask:0xf bank_mask:0xf
	s_nop 0
	v_fmac_f32_dpp v102, v134, v122 row_shl:14 row_mask:0xf bank_mask:0xf
	v_fmac_f32_dpp v103, v149, v127 row_shr:1 row_mask:0xf bank_mask:0xf
	v_mov_b32_e32 v122, 0
	v_fmac_f32_dpp v103, v149, v123 row_shr:2 row_mask:0xf bank_mask:0xf
	s_nop 0
	v_fmac_f32_dpp v103, v135, v127 row_shl:15 row_mask:0xf bank_mask:0xf
	s_nop 0
	v_fmac_f32_dpp v103, v135, v123 row_shl:14 row_mask:0xf bank_mask:0xf
	v_fmac_f32_dpp v112, v146, v128 row_shr:1 row_mask:0xf bank_mask:0xf
	v_mov_b32_e32 v123, 0
	v_fmac_f32_dpp v112, v146, v124 row_shr:2 row_mask:0xf bank_mask:0xf
	s_nop 0
	v_fmac_f32_dpp v112, v136, v128 row_shl:15 row_mask:0xf bank_mask:0xf
	s_nop 0
	v_fmac_f32_dpp v112, v136, v124 row_shl:14 row_mask:0xf bank_mask:0xf
	v_fmac_f32_dpp v113, v147, v129 row_shr:1 row_mask:0xf bank_mask:0xf
	s_nop 0
	v_fmac_f32_dpp v113, v147, v125 row_shr:2 row_mask:0xf bank_mask:0xf
	s_nop 0
	v_fmac_f32_dpp v113, v137, v129 row_shl:15 row_mask:0xf bank_mask:0xf
	s_nop 0
	v_fmac_f32_dpp v113, v137, v125 row_shl:14 row_mask:0xf bank_mask:0xf
	s_nop 0
	s_nop 0
	s_nop 0
	s_nop 0
	s_nop 0
	s_nop 0
	s_nop 0
	v_pk_mul_f32 v[244:245], v[112:113], s[100:101]
	v_exp_f32_e32 v244, v244
	v_exp_f32_e32 v245, v245
	s_nop 0
	v_pk_add_f32 v[244:245], v[244:245], s[98:99]
	v_rcp_f32_e32 v104, v244
	v_rcp_f32_e32 v105, v245
	v_pk_mul_f32 v[244:245], v[102:103], s[100:101]
	v_exp_f32_e32 v244, v244
	v_exp_f32_e32 v245, v245
	s_nop 0
	v_pk_add_f32 v[244:245], v[244:245], s[98:99]
	v_rcp_f32_e32 v106, v244
	v_rcp_f32_e32 v107, v245
	v_pk_mul_f32 v[108:109], v[132:133], v[112:113]
	v_pk_mul_f32 v[102:103], v[130:131], v[102:103]
	v_pk_mul_f32 v[104:105], v[108:109], v[104:105]
	v_pk_mul_f32 v[102:103], v[102:103], v[106:107]
	v_mov_b32_e32 v124, 0
	ds_read_b128 v[114:117], v223 offset:528
	ds_read_b128 v[118:121], v223 offset:1552
	ds_read_b128 v[126:129], v223 offset:2576
	ds_read_b128 v[106:109], v223 offset:3600
	v_mov_b32_e32 v125, 0
	s_and_saveexec_b64 s[52:53], s[36:37]
	v_add_u32_e32 v110, s77, v217
	ds_read_b128 v[122:125], v110 offset:512
	s_or_b64 exec, exec, s[52:53]
	s_nop 0
	s_nop 0
	v_pk_fma_f32 v[76:77], v[76:77], v[196:197], v[56:57] op_sel_hi:[1,0,1]
	s_nop 0
	s_nop 0
	v_pk_fma_f32 v[130:131], v[72:73], v[198:199], v[56:57] op_sel_hi:[1,0,1]
	s_waitcnt lgkmcnt(0)
	v_pk_fma_f32 v[110:111], v[98:99], v[126:127], v[106:107]
	s_nop 4
	v_fmac_f32_dpp v110, v98, v118 row_shr:1 row_mask:0xf bank_mask:0xf
	v_pk_fma_f32 v[66:67], v[66:67], v[200:201], v[54:55]
	v_fmac_f32_dpp v110, v98, v114 row_shr:2 row_mask:0xf bank_mask:0xf
	s_nop 0
	v_fmac_f32_dpp v110, v66, v118 row_shl:15 row_mask:0xf bank_mask:0xf
	v_pk_fma_f32 v[112:113], v[100:101], v[128:129], v[108:109]
	v_fmac_f32_dpp v110, v66, v114 row_shl:14 row_mask:0xf bank_mask:0xf
	v_fmac_f32_dpp v111, v99, v119 row_shr:1 row_mask:0xf bank_mask:0xf
	v_pk_fma_f32 v[132:133], v[70:71], v[198:199], v[54:55]
	v_fmac_f32_dpp v111, v99, v115 row_shr:2 row_mask:0xf bank_mask:0xf
	s_nop 0
	v_fmac_f32_dpp v111, v67, v119 row_shl:15 row_mask:0xf bank_mask:0xf
	s_nop 0
	v_fmac_f32_dpp v111, v67, v115 row_shl:14 row_mask:0xf bank_mask:0xf
	v_fmac_f32_dpp v112, v100, v120 row_shr:1 row_mask:0xf bank_mask:0xf
	v_pk_fma_f32 v[68:69], v[68:69], v[200:201], v[56:57] op_sel_hi:[1,0,1]
	v_fmac_f32_dpp v112, v100, v116 row_shr:2 row_mask:0xf bank_mask:0xf
	s_nop 0
	v_fmac_f32_dpp v112, v68, v120 row_shl:15 row_mask:0xf bank_mask:0xf
	v_pk_fma_f32 v[70:71], v[66:67], v[126:127], v[106:107]
	v_fmac_f32_dpp v112, v68, v116 row_shl:14 row_mask:0xf bank_mask:0xf
	v_fmac_f32_dpp v113, v101, v121 row_shr:1 row_mask:0xf bank_mask:0xf
	s_nop 0
	v_fmac_f32_dpp v113, v101, v117 row_shr:2 row_mask:0xf bank_mask:0xf
	v_pk_fma_f32 v[72:73], v[68:69], v[128:129], v[108:109]
	v_fmac_f32_dpp v113, v69, v121 row_shl:15 row_mask:0xf bank_mask:0xf
	s_nop 0
	v_fmac_f32_dpp v113, v69, v117 row_shl:14 row_mask:0xf bank_mask:0xf
	v_pk_fma_f32 v[74:75], v[74:75], v[196:197], v[54:55]
	v_fmac_f32_dpp v70, v66, v118 row_shr:1 row_mask:0xf bank_mask:0xf
	s_nop 0
	v_fmac_f32_dpp v70, v66, v114 row_shr:2 row_mask:0xf bank_mask:0xf
	v_fma_f32 v66, v132, v126, v106
	v_fmac_f32_dpp v70, v132, v118 row_shl:15 row_mask:0xf bank_mask:0xf
	s_nop 0
	v_fmac_f32_dpp v70, v132, v114 row_shl:14 row_mask:0xf bank_mask:0xf
	v_fmac_f32_dpp v71, v67, v119 row_shr:1 row_mask:0xf bank_mask:0xf
	s_nop 0
	v_fmac_f32_dpp v71, v67, v115 row_shr:2 row_mask:0xf bank_mask:0xf
	v_fma_f32 v67, v133, v127, v107
	v_fmac_f32_dpp v71, v133, v119 row_shl:15 row_mask:0xf bank_mask:0xf
	v_pk_fma_f32 v[106:107], v[74:75], v[126:127], v[106:107]
	v_fmac_f32_dpp v71, v133, v115 row_shl:14 row_mask:0xf bank_mask:0xf
	v_fmac_f32_dpp v72, v68, v120 row_shr:1 row_mask:0xf bank_mask:0xf
	s_nop 0
	v_fmac_f32_dpp v72, v68, v116 row_shr:2 row_mask:0xf bank_mask:0xf
	v_fma_f32 v68, v130, v128, v108
	v_fmac_f32_dpp v72, v130, v120 row_shl:15 row_mask:0xf bank_mask:0xf
	s_nop 0
	v_fmac_f32_dpp v72, v130, v116 row_shl:14 row_mask:0xf bank_mask:0xf
	v_fmac_f32_dpp v73, v69, v121 row_shr:1 row_mask:0xf bank_mask:0xf
	s_nop 0
	v_fmac_f32_dpp v73, v69, v117 row_shr:2 row_mask:0xf bank_mask:0xf
	v_fma_f32 v69, v131, v129, v109
	v_fmac_f32_dpp v73, v131, v121 row_shl:15 row_mask:0xf bank_mask:0xf
	v_pk_fma_f32 v[108:109], v[76:77], v[128:129], v[108:109]
	v_fmac_f32_dpp v73, v131, v117 row_shl:14 row_mask:0xf bank_mask:0xf
	s_nop 0
	v_fmac_f32_dpp v66, v132, v118 row_shr:1 row_mask:0xf bank_mask:0xf
	s_nop 0
	v_fmac_f32_dpp v66, v132, v114 row_shr:2 row_mask:0xf bank_mask:0xf
	s_nop 0
	v_fmac_f32_dpp v66, v74, v118 row_shl:15 row_mask:0xf bank_mask:0xf
	s_nop 0
	v_fmac_f32_dpp v66, v74, v114 row_shl:14 row_mask:0xf bank_mask:0xf
	v_fmac_f32_dpp v67, v133, v119 row_shr:1 row_mask:0xf bank_mask:0xf
	s_nop 0
	v_fmac_f32_dpp v67, v133, v115 row_shr:2 row_mask:0xf bank_mask:0xf
	s_nop 0
	v_fmac_f32_dpp v67, v75, v119 row_shl:15 row_mask:0xf bank_mask:0xf
	s_nop 0
	v_fmac_f32_dpp v67, v75, v115 row_shl:14 row_mask:0xf bank_mask:0xf
	v_fmac_f32_dpp v68, v130, v120 row_shr:1 row_mask:0xf bank_mask:0xf
	s_nop 0
	v_fmac_f32_dpp v68, v130, v116 row_shr:2 row_mask:0xf bank_mask:0xf
	s_nop 0
	v_fmac_f32_dpp v68, v76, v120 row_shl:15 row_mask:0xf bank_mask:0xf
	s_nop 0
	v_fmac_f32_dpp v68, v76, v116 row_shl:14 row_mask:0xf bank_mask:0xf
	v_fmac_f32_dpp v69, v131, v121 row_shr:1 row_mask:0xf bank_mask:0xf
	s_nop 0
	v_fmac_f32_dpp v69, v131, v117 row_shr:2 row_mask:0xf bank_mask:0xf
	s_nop 0
	v_fmac_f32_dpp v69, v77, v121 row_shl:15 row_mask:0xf bank_mask:0xf
	s_nop 0
	v_fmac_f32_dpp v69, v77, v117 row_shl:14 row_mask:0xf bank_mask:0xf
	s_nop 0
	v_fmac_f32_dpp v106, v74, v118 row_shr:1 row_mask:0xf bank_mask:0xf
	s_nop 0
	v_fmac_f32_dpp v106, v74, v114 row_shr:2 row_mask:0xf bank_mask:0xf
	s_nop 0
	v_fmac_f32_dpp v106, v122, v118 row_shl:15 row_mask:0xf bank_mask:0xf
	s_nop 0
	v_fmac_f32_dpp v106, v122, v114 row_shl:14 row_mask:0xf bank_mask:0xf
	v_fmac_f32_dpp v107, v75, v119 row_shr:1 row_mask:0xf bank_mask:0xf
	s_nop 0
	v_fmac_f32_dpp v107, v75, v115 row_shr:2 row_mask:0xf bank_mask:0xf
	s_nop 0
	v_fmac_f32_dpp v107, v123, v119 row_shl:15 row_mask:0xf bank_mask:0xf
	s_nop 0
	v_fmac_f32_dpp v107, v123, v115 row_shl:14 row_mask:0xf bank_mask:0xf
	v_fmac_f32_dpp v108, v76, v120 row_shr:1 row_mask:0xf bank_mask:0xf
	s_nop 0
	v_fmac_f32_dpp v108, v76, v116 row_shr:2 row_mask:0xf bank_mask:0xf
	s_nop 0
	v_fmac_f32_dpp v108, v124, v120 row_shl:15 row_mask:0xf bank_mask:0xf
	s_nop 0
	v_fmac_f32_dpp v108, v124, v116 row_shl:14 row_mask:0xf bank_mask:0xf
	v_fmac_f32_dpp v109, v77, v121 row_shr:1 row_mask:0xf bank_mask:0xf
	s_nop 0
	v_fmac_f32_dpp v109, v77, v117 row_shr:2 row_mask:0xf bank_mask:0xf
	s_nop 0
	v_fmac_f32_dpp v109, v125, v121 row_shl:15 row_mask:0xf bank_mask:0xf
	s_nop 0
	v_fmac_f32_dpp v109, v125, v117 row_shl:14 row_mask:0xf bank_mask:0xf
	s_and_saveexec_b64 s[52:53], s[38:39]
	s_cbranch_execz .LBB0_1339
	v_or_b32_e32 v74, 4, v202
	v_ashrrev_i32_e32 v75, 31, v74
	v_lshl_add_u64 v[74:75], v[74:75], 2, v[168:169]
	v_add_co_u32_e32 v74, vcc, 0x2000, v74
	s_nop 1
	v_addc_co_u32_e32 v75, vcc, 0, v75, vcc
	global_store_dwordx4 v[74:75], v[106:109], off offset:3072
.LBB0_1339:
	s_or_b64 exec, exec, s[52:53]
	s_nop 0
	ds_read_b128 v[98:101], v223 offset:16
	ds_read_b128 v[114:117], v223 offset:1040
	ds_read_b128 v[122:125], v223 offset:2064
	ds_read_b128 v[74:77], v223 offset:3088
	v_mov_b32_e32 v118, 0
	v_mov_b32_e32 v119, 0
	v_mov_b32_e32 v120, 0
	v_mov_b32_e32 v121, 0
	s_and_saveexec_b64 s[52:53], s[36:37]
	v_add_u32_e32 v118, 0, v217
	v_add_u32_e32 v118, 0x20000, v118
	ds_read_b128 v[118:121], v118
	s_or_b64 exec, exec, s[52:53]
	v_pk_fma_f32 v[128:129], v[42:43], v[196:197], v[30:31]
	s_nop 0
	s_nop 0
	v_pk_fma_f32 v[42:43], v[40:41], v[198:199], v[32:33] op_sel_hi:[1,0,1]
	v_pk_fma_f32 v[40:41], v[34:35], v[200:201], v[30:31]
	s_waitcnt lgkmcnt(0)
	v_pk_fma_f32 v[34:35], v[82:83], v[122:123], v[74:75]
	s_nop 4
	v_fmac_f32_dpp v34, v82, v114 row_shr:1 row_mask:0xf bank_mask:0xf
	s_nop 0
	v_fmac_f32_dpp v34, v82, v98 row_shr:2 row_mask:0xf bank_mask:0xf
	s_nop 0
	v_fmac_f32_dpp v34, v40, v114 row_shl:15 row_mask:0xf bank_mask:0xf
	s_nop 0
	v_fmac_f32_dpp v34, v40, v98 row_shl:14 row_mask:0xf bank_mask:0xf
	v_fmac_f32_dpp v35, v83, v115 row_shr:1 row_mask:0xf bank_mask:0xf
	v_pk_fma_f32 v[126:127], v[44:45], v[196:197], v[32:33] op_sel_hi:[1,0,1]
	v_pk_fma_f32 v[44:45], v[38:39], v[198:199], v[30:31]
	s_nop 0
	s_nop 0
	v_fmac_f32_dpp v35, v83, v99 row_shr:2 row_mask:0xf bank_mask:0xf
	v_pk_fma_f32 v[38:39], v[36:37], v[200:201], v[32:33] op_sel_hi:[1,0,1]
	v_fmac_f32_dpp v35, v41, v115 row_shl:15 row_mask:0xf bank_mask:0xf
	v_pk_fma_f32 v[36:37], v[84:85], v[124:125], v[76:77]
	v_fmac_f32_dpp v35, v41, v99 row_shl:14 row_mask:0xf bank_mask:0xf
	v_fmac_f32_dpp v36, v84, v116 row_shr:1 row_mask:0xf bank_mask:0xf
	s_nop 0
	v_fmac_f32_dpp v36, v84, v100 row_shr:2 row_mask:0xf bank_mask:0xf
	s_nop 0
	v_fmac_f32_dpp v36, v38, v116 row_shl:15 row_mask:0xf bank_mask:0xf
	s_nop 0
	v_fmac_f32_dpp v36, v38, v100 row_shl:14 row_mask:0xf bank_mask:0xf
	v_fmac_f32_dpp v37, v85, v117 row_shr:1 row_mask:0xf bank_mask:0xf
	s_nop 0
	v_fmac_f32_dpp v37, v85, v101 row_shr:2 row_mask:0xf bank_mask:0xf
	s_nop 0
	v_fmac_f32_dpp v37, v39, v117 row_shl:15 row_mask:0xf bank_mask:0xf
	s_nop 0
	v_fmac_f32_dpp v37, v39, v101 row_shl:14 row_mask:0xf bank_mask:0xf
	s_nop 0
	s_nop 0
	s_nop 0
	s_nop 0
	s_nop 0
	s_nop 0
	s_nop 0
	s_nop 0
	s_nop 0
	v_pk_mul_f32 v[244:245], v[36:37], s[100:101]
	v_exp_f32_e32 v244, v244
	v_exp_f32_e32 v245, v245
	s_nop 0
	v_pk_add_f32 v[244:245], v[244:245], s[98:99]
	v_rcp_f32_e32 v84, v244
	v_rcp_f32_e32 v85, v245
	v_pk_mul_f32 v[244:245], v[34:35], s[100:101]
	v_exp_f32_e32 v244, v244
	v_exp_f32_e32 v245, v245
	s_nop 0
	v_pk_add_f32 v[244:245], v[244:245], s[98:99]
	v_rcp_f32_e32 v82, v244
	v_rcp_f32_e32 v83, v245
	v_pk_mul_f32 v[36:37], v[112:113], v[36:37]
	v_pk_mul_f32 v[34:35], v[110:111], v[34:35]
	v_pk_mul_f32 v[36:37], v[36:37], v[84:85]
	v_pk_mul_f32 v[34:35], v[34:35], v[82:83]
	v_pk_fma_f32 v[82:83], v[40:41], v[122:123], v[74:75]
	v_fmac_f32_dpp v82, v40, v114 row_shr:1 row_mask:0xf bank_mask:0xf
	s_nop 0
	v_fmac_f32_dpp v82, v40, v98 row_shr:2 row_mask:0xf bank_mask:0xf
	s_nop 0
	v_fmac_f32_dpp v82, v44, v114 row_shl:15 row_mask:0xf bank_mask:0xf
	s_nop 0
	v_fmac_f32_dpp v82, v44, v98 row_shl:14 row_mask:0xf bank_mask:0xf
	v_fmac_f32_dpp v83, v41, v115 row_shr:1 row_mask:0xf bank_mask:0xf
	s_nop 0
	v_fmac_f32_dpp v83, v41, v99 row_shr:2 row_mask:0xf bank_mask:0xf
	v_pk_fma_f32 v[40:41], v[38:39], v[124:125], v[76:77]
	v_fmac_f32_dpp v83, v45, v115 row_shl:15 row_mask:0xf bank_mask:0xf
	s_nop 0
	v_fmac_f32_dpp v83, v45, v99 row_shl:14 row_mask:0xf bank_mask:0xf
	v_fmac_f32_dpp v40, v38, v116 row_shr:1 row_mask:0xf bank_mask:0xf
	s_nop 0
	v_fmac_f32_dpp v40, v38, v100 row_shr:2 row_mask:0xf bank_mask:0xf
	s_nop 0
	v_fmac_f32_dpp v40, v42, v116 row_shl:15 row_mask:0xf bank_mask:0xf
	s_nop 0
	v_fmac_f32_dpp v40, v42, v100 row_shl:14 row_mask:0xf bank_mask:0xf
	v_fmac_f32_dpp v41, v39, v117 row_shr:1 row_mask:0xf bank_mask:0xf
	v_pk_mul_f32 v[70:71], v[70:71], v[82:83]
	v_fmac_f32_dpp v41, v39, v101 row_shr:2 row_mask:0xf bank_mask:0xf
	s_nop 0
	v_fmac_f32_dpp v41, v43, v117 row_shl:15 row_mask:0xf bank_mask:0xf
	s_nop 0
	v_fmac_f32_dpp v41, v43, v101 row_shl:14 row_mask:0xf bank_mask:0xf
	s_nop 0
	s_nop 0
	s_nop 0
	s_nop 0
	s_nop 0
	s_nop 0
	s_nop 0
	s_nop 0
	s_nop 0
	s_nop 0
	v_pk_mul_f32 v[244:245], v[40:41], s[100:101]
	v_exp_f32_e32 v244, v244
	v_exp_f32_e32 v245, v245
	s_nop 0
	v_pk_add_f32 v[244:245], v[244:245], s[98:99]
	v_rcp_f32_e32 v84, v244
	v_rcp_f32_e32 v85, v245
	v_pk_mul_f32 v[244:245], v[82:83], s[100:101]
	v_exp_f32_e32 v244, v244
	v_exp_f32_e32 v245, v245
	s_nop 0
	v_pk_add_f32 v[244:245], v[244:245], s[98:99]
	v_rcp_f32_e32 v38, v244
	v_rcp_f32_e32 v39, v245
	v_pk_mul_f32 v[40:41], v[72:73], v[40:41]
	v_pk_mul_f32 v[38:39], v[70:71], v[38:39]
	v_pk_mul_f32 v[40:41], v[40:41], v[84:85]
	v_pk_fma_f32 v[70:71], v[44:45], v[122:123], v[74:75]
	v_fmac_f32_dpp v70, v44, v114 row_shr:1 row_mask:0xf bank_mask:0xf
	s_nop 0
	v_fmac_f32_dpp v70, v44, v98 row_shr:2 row_mask:0xf bank_mask:0xf
	s_nop 0
	v_fmac_f32_dpp v70, v128, v114 row_shl:15 row_mask:0xf bank_mask:0xf
	v_pk_fma_f32 v[74:75], v[128:129], v[122:123], v[74:75]
	v_fmac_f32_dpp v70, v128, v98 row_shl:14 row_mask:0xf bank_mask:0xf
	v_fmac_f32_dpp v71, v45, v115 row_shr:1 row_mask:0xf bank_mask:0xf
	s_nop 0
	v_fmac_f32_dpp v71, v45, v99 row_shr:2 row_mask:0xf bank_mask:0xf
	v_pk_fma_f32 v[44:45], v[42:43], v[124:125], v[76:77]
	v_fmac_f32_dpp v71, v129, v115 row_shl:15 row_mask:0xf bank_mask:0xf
	v_pk_fma_f32 v[76:77], v[126:127], v[124:125], v[76:77]
	v_fmac_f32_dpp v71, v129, v99 row_shl:14 row_mask:0xf bank_mask:0xf
	v_fmac_f32_dpp v44, v42, v116 row_shr:1 row_mask:0xf bank_mask:0xf
	s_nop 0
	v_fmac_f32_dpp v44, v42, v100 row_shr:2 row_mask:0xf bank_mask:0xf
	s_nop 0
	v_fmac_f32_dpp v44, v126, v116 row_shl:15 row_mask:0xf bank_mask:0xf
	s_nop 0
	v_fmac_f32_dpp v44, v126, v100 row_shl:14 row_mask:0xf bank_mask:0xf
	v_fmac_f32_dpp v45, v43, v117 row_shr:1 row_mask:0xf bank_mask:0xf
	v_pk_mul_f32 v[66:67], v[66:67], v[70:71]
	v_fmac_f32_dpp v45, v43, v101 row_shr:2 row_mask:0xf bank_mask:0xf
	s_nop 0
	v_fmac_f32_dpp v45, v127, v117 row_shl:15 row_mask:0xf bank_mask:0xf
	s_nop 0
	v_fmac_f32_dpp v45, v127, v101 row_shl:14 row_mask:0xf bank_mask:0xf
	s_nop 0
	s_nop 0
	s_nop 0
	s_nop 0
	s_nop 0
	s_nop 0
	s_nop 0
	s_nop 0
	s_nop 0
	s_nop 0
	v_pk_mul_f32 v[244:245], v[44:45], s[100:101]
	v_exp_f32_e32 v244, v244
	v_exp_f32_e32 v245, v245
	s_nop 0
	v_pk_add_f32 v[244:245], v[244:245], s[98:99]
	v_rcp_f32_e32 v72, v244
	v_rcp_f32_e32 v73, v245
	v_pk_mul_f32 v[244:245], v[70:71], s[100:101]
	v_exp_f32_e32 v244, v244
	v_exp_f32_e32 v245, v245
	s_nop 0
	v_pk_add_f32 v[244:245], v[244:245], s[98:99]
	v_rcp_f32_e32 v42, v244
	v_rcp_f32_e32 v43, v245
	v_pk_mul_f32 v[44:45], v[68:69], v[44:45]
	v_pk_mul_f32 v[42:43], v[66:67], v[42:43]
	v_pk_mul_f32 v[44:45], v[44:45], v[72:73]
	s_nop 0
	v_fmac_f32_dpp v74, v128, v114 row_shr:1 row_mask:0xf bank_mask:0xf
	s_nop 0
	v_fmac_f32_dpp v74, v128, v98 row_shr:2 row_mask:0xf bank_mask:0xf
	s_nop 0
	v_fmac_f32_dpp v74, v118, v114 row_shl:15 row_mask:0xf bank_mask:0xf
	s_nop 0
	v_fmac_f32_dpp v74, v118, v98 row_shl:14 row_mask:0xf bank_mask:0xf
	v_fmac_f32_dpp v75, v129, v115 row_shr:1 row_mask:0xf bank_mask:0xf
	s_nop 0
	v_fmac_f32_dpp v75, v129, v99 row_shr:2 row_mask:0xf bank_mask:0xf
	s_nop 0
	v_fmac_f32_dpp v75, v119, v115 row_shl:15 row_mask:0xf bank_mask:0xf
	s_nop 0
	v_fmac_f32_dpp v75, v119, v99 row_shl:14 row_mask:0xf bank_mask:0xf
	v_fmac_f32_dpp v76, v126, v116 row_shr:1 row_mask:0xf bank_mask:0xf
	s_nop 0
	v_fmac_f32_dpp v76, v126, v100 row_shr:2 row_mask:0xf bank_mask:0xf
	s_nop 0
	v_fmac_f32_dpp v76, v120, v116 row_shl:15 row_mask:0xf bank_mask:0xf
	s_nop 0
	v_fmac_f32_dpp v76, v120, v100 row_shl:14 row_mask:0xf bank_mask:0xf
	v_fmac_f32_dpp v77, v127, v117 row_shr:1 row_mask:0xf bank_mask:0xf
	s_nop 0
	v_fmac_f32_dpp v77, v127, v101 row_shr:2 row_mask:0xf bank_mask:0xf
	s_nop 0
	v_fmac_f32_dpp v77, v121, v117 row_shl:15 row_mask:0xf bank_mask:0xf
	s_nop 0
	v_fmac_f32_dpp v77, v121, v101 row_shl:14 row_mask:0xf bank_mask:0xf
	s_and_saveexec_b64 s[52:53], s[38:39]
	s_cbranch_execz .LBB0_1343
	global_store_dwordx4 v[166:167], v[74:77], off offset:16
.LBB0_1343:
	s_or_b64 exec, exec, s[52:53]
	s_nop 0
	s_nop 0
	s_nop 0
	s_nop 0
	s_nop 0
	s_nop 0
	s_nop 0
	s_nop 0
	s_nop 0
	s_nop 0
	s_nop 0
	s_nop 0
	s_nop 0
	s_nop 0
	v_pk_mul_f32 v[244:245], v[76:77], s[100:101]
	v_exp_f32_e32 v244, v244
	v_exp_f32_e32 v245, v245
	s_nop 0
	v_pk_add_f32 v[244:245], v[244:245], s[98:99]
	v_rcp_f32_e32 v68, v244
	v_rcp_f32_e32 v69, v245
	v_pk_mul_f32 v[244:245], v[74:75], s[100:101]
	v_exp_f32_e32 v244, v244
	v_exp_f32_e32 v245, v245
	s_nop 0
	v_pk_add_f32 v[244:245], v[244:245], s[98:99]
	v_rcp_f32_e32 v66, v244
	v_rcp_f32_e32 v67, v245
	v_pk_mul_f32 v[70:71], v[108:109], v[76:77]
	v_pk_mul_f32 v[72:73], v[106:107], v[74:75]
	v_pk_mul_f32 v[68:69], v[70:71], v[68:69]
	v_pk_mul_f32 v[66:67], v[72:73], v[66:67]
	v_mov_b32_e32 v74, 0
	ds_read_b128 v[98:101], v223 offset:528
	ds_read_b128 v[106:109], v223 offset:1552
	ds_read_b128 v[114:117], v223 offset:2576
	ds_read_b128 v[70:73], v223 offset:3600
	v_mov_b32_e32 v110, 0
	v_mov_b32_e32 v111, 0
	v_mov_b32_e32 v112, 0
	v_mov_b32_e32 v113, 0
	s_and_saveexec_b64 s[52:53], s[0:1]
	v_add_u32_e32 v75, s77, v218
	ds_read_b128 v[110:113], v75 offset:512
	s_or_b64 exec, exec, s[52:53]
	s_waitcnt lgkmcnt(0)
	v_pk_fma_f32 v[82:83], v[58:59], v[114:115], v[70:71]
	s_nop 4
	v_fmac_f32_dpp v82, v58, v106 row_shr:1 row_mask:0xf bank_mask:0xf
	v_pk_fma_f32 v[14:15], v[14:15], v[160:161], v[54:55]
	v_fmac_f32_dpp v82, v58, v98 row_shr:2 row_mask:0xf bank_mask:0xf
	s_nop 0
	v_fmac_f32_dpp v82, v14, v106 row_shl:15 row_mask:0xf bank_mask:0xf
	v_pk_fma_f32 v[84:85], v[60:61], v[116:117], v[72:73]
	v_fmac_f32_dpp v82, v14, v98 row_shl:14 row_mask:0xf bank_mask:0xf
	v_fmac_f32_dpp v83, v59, v107 row_shr:1 row_mask:0xf bank_mask:0xf
	v_mov_b32_e32 v122, v160
	v_fmac_f32_dpp v83, v59, v99 row_shr:2 row_mask:0xf bank_mask:0xf
	v_mov_b32_e32 v123, v160
	v_fmac_f32_dpp v83, v15, v107 row_shl:15 row_mask:0xf bank_mask:0xf
	v_pk_fma_f32 v[16:17], v[16:17], v[160:161], v[56:57] op_sel_hi:[1,0,1]
	v_fmac_f32_dpp v83, v15, v99 row_shl:14 row_mask:0xf bank_mask:0xf
	v_fmac_f32_dpp v84, v60, v108 row_shr:1 row_mask:0xf bank_mask:0xf
	s_nop 0
	v_fmac_f32_dpp v84, v60, v100 row_shr:2 row_mask:0xf bank_mask:0xf
	v_pk_fma_f32 v[124:125], v[18:19], v[162:163], v[54:55]
	v_fmac_f32_dpp v84, v16, v108 row_shl:15 row_mask:0xf bank_mask:0xf
	v_pk_fma_f32 v[18:19], v[14:15], v[114:115], v[70:71]
	v_fmac_f32_dpp v84, v16, v100 row_shl:14 row_mask:0xf bank_mask:0xf
	v_fmac_f32_dpp v85, v61, v109 row_shr:1 row_mask:0xf bank_mask:0xf
	s_nop 0
	v_fmac_f32_dpp v85, v61, v101 row_shr:2 row_mask:0xf bank_mask:0xf
	v_mov_b32_e32 v120, v162
	v_fmac_f32_dpp v85, v17, v109 row_shl:15 row_mask:0xf bank_mask:0xf
	v_mov_b32_e32 v121, v162
	v_fmac_f32_dpp v85, v17, v101 row_shl:14 row_mask:0xf bank_mask:0xf
	v_pk_fma_f32 v[76:77], v[20:21], v[162:163], v[56:57] op_sel_hi:[1,0,1]
	v_fmac_f32_dpp v18, v14, v106 row_shr:1 row_mask:0xf bank_mask:0xf
	v_pk_fma_f32 v[20:21], v[16:17], v[116:117], v[72:73]
	v_fmac_f32_dpp v18, v14, v98 row_shr:2 row_mask:0xf bank_mask:0xf
	s_nop 0
	v_fmac_f32_dpp v18, v124, v106 row_shl:15 row_mask:0xf bank_mask:0xf
	s_nop 0
	v_fmac_f32_dpp v18, v124, v98 row_shl:14 row_mask:0xf bank_mask:0xf
	v_fmac_f32_dpp v19, v15, v107 row_shr:1 row_mask:0xf bank_mask:0xf
	v_pk_fma_f32 v[22:23], v[22:23], v[158:159], v[54:55]
	v_fmac_f32_dpp v19, v15, v99 row_shr:2 row_mask:0xf bank_mask:0xf
	v_pk_fma_f32 v[14:15], v[124:125], v[114:115], v[70:71]
	v_fmac_f32_dpp v19, v125, v107 row_shl:15 row_mask:0xf bank_mask:0xf
	v_mov_b32_e32 v118, v158
	v_fmac_f32_dpp v19, v125, v99 row_shl:14 row_mask:0xf bank_mask:0xf
	v_fmac_f32_dpp v20, v16, v108 row_shr:1 row_mask:0xf bank_mask:0xf
	v_mov_b32_e32 v119, v158
	v_fmac_f32_dpp v20, v16, v100 row_shr:2 row_mask:0xf bank_mask:0xf
	s_nop 0
	v_fmac_f32_dpp v20, v76, v108 row_shl:15 row_mask:0xf bank_mask:0xf
	v_pk_fma_f32 v[24:25], v[24:25], v[158:159], v[56:57] op_sel_hi:[1,0,1]
	v_fmac_f32_dpp v20, v76, v100 row_shl:14 row_mask:0xf bank_mask:0xf
	v_fmac_f32_dpp v21, v17, v109 row_shr:1 row_mask:0xf bank_mask:0xf
	v_pk_fma_f32 v[70:71], v[22:23], v[114:115], v[70:71]
	v_fmac_f32_dpp v21, v17, v101 row_shr:2 row_mask:0xf bank_mask:0xf
	v_pk_fma_f32 v[16:17], v[76:77], v[116:117], v[72:73]
	v_fmac_f32_dpp v21, v77, v109 row_shl:15 row_mask:0xf bank_mask:0xf
	s_nop 0
	v_fmac_f32_dpp v21, v77, v101 row_shl:14 row_mask:0xf bank_mask:0xf
	v_pk_fma_f32 v[72:73], v[24:25], v[116:117], v[72:73]
	v_fmac_f32_dpp v14, v124, v106 row_shr:1 row_mask:0xf bank_mask:0xf
	s_nop 0
	v_fmac_f32_dpp v14, v124, v98 row_shr:2 row_mask:0xf bank_mask:0xf
	v_mov_b32_e32 v75, 0
	v_fmac_f32_dpp v14, v22, v106 row_shl:15 row_mask:0xf bank_mask:0xf
	s_nop 0
	v_fmac_f32_dpp v14, v22, v98 row_shl:14 row_mask:0xf bank_mask:0xf
	v_fmac_f32_dpp v15, v125, v107 row_shr:1 row_mask:0xf bank_mask:0xf
	s_nop 0
	v_fmac_f32_dpp v15, v125, v99 row_shr:2 row_mask:0xf bank_mask:0xf
	s_nop 0
	v_fmac_f32_dpp v15, v23, v107 row_shl:15 row_mask:0xf bank_mask:0xf
	s_nop 0
	v_fmac_f32_dpp v15, v23, v99 row_shl:14 row_mask:0xf bank_mask:0xf
	v_fmac_f32_dpp v16, v76, v108 row_shr:1 row_mask:0xf bank_mask:0xf
	s_nop 0
	v_fmac_f32_dpp v16, v76, v100 row_shr:2 row_mask:0xf bank_mask:0xf
	v_mov_b32_e32 v76, 0
	v_fmac_f32_dpp v16, v24, v108 row_shl:15 row_mask:0xf bank_mask:0xf
	s_nop 0
	v_fmac_f32_dpp v16, v24, v100 row_shl:14 row_mask:0xf bank_mask:0xf
	v_fmac_f32_dpp v17, v77, v109 row_shr:1 row_mask:0xf bank_mask:0xf
	s_nop 0
	v_fmac_f32_dpp v17, v77, v101 row_shr:2 row_mask:0xf bank_mask:0xf
	v_mov_b32_e32 v77, 0
	v_fmac_f32_dpp v17, v25, v109 row_shl:15 row_mask:0xf bank_mask:0xf
	s_nop 0
	v_fmac_f32_dpp v17, v25, v101 row_shl:14 row_mask:0xf bank_mask:0xf
	s_nop 0
	v_fmac_f32_dpp v70, v22, v106 row_shr:1 row_mask:0xf bank_mask:0xf
	s_nop 0
	v_fmac_f32_dpp v70, v22, v98 row_shr:2 row_mask:0xf bank_mask:0xf
	s_nop 0
	v_fmac_f32_dpp v70, v110, v106 row_shl:15 row_mask:0xf bank_mask:0xf
	s_nop 0
	v_fmac_f32_dpp v70, v110, v98 row_shl:14 row_mask:0xf bank_mask:0xf
	v_fmac_f32_dpp v71, v23, v107 row_shr:1 row_mask:0xf bank_mask:0xf
	s_nop 0
	v_fmac_f32_dpp v71, v23, v99 row_shr:2 row_mask:0xf bank_mask:0xf
	s_nop 0
	v_fmac_f32_dpp v71, v111, v107 row_shl:15 row_mask:0xf bank_mask:0xf
	s_nop 0
	v_fmac_f32_dpp v71, v111, v99 row_shl:14 row_mask:0xf bank_mask:0xf
	v_fmac_f32_dpp v72, v24, v108 row_shr:1 row_mask:0xf bank_mask:0xf
	s_nop 0
	v_fmac_f32_dpp v72, v24, v100 row_shr:2 row_mask:0xf bank_mask:0xf
	s_nop 0
	v_fmac_f32_dpp v72, v112, v108 row_shl:15 row_mask:0xf bank_mask:0xf
	s_nop 0
	v_fmac_f32_dpp v72, v112, v100 row_shl:14 row_mask:0xf bank_mask:0xf
	v_fmac_f32_dpp v73, v25, v109 row_shr:1 row_mask:0xf bank_mask:0xf
	s_nop 0
	v_fmac_f32_dpp v73, v25, v101 row_shr:2 row_mask:0xf bank_mask:0xf
	s_nop 0
	v_fmac_f32_dpp v73, v113, v109 row_shl:15 row_mask:0xf bank_mask:0xf
	s_nop 0
	v_fmac_f32_dpp v73, v113, v101 row_shl:14 row_mask:0xf bank_mask:0xf
	s_nop 0
	ds_read_b128 v[54:57], v223 offset:16
	ds_read_b128 v[58:61], v223 offset:1040
	ds_read_b128 v[98:101], v223 offset:2064
	ds_read_b128 v[22:25], v223 offset:3088
	s_and_saveexec_b64 s[52:53], s[0:1]
	v_add_u32_e32 v74, 0, v218
	v_add_u32_e32 v74, 0x20000, v74
	ds_read_b128 v[74:77], v74
	s_or_b64 exec, exec, s[52:53]
	v_pk_fma_f32 v[106:107], v[8:9], v[162:163], v[32:33] op_sel_hi:[1,0,1]
	v_pk_fma_f32 v[8:9], v[2:3], v[160:161], v[30:31]
	s_waitcnt lgkmcnt(0)
	v_pk_fma_f32 v[2:3], v[26:27], v[98:99], v[22:23]
	s_nop 4
	v_fmac_f32_dpp v2, v26, v58 row_shr:1 row_mask:0xf bank_mask:0xf
	s_nop 0
	v_fmac_f32_dpp v2, v26, v54 row_shr:2 row_mask:0xf bank_mask:0xf
	v_pk_fma_f32 v[108:109], v[6:7], v[162:163], v[30:31]
	v_fmac_f32_dpp v2, v8, v58 row_shl:15 row_mask:0xf bank_mask:0xf
	v_pk_fma_f32 v[6:7], v[4:5], v[160:161], v[32:33] op_sel_hi:[1,0,1]
	v_fmac_f32_dpp v2, v8, v54 row_shl:14 row_mask:0xf bank_mask:0xf
	v_fmac_f32_dpp v3, v27, v59 row_shr:1 row_mask:0xf bank_mask:0xf
	v_pk_fma_f32 v[4:5], v[28:29], v[100:101], v[24:25]
	v_fmac_f32_dpp v3, v27, v55 row_shr:2 row_mask:0xf bank_mask:0xf
	s_nop 0
	v_fmac_f32_dpp v3, v9, v59 row_shl:15 row_mask:0xf bank_mask:0xf
	s_nop 0
	v_fmac_f32_dpp v3, v9, v55 row_shl:14 row_mask:0xf bank_mask:0xf
	v_fmac_f32_dpp v4, v28, v60 row_shr:1 row_mask:0xf bank_mask:0xf
	s_nop 0
	v_fmac_f32_dpp v4, v28, v56 row_shr:2 row_mask:0xf bank_mask:0xf
	s_nop 0
	v_fmac_f32_dpp v4, v6, v60 row_shl:15 row_mask:0xf bank_mask:0xf
	s_nop 0
	v_fmac_f32_dpp v4, v6, v56 row_shl:14 row_mask:0xf bank_mask:0xf
	v_fmac_f32_dpp v5, v29, v61 row_shr:1 row_mask:0xf bank_mask:0xf
	s_nop 0
	v_fmac_f32_dpp v5, v29, v57 row_shr:2 row_mask:0xf bank_mask:0xf
	s_nop 0
	v_fmac_f32_dpp v5, v7, v61 row_shl:15 row_mask:0xf bank_mask:0xf
	s_nop 0
	v_fmac_f32_dpp v5, v7, v57 row_shl:14 row_mask:0xf bank_mask:0xf
	s_nop 0
	s_nop 0
	s_nop 0
	s_nop 0
	s_nop 0
	s_nop 0
	s_nop 0
	v_pk_mul_f32 v[244:245], v[4:5], s[100:101]
	v_exp_f32_e32 v244, v244
	v_exp_f32_e32 v245, v245
	s_nop 0
	v_pk_add_f32 v[244:245], v[244:245], s[98:99]
	v_rcp_f32_e32 v28, v244
	v_rcp_f32_e32 v29, v245
	v_pk_mul_f32 v[244:245], v[2:3], s[100:101]
	v_exp_f32_e32 v244, v244
	v_exp_f32_e32 v245, v245
	s_nop 0
	v_pk_add_f32 v[244:245], v[244:245], s[98:99]
	v_rcp_f32_e32 v26, v244
	v_rcp_f32_e32 v27, v245
	v_pk_mul_f32 v[4:5], v[84:85], v[4:5]
	v_pk_mul_f32 v[2:3], v[82:83], v[2:3]
	v_pk_mul_f32 v[4:5], v[4:5], v[28:29]
	v_pk_mul_f32 v[2:3], v[2:3], v[26:27]
	v_pk_fma_f32 v[26:27], v[8:9], v[98:99], v[22:23]
	v_fmac_f32_dpp v26, v8, v58 row_shr:1 row_mask:0xf bank_mask:0xf
	s_nop 0
	v_fmac_f32_dpp v26, v8, v54 row_shr:2 row_mask:0xf bank_mask:0xf
	s_nop 0
	v_fmac_f32_dpp v26, v108, v58 row_shl:15 row_mask:0xf bank_mask:0xf
	v_pk_fma_f32 v[10:11], v[10:11], v[158:159], v[30:31]
	v_fmac_f32_dpp v26, v108, v54 row_shl:14 row_mask:0xf bank_mask:0xf
	v_fmac_f32_dpp v27, v9, v59 row_shr:1 row_mask:0xf bank_mask:0xf
	v_pk_fma_f32 v[12:13], v[12:13], v[158:159], v[32:33] op_sel_hi:[1,0,1]
	v_fmac_f32_dpp v27, v9, v55 row_shr:2 row_mask:0xf bank_mask:0xf
	v_pk_fma_f32 v[8:9], v[6:7], v[100:101], v[24:25]
	v_fmac_f32_dpp v27, v109, v59 row_shl:15 row_mask:0xf bank_mask:0xf
	s_ashr_i32 s51, s50, 31
	v_fmac_f32_dpp v27, v109, v55 row_shl:14 row_mask:0xf bank_mask:0xf
	v_fmac_f32_dpp v8, v6, v60 row_shr:1 row_mask:0xf bank_mask:0xf
	s_andn2_b64 vcc, exec, s[4:5]
	v_fmac_f32_dpp v8, v6, v56 row_shr:2 row_mask:0xf bank_mask:0xf
	s_nop 0
	v_fmac_f32_dpp v8, v106, v60 row_shl:15 row_mask:0xf bank_mask:0xf
	s_nop 0
	v_fmac_f32_dpp v8, v106, v56 row_shl:14 row_mask:0xf bank_mask:0xf
	v_fmac_f32_dpp v9, v7, v61 row_shr:1 row_mask:0xf bank_mask:0xf
	v_pk_mul_f32 v[18:19], v[18:19], v[26:27]
	v_fmac_f32_dpp v9, v7, v57 row_shr:2 row_mask:0xf bank_mask:0xf
	s_nop 0
	v_fmac_f32_dpp v9, v107, v61 row_shl:15 row_mask:0xf bank_mask:0xf
	s_nop 0
	v_fmac_f32_dpp v9, v107, v57 row_shl:14 row_mask:0xf bank_mask:0xf
	s_nop 0
	s_nop 0
	s_nop 0
	s_nop 0
	s_nop 0
	s_nop 0
	s_nop 0
	s_nop 0
	s_nop 0
	s_nop 0
	v_pk_mul_f32 v[244:245], v[8:9], s[100:101]
	v_exp_f32_e32 v244, v244
	v_exp_f32_e32 v245, v245
	s_nop 0
	v_pk_add_f32 v[244:245], v[244:245], s[98:99]
	v_rcp_f32_e32 v28, v244
	v_rcp_f32_e32 v29, v245
	v_pk_mul_f32 v[244:245], v[26:27], s[100:101]
	v_exp_f32_e32 v244, v244
	v_exp_f32_e32 v245, v245
	s_nop 0
	v_pk_add_f32 v[244:245], v[244:245], s[98:99]
	v_rcp_f32_e32 v6, v244
	v_rcp_f32_e32 v7, v245
	v_pk_mul_f32 v[8:9], v[20:21], v[8:9]
	v_pk_fma_f32 v[20:21], v[106:107], v[100:101], v[24:25]
	v_pk_mul_f32 v[8:9], v[8:9], v[28:29]
	v_pk_mul_f32 v[6:7], v[18:19], v[6:7]
	v_pk_fma_f32 v[18:19], v[108:109], v[98:99], v[22:23]
	v_fmac_f32_dpp v18, v108, v58 row_shr:1 row_mask:0xf bank_mask:0xf
	s_nop 0
	v_fmac_f32_dpp v18, v108, v54 row_shr:2 row_mask:0xf bank_mask:0xf
	s_nop 0
	v_fmac_f32_dpp v18, v10, v58 row_shl:15 row_mask:0xf bank_mask:0xf
	v_pk_fma_f32 v[24:25], v[12:13], v[100:101], v[24:25]
	v_fmac_f32_dpp v18, v10, v54 row_shl:14 row_mask:0xf bank_mask:0xf
	v_fmac_f32_dpp v19, v109, v59 row_shr:1 row_mask:0xf bank_mask:0xf
	s_nop 0
	v_fmac_f32_dpp v19, v109, v55 row_shr:2 row_mask:0xf bank_mask:0xf
	s_nop 0
	v_fmac_f32_dpp v19, v11, v59 row_shl:15 row_mask:0xf bank_mask:0xf
	s_nop 0
	v_fmac_f32_dpp v19, v11, v55 row_shl:14 row_mask:0xf bank_mask:0xf
	v_fmac_f32_dpp v20, v106, v60 row_shr:1 row_mask:0xf bank_mask:0xf
	s_mov_b64 s[4:5], -1
	v_fmac_f32_dpp v20, v106, v56 row_shr:2 row_mask:0xf bank_mask:0xf
	s_nop 0
	v_fmac_f32_dpp v20, v12, v60 row_shl:15 row_mask:0xf bank_mask:0xf
	s_nop 0
	v_fmac_f32_dpp v20, v12, v56 row_shl:14 row_mask:0xf bank_mask:0xf
	v_fmac_f32_dpp v21, v107, v61 row_shr:1 row_mask:0xf bank_mask:0xf
	s_nop 0
	v_fmac_f32_dpp v21, v107, v57 row_shr:2 row_mask:0xf bank_mask:0xf
	s_nop 0
	v_fmac_f32_dpp v21, v13, v61 row_shl:15 row_mask:0xf bank_mask:0xf
	s_nop 0
	v_fmac_f32_dpp v21, v13, v57 row_shl:14 row_mask:0xf bank_mask:0xf
	s_nop 0
	s_nop 0
	s_nop 0
	s_nop 0
	s_nop 0
	s_nop 0
	s_nop 0
	v_pk_mul_f32 v[244:245], v[20:21], s[100:101]
	v_exp_f32_e32 v244, v244
	v_exp_f32_e32 v245, v245
	s_nop 0
	v_pk_add_f32 v[244:245], v[244:245], s[98:99]
	v_rcp_f32_e32 v28, v244
	v_rcp_f32_e32 v29, v245
	v_pk_mul_f32 v[244:245], v[18:19], s[100:101]
	v_exp_f32_e32 v244, v244
	v_exp_f32_e32 v245, v245
	s_nop 0
	v_pk_add_f32 v[244:245], v[244:245], s[98:99]
	v_rcp_f32_e32 v26, v244
	v_rcp_f32_e32 v27, v245
	v_pk_mul_f32 v[16:17], v[16:17], v[20:21]
	v_pk_mul_f32 v[14:15], v[14:15], v[18:19]
	v_pk_mul_f32 v[16:17], v[16:17], v[28:29]
	v_pk_mul_f32 v[14:15], v[14:15], v[26:27]
	v_pk_fma_f32 v[18:19], v[10:11], v[98:99], v[22:23]
	v_fmac_f32_dpp v18, v10, v58 row_shr:1 row_mask:0xf bank_mask:0xf
	s_nop 0
	v_fmac_f32_dpp v18, v10, v54 row_shr:2 row_mask:0xf bank_mask:0xf
	v_lshl_add_u32 v26, s30, 8, v173
	v_fmac_f32_dpp v18, v74, v58 row_shl:15 row_mask:0xf bank_mask:0xf
	v_mov_b64_e32 v[22:23], s[66:67]
	v_fmac_f32_dpp v18, v74, v54 row_shl:14 row_mask:0xf bank_mask:0xf
	v_fmac_f32_dpp v19, v11, v59 row_shr:1 row_mask:0xf bank_mask:0xf
	s_nop 0
	v_fmac_f32_dpp v19, v11, v55 row_shr:2 row_mask:0xf bank_mask:0xf
	s_nop 0
	v_fmac_f32_dpp v19, v75, v59 row_shl:15 row_mask:0xf bank_mask:0xf
	s_nop 0
	v_fmac_f32_dpp v19, v75, v55 row_shl:14 row_mask:0xf bank_mask:0xf
	v_fmac_f32_dpp v24, v12, v60 row_shr:1 row_mask:0xf bank_mask:0xf
	s_nop 0
	v_fmac_f32_dpp v24, v12, v56 row_shr:2 row_mask:0xf bank_mask:0xf
	s_nop 0
	v_fmac_f32_dpp v24, v76, v60 row_shl:15 row_mask:0xf bank_mask:0xf
	s_nop 0
	v_fmac_f32_dpp v24, v76, v56 row_shl:14 row_mask:0xf bank_mask:0xf
	v_fmac_f32_dpp v25, v13, v61 row_shr:1 row_mask:0xf bank_mask:0xf
	s_nop 0
	v_fmac_f32_dpp v25, v13, v57 row_shr:2 row_mask:0xf bank_mask:0xf
	s_nop 0
	v_fmac_f32_dpp v25, v77, v61 row_shl:15 row_mask:0xf bank_mask:0xf
	s_nop 0
	v_fmac_f32_dpp v25, v77, v57 row_shl:14 row_mask:0xf bank_mask:0xf
	s_nop 0
	s_nop 0
	s_nop 0
	s_nop 0
	s_nop 0
	s_nop 0
	s_nop 0
	v_pk_mul_f32 v[244:245], v[24:25], s[100:101]
	v_exp_f32_e32 v244, v244
	v_exp_f32_e32 v245, v245
	s_nop 0
	v_pk_add_f32 v[244:245], v[244:245], s[98:99]
	v_rcp_f32_e32 v12, v244
	v_rcp_f32_e32 v13, v245
	v_pk_mul_f32 v[244:245], v[18:19], s[100:101]
	v_exp_f32_e32 v244, v244
	v_exp_f32_e32 v245, v245
	s_nop 0
	v_pk_add_f32 v[244:245], v[244:245], s[98:99]
	v_rcp_f32_e32 v10, v244
	v_rcp_f32_e32 v11, v245
	v_pk_mul_f32 v[20:21], v[72:73], v[24:25]
	v_mad_i64_i32 v[24:25], s[30:31], v26, s81, v[22:23]
	s_lshl_b64 s[30:31], s[50:51], 1
	v_pk_mul_f32 v[18:19], v[70:71], v[18:19]
	v_lshl_add_u64 v[24:25], v[24:25], 0, s[30:31]
	v_pk_mul_f32 v[12:13], v[20:21], v[12:13]
	v_pk_mul_f32 v[10:11], v[18:19], v[10:11]
	v_lshl_add_u64 v[24:25], v[24:25], 0, v[184:185]
	v_cvt_pk_bf16_f32 v18, v78, v79
	v_cvt_pk_bf16_f32 v19, v80, v81
	v_cvt_pk_bf16_f32 v20, v66, v67
	v_cvt_pk_bf16_f32 v21, v68, v69
	global_store_dwordx4 v[24:25], v[18:21], off
	v_or_b32_e32 v24, 16, v26
	v_mad_i64_i32 v[24:25], s[50:51], v24, s81, v[22:23]
	v_lshl_add_u64 v[24:25], v[24:25], 0, s[30:31]
	v_lshl_add_u64 v[24:25], v[24:25], 0, v[184:185]
	v_cvt_pk_bf16_f32 v18, v62, v63
	v_cvt_pk_bf16_f32 v19, v64, v65
	v_cvt_pk_bf16_f32 v20, v42, v43
	v_cvt_pk_bf16_f32 v21, v44, v45
	global_store_dwordx4 v[24:25], v[18:21], off
	v_or_b32_e32 v24, 32, v26
	v_mad_i64_i32 v[24:25], s[50:51], v24, s81, v[22:23]
	v_lshl_add_u64 v[24:25], v[24:25], 0, s[30:31]
	v_lshl_add_u64 v[24:25], v[24:25], 0, v[184:185]
	v_cvt_pk_bf16_f32 v18, v50, v51
	v_cvt_pk_bf16_f32 v19, v52, v53
	v_cvt_pk_bf16_f32 v20, v38, v39
	v_cvt_pk_bf16_f32 v21, v40, v41
	global_store_dwordx4 v[24:25], v[18:21], off
	v_or_b32_e32 v24, 48, v26
	v_mad_i64_i32 v[24:25], s[50:51], v24, s81, v[22:23]
	v_lshl_add_u64 v[24:25], v[24:25], 0, s[30:31]
	v_lshl_add_u64 v[24:25], v[24:25], 0, v[184:185]
	v_cvt_pk_bf16_f32 v18, v46, v47
	v_cvt_pk_bf16_f32 v19, v48, v49
	v_cvt_pk_bf16_f32 v20, v34, v35
	v_cvt_pk_bf16_f32 v21, v36, v37
	global_store_dwordx4 v[24:25], v[18:21], off
	v_add_u32_e32 v24, 0x80, v26
	s_nop 0
	v_cvt_pk_bf16_f32 v18, v102, v103
	v_cvt_pk_bf16_f32 v19, v104, v105
	v_cvt_pk_bf16_f32 v20, v10, v11
	v_mad_i64_i32 v[10:11], s[50:51], v24, s81, v[22:23]
	v_lshl_add_u64 v[10:11], v[10:11], 0, s[30:31]
	v_lshl_add_u64 v[10:11], v[10:11], 0, v[184:185]
	v_cvt_pk_bf16_f32 v21, v12, v13
	global_store_dwordx4 v[10:11], v[18:21], off
	v_cvt_pk_bf16_f32 v10, v94, v95
	v_cvt_pk_bf16_f32 v11, v96, v97
	v_cvt_pk_bf16_f32 v12, v14, v15
	v_add_u32_e32 v14, 0x90, v26
	v_mad_i64_i32 v[14:15], s[50:51], v14, s81, v[22:23]
	v_lshl_add_u64 v[14:15], v[14:15], 0, s[30:31]
	v_lshl_add_u64 v[14:15], v[14:15], 0, v[184:185]
	v_cvt_pk_bf16_f32 v13, v16, v17
	global_store_dwordx4 v[14:15], v[10:13], off
	s_nop 1
	v_cvt_pk_bf16_f32 v10, v90, v91
	v_cvt_pk_bf16_f32 v11, v92, v93
	v_cvt_pk_bf16_f32 v12, v6, v7
	v_add_u32_e32 v6, 0xa0, v26
	v_mad_i64_i32 v[6:7], s[50:51], v6, s81, v[22:23]
	v_lshl_add_u64 v[6:7], v[6:7], 0, s[30:31]
	v_lshl_add_u64 v[6:7], v[6:7], 0, v[184:185]
	v_cvt_pk_bf16_f32 v13, v8, v9
	global_store_dwordx4 v[6:7], v[10:13], off
	v_cvt_pk_bf16_f32 v6, v86, v87
	v_cvt_pk_bf16_f32 v7, v88, v89
	v_cvt_pk_bf16_f32 v8, v2, v3
	v_add_u32_e32 v2, 0xb0, v26
	v_mad_i64_i32 v[2:3], s[50:51], v2, s81, v[22:23]
	v_lshl_add_u64 v[2:3], v[2:3], 0, s[30:31]
	v_lshl_add_u64 v[2:3], v[2:3], 0, v[184:185]
	v_cvt_pk_bf16_f32 v9, v4, v5
	global_store_dwordx4 v[2:3], v[6:9], off
	s_cbranch_vccnz .LBB0_1313
	s_andn2_b64 vcc, exec, s[20:21]
	s_mov_b32 s43, s44
	s_mov_b64 s[30:31], s[16:17]
	s_mov_b64 s[4:5], s[40:41]
	s_cbranch_vccnz .LBB0_1350
	s_ashr_i32 s4, s44, 5
	s_mul_hi_i32 s5, s4, 0x5800
	s_mulk_i32 s4, 0x5800
	s_add_u32 s30, s3, s4
	s_addc_u32 s31, s6, s5
	s_mov_b32 s43, s42
	s_mov_b64 s[4:5], s[14:15]
